# scalar-base LDS-DMA also in the hand-written GEMM phases (P3, P11, P19)
# speedup vs baseline: 1.0255x; 1.0175x over previous
.Lmq3_vb:
	v_mbcnt_hi_u32_b32 v206, -1, v210
	s_lshr_b32 s29, s70, 6
	s_lshl_b32 s88, s70, 4
	s_and_b32 s90, s70, 0x40
	v_and_b32_e32 v245, 48, v206
	v_or_b32_e32 v245, s90, v245
	v_and_b32_e32 v207, 31, v206
	v_lshrrev_b32_e32 v208, 5, v206
	v_bfe_u32 v209, v206, 1, 3
	v_lshlrev_b32_e32 v211, 7, v207
	s_lshr_b32 s91, s70, 7
	s_lshl_b32 s31, s91, 6
	s_lshl_b32 s91, s91, 13
	s_lshl_b32 s34, s90, 1
	s_lshl_b32 s90, s90, 8
	s_add_u32 s90, s90, 0x8000
	v_xor_b32_e32 v212, v208, v209
	v_lshl_add_u32 v212, v212, 4, v211
	v_add_u32_e32 v184, s91, v212
	v_add_u32_e32 v188, s90, v212
	v_or_b32_e32 v212, 2, v208
	v_xor_b32_e32 v212, v212, v209
	v_lshl_add_u32 v212, v212, 4, v211
	v_add_u32_e32 v185, s91, v212
	v_add_u32_e32 v189, s90, v212
	v_or_b32_e32 v212, 4, v208
	v_xor_b32_e32 v212, v212, v209
	v_lshl_add_u32 v212, v212, 4, v211
	v_add_u32_e32 v186, s91, v212
	v_add_u32_e32 v190, s90, v212
	v_or_b32_e32 v212, 6, v208
	v_xor_b32_e32 v212, v212, v209
	v_lshl_add_u32 v212, v212, 4, v211
	v_add_u32_e32 v187, s91, v212
	v_add_u32_e32 v191, s90, v212
	v_lshlrev_b32_e32 v200, 3, v207
	v_lshlrev_b32_e32 v203, 2, v208
	s_mul_i32 s91, s29, 0x1200
	s_add_u32 s91, s91, 0x12000
	v_mul_u32_u24_e32 v212, 0x240, v208
	v_lshl_add_u32 v212, v207, 1, v212
	v_add_u32_e32 v201, s91, v212
	v_lshrrev_b32_e32 v204, 3, v206
	v_and_b32_e32 v212, 7, v206
	v_lshlrev_b32_e32 v205, 4, v212
	v_mul_u32_u24_e32 v212, 0x90, v204
	v_add3_u32 v202, v212, v205, s91
	s_load_dwordx2 s[4:5], s[0:1], 0x168
	s_load_dwordx2 s[6:7], s[0:1], 0xd0
	s_load_dwordx2 s[8:9], s[0:1], 0x210
	s_load_dwordx2 s[10:11], s[0:1], 0x148
	s_load_dwordx2 s[12:13], s[0:1], 0x178
	s_lshl_b32 s96, s29, 3
	v_add_u32_e32 v206, s96, v204
	v_xor_b32_e32 v207, v245, v205
	v_lshl_add_u32 v192, v206, 9, v207
	v_mov_b32_e32 v193, 0
	v_add_u32_e32 v208, 64, v206
	v_lshl_add_u32 v194, v208, 9, v207
	v_mov_b32_e32 v195, 0
	v_add_u32_e32 v208, 128, v206
	v_lshl_add_u32 v196, v208, 9, v207
	v_mov_b32_e32 v197, 0
	v_add_u32_e32 v208, 192, v206
	v_lshl_add_u32 v198, v208, 9, v207
	v_mov_b32_e32 v199, 0
	s_mov_b32 s30, s28
	s_cmp_ge_u32 s30, 768
	s_cbranch_scc1 .Lmq3q_done
	s_waitcnt lgkmcnt(0)
	s_mul_hi_u32 s35, s30, 0xaaaaaaab
	s_lshr_b32 s35, s35, 2
	s_mul_i32 s36, s35, 6
	s_sub_u32 s36, s30, s36
	s_lshl_b32 s98, s35, 17
	s_add_u32 s16, s4, s98
	s_addc_u32 s17, s5, 0
	s_lshl_b32 s98, s36, 17
	s_add_u32 s18, s6, s98
	s_addc_u32 s19, s7, 0
	s_add_u32 m0, s88, 0
	s_nop 0
	global_load_lds_dwordx4 v192, s[16:17]
	s_add_u32 m0, s88, 32768
	s_nop 0
	global_load_lds_dwordx4 v192, s[18:19]
	s_add_u32 m0, s88, 8192
	s_nop 0
	global_load_lds_dwordx4 v194, s[16:17]
	s_add_u32 m0, s88, 40960
	s_nop 0
	global_load_lds_dwordx4 v194, s[18:19]
	s_add_u32 m0, s88, 16384
	s_nop 0
	global_load_lds_dwordx4 v196, s[16:17]
	s_add_u32 m0, s88, 49152
	s_nop 0
	global_load_lds_dwordx4 v196, s[18:19]
	s_add_u32 m0, s88, 24576
	s_nop 0
	global_load_lds_dwordx4 v198, s[16:17]
	s_add_u32 m0, s88, 57344
	s_nop 0
	global_load_lds_dwordx4 v198, s[18:19]
.Lmq3q_tile:
	s_mul_hi_u32 s35, s30, 0xaaaaaaab
	s_lshr_b32 s35, s35, 2
	s_mul_i32 s36, s35, 6
	s_sub_u32 s36, s30, s36
	s_lshl_b32 s92, s35, 8
	s_add_u32 s92, s92, s31
	s_lshl_b32 s93, s36, 8
	s_add_u32 s93, s93, s34
	s_lshl_b32 s96, s92, 2
	v_lshl_add_u32 v212, v203, 2, s96
	s_waitcnt vmcnt(0)
	s_barrier
	s_add_u32 s20, s16, 128
	s_addc_u32 s21, s17, 0
	s_add_u32 s24, s18, 128
	s_addc_u32 s25, s19, 0
	s_add_u32 m0, s88, 65536
	s_nop 0
	global_load_lds_dwordx4 v192, s[20:21]
	s_add_u32 m0, s88, 98304
	s_nop 0
	global_load_lds_dwordx4 v192, s[24:25]
	s_add_u32 m0, s88, 73728
	s_nop 0
	global_load_lds_dwordx4 v194, s[20:21]
	s_add_u32 m0, s88, 106496
	s_nop 0
	global_load_lds_dwordx4 v194, s[24:25]
	s_add_u32 m0, s88, 81920
	s_nop 0
	global_load_lds_dwordx4 v196, s[20:21]
	s_add_u32 m0, s88, 114688
	s_nop 0
	global_load_lds_dwordx4 v196, s[24:25]
	s_add_u32 m0, s88, 90112
	s_nop 0
	global_load_lds_dwordx4 v198, s[20:21]
	s_add_u32 m0, s88, 122880
	s_nop 0
	global_load_lds_dwordx4 v198, s[24:25]
	global_load_dword v213, v212, s[8:9] offset:0
	global_load_dword v214, v212, s[8:9] offset:4
	global_load_dword v215, v212, s[8:9] offset:8
	global_load_dword v216, v212, s[8:9] offset:12
	global_load_dword v217, v212, s[8:9] offset:32
	global_load_dword v218, v212, s[8:9] offset:36
	global_load_dword v219, v212, s[8:9] offset:40
	global_load_dword v220, v212, s[8:9] offset:44
	global_load_dword v221, v212, s[8:9] offset:64
	global_load_dword v222, v212, s[8:9] offset:68
	global_load_dword v223, v212, s[8:9] offset:72
	global_load_dword v224, v212, s[8:9] offset:76
	global_load_dword v225, v212, s[8:9] offset:96
	global_load_dword v226, v212, s[8:9] offset:100
	global_load_dword v227, v212, s[8:9] offset:104
	global_load_dword v228, v212, s[8:9] offset:108
	global_load_dword v229, v212, s[8:9] offset:128
	global_load_dword v230, v212, s[8:9] offset:132
	global_load_dword v231, v212, s[8:9] offset:136
	global_load_dword v232, v212, s[8:9] offset:140
	global_load_dword v233, v212, s[8:9] offset:160
	global_load_dword v234, v212, s[8:9] offset:164
	global_load_dword v235, v212, s[8:9] offset:168
	global_load_dword v236, v212, s[8:9] offset:172
	global_load_dword v237, v212, s[8:9] offset:192
	global_load_dword v238, v212, s[8:9] offset:196
	global_load_dword v239, v212, s[8:9] offset:200
	global_load_dword v240, v212, s[8:9] offset:204
	global_load_dword v241, v212, s[8:9] offset:224
	global_load_dword v242, v212, s[8:9] offset:228
	global_load_dword v243, v212, s[8:9] offset:232
	global_load_dword v244, v212, s[8:9] offset:236
	ds_read_b128 v[160:163], v184
	ds_read_b128 v[168:171], v188
	ds_read_b128 v[164:167], v184 offset:4096
	ds_read_b128 v[172:175], v188 offset:4096
	ds_read_b128 v[176:179], v188 offset:8192
	ds_read_b128 v[180:183], v188 offset:12288
	ds_read_b128 v[128:131], v185
	ds_read_b128 v[136:139], v189
	ds_read_b128 v[132:135], v185 offset:4096
	ds_read_b128 v[140:143], v189 offset:4096
	ds_read_b128 v[144:147], v189 offset:8192
	ds_read_b128 v[148:151], v189 offset:12288
	s_waitcnt lgkmcnt(6)
	v_mfma_f32_32x32x16_bf16 v[112:127], v[160:163], v[168:171], 0
	v_mfma_f32_32x32x16_bf16 v[48:63], v[164:167], v[168:171], 0
	v_mfma_f32_32x32x16_bf16 v[96:111], v[160:163], v[172:175], 0
	v_mfma_f32_32x32x16_bf16 v[32:47], v[164:167], v[172:175], 0
	v_mfma_f32_32x32x16_bf16 v[80:95], v[160:163], v[176:179], 0
	v_mfma_f32_32x32x16_bf16 v[16:31], v[164:167], v[176:179], 0
	v_mfma_f32_32x32x16_bf16 v[64:79], v[160:163], v[180:183], 0
	v_mfma_f32_32x32x16_bf16 v[0:15], v[164:167], v[180:183], 0
	ds_read_b128 v[160:163], v186
	ds_read_b128 v[168:171], v190
	ds_read_b128 v[164:167], v186 offset:4096
	ds_read_b128 v[172:175], v190 offset:4096
	ds_read_b128 v[176:179], v190 offset:8192
	ds_read_b128 v[180:183], v190 offset:12288
	s_waitcnt lgkmcnt(6)
	v_mfma_f32_32x32x16_bf16 v[112:127], v[128:131], v[136:139], v[112:127]
	v_mfma_f32_32x32x16_bf16 v[48:63], v[132:135], v[136:139], v[48:63]
	v_mfma_f32_32x32x16_bf16 v[96:111], v[128:131], v[140:143], v[96:111]
	v_mfma_f32_32x32x16_bf16 v[32:47], v[132:135], v[140:143], v[32:47]
	v_mfma_f32_32x32x16_bf16 v[80:95], v[128:131], v[144:147], v[80:95]
	v_mfma_f32_32x32x16_bf16 v[16:31], v[132:135], v[144:147], v[16:31]
	v_mfma_f32_32x32x16_bf16 v[64:79], v[128:131], v[148:151], v[64:79]
	v_mfma_f32_32x32x16_bf16 v[0:15], v[132:135], v[148:151], v[0:15]
	ds_read_b128 v[128:131], v187
	ds_read_b128 v[136:139], v191
	ds_read_b128 v[132:135], v187 offset:4096
	ds_read_b128 v[140:143], v191 offset:4096
	ds_read_b128 v[144:147], v191 offset:8192
	ds_read_b128 v[148:151], v191 offset:12288
	s_waitcnt lgkmcnt(6)
	v_mfma_f32_32x32x16_bf16 v[112:127], v[160:163], v[168:171], v[112:127]
	v_mfma_f32_32x32x16_bf16 v[48:63], v[164:167], v[168:171], v[48:63]
	v_mfma_f32_32x32x16_bf16 v[96:111], v[160:163], v[172:175], v[96:111]
	v_mfma_f32_32x32x16_bf16 v[32:47], v[164:167], v[172:175], v[32:47]
	v_mfma_f32_32x32x16_bf16 v[80:95], v[160:163], v[176:179], v[80:95]
	v_mfma_f32_32x32x16_bf16 v[16:31], v[164:167], v[176:179], v[16:31]
	v_mfma_f32_32x32x16_bf16 v[64:79], v[160:163], v[180:183], v[64:79]
	v_mfma_f32_32x32x16_bf16 v[0:15], v[164:167], v[180:183], v[0:15]
	s_waitcnt vmcnt(0) lgkmcnt(0)
	s_barrier
	v_xor_b32_e32 v184, 0x10000, v184
	v_xor_b32_e32 v188, 0x10000, v188
	ds_read_b128 v[160:163], v184
	ds_read_b128 v[168:171], v188
	ds_read_b128 v[164:167], v184 offset:4096
	ds_read_b128 v[172:175], v188 offset:4096
	ds_read_b128 v[176:179], v188 offset:8192
	ds_read_b128 v[180:183], v188 offset:12288
	s_add_u32 s20, s16, 256
	s_addc_u32 s21, s17, 0
	s_add_u32 s24, s18, 256
	s_addc_u32 s25, s19, 0
	v_mfma_f32_32x32x16_bf16 v[112:127], v[128:131], v[136:139], v[112:127]
	v_xor_b32_e32 v185, 0x10000, v185
	v_xor_b32_e32 v189, 0x10000, v189
	s_add_u32 m0, s88, 0
	s_nop 0
	global_load_lds_dwordx4 v192, s[20:21]
	v_mfma_f32_32x32x16_bf16 v[48:63], v[132:135], v[136:139], v[48:63]
	v_xor_b32_e32 v186, 0x10000, v186
	v_xor_b32_e32 v190, 0x10000, v190
	s_add_u32 m0, s88, 32768
	s_nop 0
	global_load_lds_dwordx4 v192, s[24:25]
	v_mfma_f32_32x32x16_bf16 v[96:111], v[128:131], v[140:143], v[96:111]
	v_xor_b32_e32 v187, 0x10000, v187
	v_xor_b32_e32 v191, 0x10000, v191
	s_add_u32 m0, s88, 8192
	s_nop 0
	global_load_lds_dwordx4 v194, s[20:21]
	v_mfma_f32_32x32x16_bf16 v[32:47], v[132:135], v[140:143], v[32:47]
	s_add_u32 m0, s88, 40960
	s_nop 0
	global_load_lds_dwordx4 v194, s[24:25]
	v_mfma_f32_32x32x16_bf16 v[80:95], v[128:131], v[144:147], v[80:95]
	s_add_u32 m0, s88, 16384
	s_nop 0
	global_load_lds_dwordx4 v196, s[20:21]
	v_mfma_f32_32x32x16_bf16 v[16:31], v[132:135], v[144:147], v[16:31]
	s_add_u32 m0, s88, 49152
	s_nop 0
	global_load_lds_dwordx4 v196, s[24:25]
	v_mfma_f32_32x32x16_bf16 v[64:79], v[128:131], v[148:151], v[64:79]
	s_add_u32 m0, s88, 24576
	s_nop 0
	global_load_lds_dwordx4 v198, s[20:21]
	v_mfma_f32_32x32x16_bf16 v[0:15], v[132:135], v[148:151], v[0:15]
	s_add_u32 m0, s88, 57344
	s_nop 0
	global_load_lds_dwordx4 v198, s[24:25]
	ds_read_b128 v[128:131], v185
	ds_read_b128 v[136:139], v189
	ds_read_b128 v[132:135], v185 offset:4096
	ds_read_b128 v[140:143], v189 offset:4096
	ds_read_b128 v[144:147], v189 offset:8192
	ds_read_b128 v[148:151], v189 offset:12288
	s_waitcnt lgkmcnt(6)
	v_mfma_f32_32x32x16_bf16 v[112:127], v[160:163], v[168:171], v[112:127]
	v_mfma_f32_32x32x16_bf16 v[48:63], v[164:167], v[168:171], v[48:63]
	v_mfma_f32_32x32x16_bf16 v[96:111], v[160:163], v[172:175], v[96:111]
	v_mfma_f32_32x32x16_bf16 v[32:47], v[164:167], v[172:175], v[32:47]
	v_mfma_f32_32x32x16_bf16 v[80:95], v[160:163], v[176:179], v[80:95]
	v_mfma_f32_32x32x16_bf16 v[16:31], v[164:167], v[176:179], v[16:31]
	v_mfma_f32_32x32x16_bf16 v[64:79], v[160:163], v[180:183], v[64:79]
	v_mfma_f32_32x32x16_bf16 v[0:15], v[164:167], v[180:183], v[0:15]
	ds_read_b128 v[160:163], v186
	ds_read_b128 v[168:171], v190
	ds_read_b128 v[164:167], v186 offset:4096
	ds_read_b128 v[172:175], v190 offset:4096
	ds_read_b128 v[176:179], v190 offset:8192
	ds_read_b128 v[180:183], v190 offset:12288
	s_waitcnt lgkmcnt(6)
	v_mfma_f32_32x32x16_bf16 v[112:127], v[128:131], v[136:139], v[112:127]
	v_mfma_f32_32x32x16_bf16 v[48:63], v[132:135], v[136:139], v[48:63]
	v_mfma_f32_32x32x16_bf16 v[96:111], v[128:131], v[140:143], v[96:111]
	v_mfma_f32_32x32x16_bf16 v[32:47], v[132:135], v[140:143], v[32:47]
	v_mfma_f32_32x32x16_bf16 v[80:95], v[128:131], v[144:147], v[80:95]
	v_mfma_f32_32x32x16_bf16 v[16:31], v[132:135], v[144:147], v[16:31]
	v_mfma_f32_32x32x16_bf16 v[64:79], v[128:131], v[148:151], v[64:79]
	v_mfma_f32_32x32x16_bf16 v[0:15], v[132:135], v[148:151], v[0:15]
	ds_read_b128 v[128:131], v187
	ds_read_b128 v[136:139], v191
	ds_read_b128 v[132:135], v187 offset:4096
	ds_read_b128 v[140:143], v191 offset:4096
	ds_read_b128 v[144:147], v191 offset:8192
	ds_read_b128 v[148:151], v191 offset:12288
	s_waitcnt lgkmcnt(6)
	v_mfma_f32_32x32x16_bf16 v[112:127], v[160:163], v[168:171], v[112:127]
	v_mfma_f32_32x32x16_bf16 v[48:63], v[164:167], v[168:171], v[48:63]
	v_mfma_f32_32x32x16_bf16 v[96:111], v[160:163], v[172:175], v[96:111]
	v_mfma_f32_32x32x16_bf16 v[32:47], v[164:167], v[172:175], v[32:47]
	v_mfma_f32_32x32x16_bf16 v[80:95], v[160:163], v[176:179], v[80:95]
	v_mfma_f32_32x32x16_bf16 v[16:31], v[164:167], v[176:179], v[16:31]
	v_mfma_f32_32x32x16_bf16 v[64:79], v[160:163], v[180:183], v[64:79]
	v_mfma_f32_32x32x16_bf16 v[0:15], v[164:167], v[180:183], v[0:15]
	s_waitcnt vmcnt(0) lgkmcnt(0)
	s_barrier
	v_xor_b32_e32 v184, 0x10000, v184
	v_xor_b32_e32 v188, 0x10000, v188
	ds_read_b128 v[160:163], v184
	ds_read_b128 v[168:171], v188
	ds_read_b128 v[164:167], v184 offset:4096
	ds_read_b128 v[172:175], v188 offset:4096
	ds_read_b128 v[176:179], v188 offset:8192
	ds_read_b128 v[180:183], v188 offset:12288
	s_add_u32 s20, s16, 384
	s_addc_u32 s21, s17, 0
	s_add_u32 s24, s18, 384
	s_addc_u32 s25, s19, 0
	v_mfma_f32_32x32x16_bf16 v[112:127], v[128:131], v[136:139], v[112:127]
	v_xor_b32_e32 v185, 0x10000, v185
	v_xor_b32_e32 v189, 0x10000, v189
	s_add_u32 m0, s88, 65536
	s_nop 0
	global_load_lds_dwordx4 v192, s[20:21]
	v_mfma_f32_32x32x16_bf16 v[48:63], v[132:135], v[136:139], v[48:63]
	v_xor_b32_e32 v186, 0x10000, v186
	v_xor_b32_e32 v190, 0x10000, v190
	s_add_u32 m0, s88, 98304
	s_nop 0
	global_load_lds_dwordx4 v192, s[24:25]
	v_mfma_f32_32x32x16_bf16 v[96:111], v[128:131], v[140:143], v[96:111]
	v_xor_b32_e32 v187, 0x10000, v187
	v_xor_b32_e32 v191, 0x10000, v191
	s_add_u32 m0, s88, 73728
	s_nop 0
	global_load_lds_dwordx4 v194, s[20:21]
	v_mfma_f32_32x32x16_bf16 v[32:47], v[132:135], v[140:143], v[32:47]
	s_add_u32 m0, s88, 106496
	s_nop 0
	global_load_lds_dwordx4 v194, s[24:25]
	v_mfma_f32_32x32x16_bf16 v[80:95], v[128:131], v[144:147], v[80:95]
	s_add_u32 m0, s88, 81920
	s_nop 0
	global_load_lds_dwordx4 v196, s[20:21]
	v_mfma_f32_32x32x16_bf16 v[16:31], v[132:135], v[144:147], v[16:31]
	s_add_u32 m0, s88, 114688
	s_nop 0
	global_load_lds_dwordx4 v196, s[24:25]
	v_mfma_f32_32x32x16_bf16 v[64:79], v[128:131], v[148:151], v[64:79]
	s_add_u32 m0, s88, 90112
	s_nop 0
	global_load_lds_dwordx4 v198, s[20:21]
	v_mfma_f32_32x32x16_bf16 v[0:15], v[132:135], v[148:151], v[0:15]
	s_add_u32 m0, s88, 122880
	s_nop 0
	global_load_lds_dwordx4 v198, s[24:25]
	ds_read_b128 v[128:131], v185
	ds_read_b128 v[136:139], v189
	ds_read_b128 v[132:135], v185 offset:4096
	ds_read_b128 v[140:143], v189 offset:4096
	ds_read_b128 v[144:147], v189 offset:8192
	ds_read_b128 v[148:151], v189 offset:12288
	s_waitcnt lgkmcnt(6)
	v_mfma_f32_32x32x16_bf16 v[112:127], v[160:163], v[168:171], v[112:127]
	v_mfma_f32_32x32x16_bf16 v[48:63], v[164:167], v[168:171], v[48:63]
	v_mfma_f32_32x32x16_bf16 v[96:111], v[160:163], v[172:175], v[96:111]
	v_mfma_f32_32x32x16_bf16 v[32:47], v[164:167], v[172:175], v[32:47]
	v_mfma_f32_32x32x16_bf16 v[80:95], v[160:163], v[176:179], v[80:95]
	v_mfma_f32_32x32x16_bf16 v[16:31], v[164:167], v[176:179], v[16:31]
	v_mfma_f32_32x32x16_bf16 v[64:79], v[160:163], v[180:183], v[64:79]
	v_mfma_f32_32x32x16_bf16 v[0:15], v[164:167], v[180:183], v[0:15]
	ds_read_b128 v[160:163], v186
	ds_read_b128 v[168:171], v190
	ds_read_b128 v[164:167], v186 offset:4096
	ds_read_b128 v[172:175], v190 offset:4096
	ds_read_b128 v[176:179], v190 offset:8192
	ds_read_b128 v[180:183], v190 offset:12288
	s_waitcnt lgkmcnt(6)
	v_mfma_f32_32x32x16_bf16 v[112:127], v[128:131], v[136:139], v[112:127]
	v_mfma_f32_32x32x16_bf16 v[48:63], v[132:135], v[136:139], v[48:63]
	v_mfma_f32_32x32x16_bf16 v[96:111], v[128:131], v[140:143], v[96:111]
	v_mfma_f32_32x32x16_bf16 v[32:47], v[132:135], v[140:143], v[32:47]
	v_mfma_f32_32x32x16_bf16 v[80:95], v[128:131], v[144:147], v[80:95]
	v_mfma_f32_32x32x16_bf16 v[16:31], v[132:135], v[144:147], v[16:31]
	v_mfma_f32_32x32x16_bf16 v[64:79], v[128:131], v[148:151], v[64:79]
	v_mfma_f32_32x32x16_bf16 v[0:15], v[132:135], v[148:151], v[0:15]
	ds_read_b128 v[128:131], v187
	ds_read_b128 v[136:139], v191
	ds_read_b128 v[132:135], v187 offset:4096
	ds_read_b128 v[140:143], v191 offset:4096
	ds_read_b128 v[144:147], v191 offset:8192
	ds_read_b128 v[148:151], v191 offset:12288
	s_waitcnt lgkmcnt(6)
	v_mfma_f32_32x32x16_bf16 v[112:127], v[160:163], v[168:171], v[112:127]
	v_mfma_f32_32x32x16_bf16 v[48:63], v[164:167], v[168:171], v[48:63]
	v_mfma_f32_32x32x16_bf16 v[96:111], v[160:163], v[172:175], v[96:111]
	v_mfma_f32_32x32x16_bf16 v[32:47], v[164:167], v[172:175], v[32:47]
	v_mfma_f32_32x32x16_bf16 v[80:95], v[160:163], v[176:179], v[80:95]
	v_mfma_f32_32x32x16_bf16 v[16:31], v[164:167], v[176:179], v[16:31]
	v_mfma_f32_32x32x16_bf16 v[64:79], v[160:163], v[180:183], v[64:79]
	v_mfma_f32_32x32x16_bf16 v[0:15], v[164:167], v[180:183], v[0:15]
	s_waitcnt vmcnt(0) lgkmcnt(0)
	s_barrier
	v_xor_b32_e32 v184, 0x10000, v184
	v_xor_b32_e32 v188, 0x10000, v188
	ds_read_b128 v[160:163], v184
	ds_read_b128 v[168:171], v188
	ds_read_b128 v[164:167], v184 offset:4096
	ds_read_b128 v[172:175], v188 offset:4096
	ds_read_b128 v[176:179], v188 offset:8192
	ds_read_b128 v[180:183], v188 offset:12288
	s_add_u32 s37, s30, s42
	s_cmp_ge_u32 s37, 768
	s_cbranch_scc1 .Lmq3q_nonext2
	s_mul_hi_u32 s38, s37, 0xaaaaaaab
	s_lshr_b32 s38, s38, 2
	s_mul_i32 s39, s38, 6
	s_sub_u32 s39, s37, s39
	s_lshl_b32 s98, s38, 17
	s_add_u32 s16, s4, s98
	s_addc_u32 s17, s5, 0
	s_lshl_b32 s98, s39, 17
	s_add_u32 s18, s6, s98
	s_addc_u32 s19, s7, 0
	v_mfma_f32_32x32x16_bf16 v[112:127], v[128:131], v[136:139], v[112:127]
	v_xor_b32_e32 v185, 0x10000, v185
	v_xor_b32_e32 v189, 0x10000, v189
	s_add_u32 m0, s88, 0
	s_nop 0
	global_load_lds_dwordx4 v192, s[16:17]
	v_mfma_f32_32x32x16_bf16 v[48:63], v[132:135], v[136:139], v[48:63]
	v_xor_b32_e32 v186, 0x10000, v186
	v_xor_b32_e32 v190, 0x10000, v190
	s_add_u32 m0, s88, 32768
	s_nop 0
	global_load_lds_dwordx4 v192, s[18:19]
	v_mfma_f32_32x32x16_bf16 v[96:111], v[128:131], v[140:143], v[96:111]
	v_xor_b32_e32 v187, 0x10000, v187
	v_xor_b32_e32 v191, 0x10000, v191
	s_add_u32 m0, s88, 8192
	s_nop 0
	global_load_lds_dwordx4 v194, s[16:17]
	v_mfma_f32_32x32x16_bf16 v[32:47], v[132:135], v[140:143], v[32:47]
	s_add_u32 m0, s88, 40960
	s_nop 0
	global_load_lds_dwordx4 v194, s[18:19]
	v_mfma_f32_32x32x16_bf16 v[80:95], v[128:131], v[144:147], v[80:95]
	s_add_u32 m0, s88, 16384
	s_nop 0
	global_load_lds_dwordx4 v196, s[16:17]
	v_mfma_f32_32x32x16_bf16 v[16:31], v[132:135], v[144:147], v[16:31]
	s_add_u32 m0, s88, 49152
	s_nop 0
	global_load_lds_dwordx4 v196, s[18:19]
	v_mfma_f32_32x32x16_bf16 v[64:79], v[128:131], v[148:151], v[64:79]
	s_add_u32 m0, s88, 24576
	s_nop 0
	global_load_lds_dwordx4 v198, s[16:17]
	v_mfma_f32_32x32x16_bf16 v[0:15], v[132:135], v[148:151], v[0:15]
	s_add_u32 m0, s88, 57344
	s_nop 0
	global_load_lds_dwordx4 v198, s[18:19]
	s_branch .Lmq3q_join2

.Lmq3q_done:
	s_load_dwordx2 s[4:5], s[0:1], 0x170
	s_load_dwordx2 s[6:7], s[0:1], 0xe0
	s_load_dwordx2 s[8:9], s[0:1], 0x218
	s_load_dwordx2 s[10:11], s[0:1], 0x148
	s_load_dwordx2 s[12:13], s[0:1], 0x180
	s_load_dwordx2 s[14:15], s[0:1], 0x188
	s_lshl_b32 s96, s29, 3
	v_add_u32_e32 v206, s96, v204
	v_xor_b32_e32 v207, v245, v205
	v_lshl_add_u32 v192, v206, 8, v207
	v_mov_b32_e32 v193, 0
	v_add_u32_e32 v208, 64, v206
	v_lshl_add_u32 v194, v208, 8, v207
	v_mov_b32_e32 v195, 0
	v_add_u32_e32 v208, 128, v206
	v_lshl_add_u32 v196, v208, 8, v207
	v_mov_b32_e32 v197, 0
	v_add_u32_e32 v208, 192, v206
	v_lshl_add_u32 v198, v208, 8, v207
	v_mov_b32_e32 v199, 0
	s_mov_b32 s30, s28
	s_cmp_ge_u32 s30, 1024
	s_cbranch_scc1 .Lmq3k_done
	s_waitcnt lgkmcnt(0)
	s_lshr_b32 s35, s30, 3
	s_mul_i32 s36, s35, 8
	s_sub_u32 s36, s30, s36
	s_lshl_b32 s98, s35, 16
	s_add_u32 s16, s4, s98
	s_addc_u32 s17, s5, 0
	s_lshl_b32 s98, s36, 16
	s_add_u32 s18, s6, s98
	s_addc_u32 s19, s7, 0
	s_add_u32 m0, s88, 0
	s_nop 0
	global_load_lds_dwordx4 v192, s[16:17]
	s_add_u32 m0, s88, 32768
	s_nop 0
	global_load_lds_dwordx4 v192, s[18:19]
	s_add_u32 m0, s88, 8192
	s_nop 0
	global_load_lds_dwordx4 v194, s[16:17]
	s_add_u32 m0, s88, 40960
	s_nop 0
	global_load_lds_dwordx4 v194, s[18:19]
	s_add_u32 m0, s88, 16384
	s_nop 0
	global_load_lds_dwordx4 v196, s[16:17]
	s_add_u32 m0, s88, 49152
	s_nop 0
	global_load_lds_dwordx4 v196, s[18:19]
	s_add_u32 m0, s88, 24576
	s_nop 0
	global_load_lds_dwordx4 v198, s[16:17]
	s_add_u32 m0, s88, 57344
	s_nop 0
	global_load_lds_dwordx4 v198, s[18:19]
.Lmq3k_tile:
	s_lshr_b32 s35, s30, 3
	s_mul_i32 s36, s35, 8
	s_sub_u32 s36, s30, s36
	s_lshl_b32 s92, s35, 8
	s_add_u32 s92, s92, s31
	s_lshl_b32 s93, s36, 8
	s_add_u32 s93, s93, s34
	s_lshl_b32 s96, s92, 2
	v_lshl_add_u32 v212, v203, 2, s96
	s_waitcnt vmcnt(0)
	s_barrier
	s_add_u32 s20, s16, 128
	s_addc_u32 s21, s17, 0
	s_add_u32 s24, s18, 128
	s_addc_u32 s25, s19, 0
	s_add_u32 m0, s88, 65536
	s_nop 0
	global_load_lds_dwordx4 v192, s[20:21]
	s_add_u32 m0, s88, 98304
	s_nop 0
	global_load_lds_dwordx4 v192, s[24:25]
	s_add_u32 m0, s88, 73728
	s_nop 0
	global_load_lds_dwordx4 v194, s[20:21]
	s_add_u32 m0, s88, 106496
	s_nop 0
	global_load_lds_dwordx4 v194, s[24:25]
	s_add_u32 m0, s88, 81920
	s_nop 0
	global_load_lds_dwordx4 v196, s[20:21]
	s_add_u32 m0, s88, 114688
	s_nop 0
	global_load_lds_dwordx4 v196, s[24:25]
	s_add_u32 m0, s88, 90112
	s_nop 0
	global_load_lds_dwordx4 v198, s[20:21]
	s_add_u32 m0, s88, 122880
	s_nop 0
	global_load_lds_dwordx4 v198, s[24:25]
	global_load_dword v213, v212, s[8:9] offset:0
	global_load_dword v214, v212, s[8:9] offset:4
	global_load_dword v215, v212, s[8:9] offset:8
	global_load_dword v216, v212, s[8:9] offset:12
	global_load_dword v217, v212, s[8:9] offset:32
	global_load_dword v218, v212, s[8:9] offset:36
	global_load_dword v219, v212, s[8:9] offset:40
	global_load_dword v220, v212, s[8:9] offset:44
	global_load_dword v221, v212, s[8:9] offset:64
	global_load_dword v222, v212, s[8:9] offset:68
	global_load_dword v223, v212, s[8:9] offset:72
	global_load_dword v224, v212, s[8:9] offset:76
	global_load_dword v225, v212, s[8:9] offset:96
	global_load_dword v226, v212, s[8:9] offset:100
	global_load_dword v227, v212, s[8:9] offset:104
	global_load_dword v228, v212, s[8:9] offset:108
	global_load_dword v229, v212, s[8:9] offset:128
	global_load_dword v230, v212, s[8:9] offset:132
	global_load_dword v231, v212, s[8:9] offset:136
	global_load_dword v232, v212, s[8:9] offset:140
	global_load_dword v233, v212, s[8:9] offset:160
	global_load_dword v234, v212, s[8:9] offset:164
	global_load_dword v235, v212, s[8:9] offset:168
	global_load_dword v236, v212, s[8:9] offset:172
	global_load_dword v237, v212, s[8:9] offset:192
	global_load_dword v238, v212, s[8:9] offset:196
	global_load_dword v239, v212, s[8:9] offset:200
	global_load_dword v240, v212, s[8:9] offset:204
	global_load_dword v241, v212, s[8:9] offset:224
	global_load_dword v242, v212, s[8:9] offset:228
	global_load_dword v243, v212, s[8:9] offset:232
	global_load_dword v244, v212, s[8:9] offset:236
	ds_read_b128 v[160:163], v184
	ds_read_b128 v[168:171], v188
	ds_read_b128 v[164:167], v184 offset:4096
	ds_read_b128 v[172:175], v188 offset:4096
	ds_read_b128 v[176:179], v188 offset:8192
	ds_read_b128 v[180:183], v188 offset:12288
	ds_read_b128 v[128:131], v185
	ds_read_b128 v[136:139], v189
	ds_read_b128 v[132:135], v185 offset:4096
	ds_read_b128 v[140:143], v189 offset:4096
	ds_read_b128 v[144:147], v189 offset:8192
	ds_read_b128 v[148:151], v189 offset:12288
	s_waitcnt lgkmcnt(6)
	v_mfma_f32_32x32x16_bf16 v[112:127], v[160:163], v[168:171], 0
	v_mfma_f32_32x32x16_bf16 v[48:63], v[164:167], v[168:171], 0
	v_mfma_f32_32x32x16_bf16 v[96:111], v[160:163], v[172:175], 0
	v_mfma_f32_32x32x16_bf16 v[32:47], v[164:167], v[172:175], 0
	v_mfma_f32_32x32x16_bf16 v[80:95], v[160:163], v[176:179], 0
	v_mfma_f32_32x32x16_bf16 v[16:31], v[164:167], v[176:179], 0
	v_mfma_f32_32x32x16_bf16 v[64:79], v[160:163], v[180:183], 0
	v_mfma_f32_32x32x16_bf16 v[0:15], v[164:167], v[180:183], 0
	ds_read_b128 v[160:163], v186
	ds_read_b128 v[168:171], v190
	ds_read_b128 v[164:167], v186 offset:4096
	ds_read_b128 v[172:175], v190 offset:4096
	ds_read_b128 v[176:179], v190 offset:8192
	ds_read_b128 v[180:183], v190 offset:12288
	s_waitcnt lgkmcnt(6)
	v_mfma_f32_32x32x16_bf16 v[112:127], v[128:131], v[136:139], v[112:127]
	v_mfma_f32_32x32x16_bf16 v[48:63], v[132:135], v[136:139], v[48:63]
	v_mfma_f32_32x32x16_bf16 v[96:111], v[128:131], v[140:143], v[96:111]
	v_mfma_f32_32x32x16_bf16 v[32:47], v[132:135], v[140:143], v[32:47]
	v_mfma_f32_32x32x16_bf16 v[80:95], v[128:131], v[144:147], v[80:95]
	v_mfma_f32_32x32x16_bf16 v[16:31], v[132:135], v[144:147], v[16:31]
	v_mfma_f32_32x32x16_bf16 v[64:79], v[128:131], v[148:151], v[64:79]
	v_mfma_f32_32x32x16_bf16 v[0:15], v[132:135], v[148:151], v[0:15]
	ds_read_b128 v[128:131], v187
	ds_read_b128 v[136:139], v191
	ds_read_b128 v[132:135], v187 offset:4096
	ds_read_b128 v[140:143], v191 offset:4096
	ds_read_b128 v[144:147], v191 offset:8192
	ds_read_b128 v[148:151], v191 offset:12288
	s_waitcnt lgkmcnt(6)
	v_mfma_f32_32x32x16_bf16 v[112:127], v[160:163], v[168:171], v[112:127]
	v_mfma_f32_32x32x16_bf16 v[48:63], v[164:167], v[168:171], v[48:63]
	v_mfma_f32_32x32x16_bf16 v[96:111], v[160:163], v[172:175], v[96:111]
	v_mfma_f32_32x32x16_bf16 v[32:47], v[164:167], v[172:175], v[32:47]
	v_mfma_f32_32x32x16_bf16 v[80:95], v[160:163], v[176:179], v[80:95]
	v_mfma_f32_32x32x16_bf16 v[16:31], v[164:167], v[176:179], v[16:31]
	v_mfma_f32_32x32x16_bf16 v[64:79], v[160:163], v[180:183], v[64:79]
	v_mfma_f32_32x32x16_bf16 v[0:15], v[164:167], v[180:183], v[0:15]
	s_waitcnt vmcnt(0) lgkmcnt(0)
	s_barrier
	v_xor_b32_e32 v184, 0x10000, v184
	v_xor_b32_e32 v188, 0x10000, v188
	ds_read_b128 v[160:163], v184
	ds_read_b128 v[168:171], v188
	ds_read_b128 v[164:167], v184 offset:4096
	ds_read_b128 v[172:175], v188 offset:4096
	ds_read_b128 v[176:179], v188 offset:8192
	ds_read_b128 v[180:183], v188 offset:12288
	s_add_u32 s37, s30, s42
	s_cmp_ge_u32 s37, 1024
	s_cbranch_scc1 .Lmq3k_nonext0
	s_lshr_b32 s38, s37, 3
	s_mul_i32 s39, s38, 8
	s_sub_u32 s39, s37, s39
	s_lshl_b32 s98, s38, 16
	s_add_u32 s16, s4, s98
	s_addc_u32 s17, s5, 0
	s_lshl_b32 s98, s39, 16
	s_add_u32 s18, s6, s98
	s_addc_u32 s19, s7, 0
	v_mfma_f32_32x32x16_bf16 v[112:127], v[128:131], v[136:139], v[112:127]
	v_xor_b32_e32 v185, 0x10000, v185
	v_xor_b32_e32 v189, 0x10000, v189
	s_add_u32 m0, s88, 0
	s_nop 0
	global_load_lds_dwordx4 v192, s[16:17]
	v_mfma_f32_32x32x16_bf16 v[48:63], v[132:135], v[136:139], v[48:63]
	v_xor_b32_e32 v186, 0x10000, v186
	v_xor_b32_e32 v190, 0x10000, v190
	s_add_u32 m0, s88, 32768
	s_nop 0
	global_load_lds_dwordx4 v192, s[18:19]
	v_mfma_f32_32x32x16_bf16 v[96:111], v[128:131], v[140:143], v[96:111]
	v_xor_b32_e32 v187, 0x10000, v187
	v_xor_b32_e32 v191, 0x10000, v191
	s_add_u32 m0, s88, 8192
	s_nop 0
	global_load_lds_dwordx4 v194, s[16:17]
	v_mfma_f32_32x32x16_bf16 v[32:47], v[132:135], v[140:143], v[32:47]
	s_add_u32 m0, s88, 40960
	s_nop 0
	global_load_lds_dwordx4 v194, s[18:19]
	v_mfma_f32_32x32x16_bf16 v[80:95], v[128:131], v[144:147], v[80:95]
	s_add_u32 m0, s88, 16384
	s_nop 0
	global_load_lds_dwordx4 v196, s[16:17]
	v_mfma_f32_32x32x16_bf16 v[16:31], v[132:135], v[144:147], v[16:31]
	s_add_u32 m0, s88, 49152
	s_nop 0
	global_load_lds_dwordx4 v196, s[18:19]
	v_mfma_f32_32x32x16_bf16 v[64:79], v[128:131], v[148:151], v[64:79]
	s_add_u32 m0, s88, 24576
	s_nop 0
	global_load_lds_dwordx4 v198, s[16:17]
	v_mfma_f32_32x32x16_bf16 v[0:15], v[132:135], v[148:151], v[0:15]
	s_add_u32 m0, s88, 57344
	s_nop 0
	global_load_lds_dwordx4 v198, s[18:19]
	s_branch .Lmq3k_join0

.Lip11_vb:
	s_load_dwordx2 s[4:5], s[0:1], 0x158
	s_load_dwordx2 s[6:7], s[0:1], 0x110
	v_mbcnt_hi_u32_b32 v234, -1, v210
	s_lshr_b32 s29, s70, 6
	s_lshl_b32 s27, s70, 4
	s_and_b32 s90, s70, 0x40
	v_and_b32_e32 v200, 48, v234
	v_or_b32_e32 v200, s90, v200
	v_and_b32_e32 v235, 31, v234
	v_lshrrev_b32_e32 v236, 5, v234
	v_bfe_u32 v237, v234, 1, 3
	v_lshlrev_b32_e32 v238, 7, v235
	s_lshr_b32 s91, s70, 7
	s_lshl_b32 s91, s91, 13
	s_and_b32 s31, s29, 1
	s_lshl_b32 s90, s90, 8
	s_add_u32 s90, s90, 0x8000
	v_xor_b32_e32 v239, v236, v237
	v_lshl_add_u32 v239, v239, 4, v238
	v_add_u32_e32 v184, s91, v239
	v_add_u32_e32 v188, s90, v239
	v_or_b32_e32 v239, 2, v236
	v_xor_b32_e32 v239, v239, v237
	v_lshl_add_u32 v239, v239, 4, v238
	v_add_u32_e32 v185, s91, v239
	v_add_u32_e32 v189, s90, v239
	v_or_b32_e32 v239, 4, v236
	v_xor_b32_e32 v239, v239, v237
	v_lshl_add_u32 v239, v239, 4, v238
	v_add_u32_e32 v186, s91, v239
	v_add_u32_e32 v190, s90, v239
	v_or_b32_e32 v239, 6, v236
	v_xor_b32_e32 v239, v239, v237
	v_lshl_add_u32 v239, v239, 4, v238
	v_add_u32_e32 v187, s91, v239
	v_add_u32_e32 v191, s90, v239
	v_lshrrev_b32_e32 v238, 3, v234
	s_lshl_b32 s96, s29, 3
	v_add_u32_e32 v238, s96, v238
	v_and_b32_e32 v239, 7, v234
	v_lshlrev_b32_e32 v239, 4, v239
	v_xor_b32_e32 v239, v200, v239
	v_lshl_add_u32 v192, v238, 11, v239
	v_mov_b32_e32 v193, 0
	v_add_u32_e32 v237, 64, v238
	v_lshl_add_u32 v194, v237, 11, v239
	v_mov_b32_e32 v195, 0
	v_add_u32_e32 v237, 128, v238
	v_lshl_add_u32 v196, v237, 11, v239
	v_mov_b32_e32 v197, 0
	v_add_u32_e32 v237, 192, v238
	v_lshl_add_u32 v198, v237, 11, v239
	v_mov_b32_e32 v199, 0
	s_mov_b32 s30, s28
	s_cmpk_ge_u32 s30, 0x780
	s_cbranch_scc1 .Lip11_done
	s_waitcnt lgkmcnt(0)
	s_mul_hi_u32 s35, s30, 0x92492493
	s_lshr_b32 s35, s35, 3
	s_mul_i32 s36, s35, 14
	s_sub_u32 s36, s30, s36
	s_sub_u32 s98, s30, 0x700
	s_cmpk_lt_u32 s30, 0x700
	s_cselect_b32 s36, s36, 14
	s_cselect_b32 s35, s35, s98
	s_lshl_b32 s98, s35, 19
	s_add_u32 s16, s4, s98
	s_addc_u32 s17, s5, 0
	s_lshl_b32 s98, s36, 19
	s_add_u32 s18, s6, s98
	s_addc_u32 s19, s7, 0
	s_add_u32 m0, s27, 0
	s_nop 0
	global_load_lds_dwordx4 v192, s[16:17]
	s_add_u32 m0, s27, 32768
	s_nop 0
	global_load_lds_dwordx4 v192, s[18:19]
	s_add_u32 m0, s27, 8192
	s_nop 0
	global_load_lds_dwordx4 v194, s[16:17]
	s_add_u32 m0, s27, 40960
	s_nop 0
	global_load_lds_dwordx4 v194, s[18:19]
	s_add_u32 m0, s27, 16384
	s_nop 0
	global_load_lds_dwordx4 v196, s[16:17]
	s_add_u32 m0, s27, 49152
	s_nop 0
	global_load_lds_dwordx4 v196, s[18:19]
	s_add_u32 m0, s27, 24576
	s_nop 0
	global_load_lds_dwordx4 v198, s[16:17]
	s_add_u32 m0, s27, 57344
	s_nop 0
	global_load_lds_dwordx4 v198, s[18:19]
.Lip11_tile:
	s_mul_hi_u32 s35, s30, 0x92492493
	s_lshr_b32 s35, s35, 3
	s_mul_i32 s36, s35, 14
	s_sub_u32 s36, s30, s36
	s_sub_u32 s98, s30, 0x700
	s_cmpk_lt_u32 s30, 0x700
	s_cselect_b32 s36, s36, 14
	s_cselect_b32 s35, s35, s98
	s_waitcnt vmcnt(0)
	s_barrier
	s_add_u32 s20, s16, 128
	s_addc_u32 s21, s17, 0
	s_add_u32 s24, s18, 128
	s_addc_u32 s25, s19, 0
	s_add_u32 m0, s27, 65536
	s_nop 0
	global_load_lds_dwordx4 v192, s[20:21]
	s_add_u32 m0, s27, 98304
	s_nop 0
	global_load_lds_dwordx4 v192, s[24:25]
	s_add_u32 m0, s27, 73728
	s_nop 0
	global_load_lds_dwordx4 v194, s[20:21]
	s_add_u32 m0, s27, 106496
	s_nop 0
	global_load_lds_dwordx4 v194, s[24:25]
	s_add_u32 m0, s27, 81920
	s_nop 0
	global_load_lds_dwordx4 v196, s[20:21]
	s_add_u32 m0, s27, 114688
	s_nop 0
	global_load_lds_dwordx4 v196, s[24:25]
	s_add_u32 m0, s27, 90112
	s_nop 0
	global_load_lds_dwordx4 v198, s[20:21]
	s_add_u32 m0, s27, 122880
	s_nop 0
	global_load_lds_dwordx4 v198, s[24:25]
	s_cmp_eq_u32 s36, 14
	s_cbranch_scc1 .Lip11_light
	ds_read_b128 v[160:163], v184
	ds_read_b128 v[168:171], v188
	ds_read_b128 v[164:167], v184 offset:4096
	ds_read_b128 v[172:175], v188 offset:4096
	ds_read_b128 v[176:179], v188 offset:8192
	ds_read_b128 v[180:183], v188 offset:12288
	ds_read_b128 v[128:131], v185
	ds_read_b128 v[136:139], v189
	ds_read_b128 v[132:135], v185 offset:4096
	ds_read_b128 v[140:143], v189 offset:4096
	ds_read_b128 v[144:147], v189 offset:8192
	ds_read_b128 v[148:151], v189 offset:12288
	s_waitcnt lgkmcnt(6)
	v_mfma_f32_32x32x16_bf16 v[112:127], v[160:163], v[168:171], 0
	v_mfma_f32_32x32x16_bf16 v[48:63], v[164:167], v[168:171], 0
	v_mfma_f32_32x32x16_bf16 v[96:111], v[160:163], v[172:175], 0
	v_mfma_f32_32x32x16_bf16 v[32:47], v[164:167], v[172:175], 0
	v_mfma_f32_32x32x16_bf16 v[80:95], v[160:163], v[176:179], 0
	v_mfma_f32_32x32x16_bf16 v[16:31], v[164:167], v[176:179], 0
	v_mfma_f32_32x32x16_bf16 v[64:79], v[160:163], v[180:183], 0
	v_mfma_f32_32x32x16_bf16 v[0:15], v[164:167], v[180:183], 0
	ds_read_b128 v[160:163], v186
	ds_read_b128 v[168:171], v190
	ds_read_b128 v[164:167], v186 offset:4096
	ds_read_b128 v[172:175], v190 offset:4096
	ds_read_b128 v[176:179], v190 offset:8192
	ds_read_b128 v[180:183], v190 offset:12288
	s_waitcnt lgkmcnt(6)
	v_mfma_f32_32x32x16_bf16 v[112:127], v[128:131], v[136:139], v[112:127]
	v_mfma_f32_32x32x16_bf16 v[48:63], v[132:135], v[136:139], v[48:63]
	v_mfma_f32_32x32x16_bf16 v[96:111], v[128:131], v[140:143], v[96:111]
	v_mfma_f32_32x32x16_bf16 v[32:47], v[132:135], v[140:143], v[32:47]
	v_mfma_f32_32x32x16_bf16 v[80:95], v[128:131], v[144:147], v[80:95]
	v_mfma_f32_32x32x16_bf16 v[16:31], v[132:135], v[144:147], v[16:31]
	v_mfma_f32_32x32x16_bf16 v[64:79], v[128:131], v[148:151], v[64:79]
	v_mfma_f32_32x32x16_bf16 v[0:15], v[132:135], v[148:151], v[0:15]
	ds_read_b128 v[128:131], v187
	ds_read_b128 v[136:139], v191
	ds_read_b128 v[132:135], v187 offset:4096
	ds_read_b128 v[140:143], v191 offset:4096
	ds_read_b128 v[144:147], v191 offset:8192
	ds_read_b128 v[148:151], v191 offset:12288
	s_waitcnt lgkmcnt(6)
	v_mfma_f32_32x32x16_bf16 v[112:127], v[160:163], v[168:171], v[112:127]
	v_mfma_f32_32x32x16_bf16 v[48:63], v[164:167], v[168:171], v[48:63]
	v_mfma_f32_32x32x16_bf16 v[96:111], v[160:163], v[172:175], v[96:111]
	v_mfma_f32_32x32x16_bf16 v[32:47], v[164:167], v[172:175], v[32:47]
	v_mfma_f32_32x32x16_bf16 v[80:95], v[160:163], v[176:179], v[80:95]
	v_mfma_f32_32x32x16_bf16 v[16:31], v[164:167], v[176:179], v[16:31]
	v_mfma_f32_32x32x16_bf16 v[64:79], v[160:163], v[180:183], v[64:79]
	v_mfma_f32_32x32x16_bf16 v[0:15], v[164:167], v[180:183], v[0:15]
	s_waitcnt vmcnt(0) lgkmcnt(0)
	s_barrier
	v_xor_b32_e32 v184, 0x10000, v184
	v_xor_b32_e32 v188, 0x10000, v188
	ds_read_b128 v[160:163], v184
	ds_read_b128 v[168:171], v188
	ds_read_b128 v[164:167], v184 offset:4096
	ds_read_b128 v[172:175], v188 offset:4096
	ds_read_b128 v[176:179], v188 offset:8192
	ds_read_b128 v[180:183], v188 offset:12288
	s_add_u32 s20, s16, 256
	s_addc_u32 s21, s17, 0
	s_add_u32 s24, s18, 256
	s_addc_u32 s25, s19, 0
	v_mfma_f32_32x32x16_bf16 v[112:127], v[128:131], v[136:139], v[112:127]
	v_xor_b32_e32 v185, 0x10000, v185
	v_xor_b32_e32 v189, 0x10000, v189
	s_add_u32 m0, s27, 0
	s_nop 0
	global_load_lds_dwordx4 v192, s[20:21]
	v_mfma_f32_32x32x16_bf16 v[48:63], v[132:135], v[136:139], v[48:63]
	v_xor_b32_e32 v186, 0x10000, v186
	v_xor_b32_e32 v190, 0x10000, v190
	s_add_u32 m0, s27, 32768
	s_nop 0
	global_load_lds_dwordx4 v192, s[24:25]
	v_mfma_f32_32x32x16_bf16 v[96:111], v[128:131], v[140:143], v[96:111]
	v_xor_b32_e32 v187, 0x10000, v187
	v_xor_b32_e32 v191, 0x10000, v191
	s_add_u32 m0, s27, 8192
	s_nop 0
	global_load_lds_dwordx4 v194, s[20:21]
	v_mfma_f32_32x32x16_bf16 v[32:47], v[132:135], v[140:143], v[32:47]
	s_add_u32 m0, s27, 40960
	s_nop 0
	global_load_lds_dwordx4 v194, s[24:25]
	v_mfma_f32_32x32x16_bf16 v[80:95], v[128:131], v[144:147], v[80:95]
	s_add_u32 m0, s27, 16384
	s_nop 0
	global_load_lds_dwordx4 v196, s[20:21]
	v_mfma_f32_32x32x16_bf16 v[16:31], v[132:135], v[144:147], v[16:31]
	s_add_u32 m0, s27, 49152
	s_nop 0
	global_load_lds_dwordx4 v196, s[24:25]
	v_mfma_f32_32x32x16_bf16 v[64:79], v[128:131], v[148:151], v[64:79]
	s_add_u32 m0, s27, 24576
	s_nop 0
	global_load_lds_dwordx4 v198, s[20:21]
	v_mfma_f32_32x32x16_bf16 v[0:15], v[132:135], v[148:151], v[0:15]
	s_add_u32 m0, s27, 57344
	s_nop 0
	global_load_lds_dwordx4 v198, s[24:25]
	ds_read_b128 v[128:131], v185
	ds_read_b128 v[136:139], v189
	ds_read_b128 v[132:135], v185 offset:4096
	ds_read_b128 v[140:143], v189 offset:4096
	ds_read_b128 v[144:147], v189 offset:8192
	ds_read_b128 v[148:151], v189 offset:12288
	s_waitcnt lgkmcnt(6)
	v_mfma_f32_32x32x16_bf16 v[112:127], v[160:163], v[168:171], v[112:127]
	v_mfma_f32_32x32x16_bf16 v[48:63], v[164:167], v[168:171], v[48:63]
	v_mfma_f32_32x32x16_bf16 v[96:111], v[160:163], v[172:175], v[96:111]
	v_mfma_f32_32x32x16_bf16 v[32:47], v[164:167], v[172:175], v[32:47]
	v_mfma_f32_32x32x16_bf16 v[80:95], v[160:163], v[176:179], v[80:95]
	v_mfma_f32_32x32x16_bf16 v[16:31], v[164:167], v[176:179], v[16:31]
	v_mfma_f32_32x32x16_bf16 v[64:79], v[160:163], v[180:183], v[64:79]
	v_mfma_f32_32x32x16_bf16 v[0:15], v[164:167], v[180:183], v[0:15]
	ds_read_b128 v[160:163], v186
	ds_read_b128 v[168:171], v190
	ds_read_b128 v[164:167], v186 offset:4096
	ds_read_b128 v[172:175], v190 offset:4096
	ds_read_b128 v[176:179], v190 offset:8192
	ds_read_b128 v[180:183], v190 offset:12288
	s_waitcnt lgkmcnt(6)
	v_mfma_f32_32x32x16_bf16 v[112:127], v[128:131], v[136:139], v[112:127]
	v_mfma_f32_32x32x16_bf16 v[48:63], v[132:135], v[136:139], v[48:63]
	v_mfma_f32_32x32x16_bf16 v[96:111], v[128:131], v[140:143], v[96:111]
	v_mfma_f32_32x32x16_bf16 v[32:47], v[132:135], v[140:143], v[32:47]
	v_mfma_f32_32x32x16_bf16 v[80:95], v[128:131], v[144:147], v[80:95]
	v_mfma_f32_32x32x16_bf16 v[16:31], v[132:135], v[144:147], v[16:31]
	v_mfma_f32_32x32x16_bf16 v[64:79], v[128:131], v[148:151], v[64:79]
	v_mfma_f32_32x32x16_bf16 v[0:15], v[132:135], v[148:151], v[0:15]
	ds_read_b128 v[128:131], v187
	ds_read_b128 v[136:139], v191
	ds_read_b128 v[132:135], v187 offset:4096
	ds_read_b128 v[140:143], v191 offset:4096
	ds_read_b128 v[144:147], v191 offset:8192
	ds_read_b128 v[148:151], v191 offset:12288
	s_waitcnt lgkmcnt(6)
	v_mfma_f32_32x32x16_bf16 v[112:127], v[160:163], v[168:171], v[112:127]
	v_mfma_f32_32x32x16_bf16 v[48:63], v[164:167], v[168:171], v[48:63]
	v_mfma_f32_32x32x16_bf16 v[96:111], v[160:163], v[172:175], v[96:111]
	v_mfma_f32_32x32x16_bf16 v[32:47], v[164:167], v[172:175], v[32:47]
	v_mfma_f32_32x32x16_bf16 v[80:95], v[160:163], v[176:179], v[80:95]
	v_mfma_f32_32x32x16_bf16 v[16:31], v[164:167], v[176:179], v[16:31]
	v_mfma_f32_32x32x16_bf16 v[64:79], v[160:163], v[180:183], v[64:79]
	v_mfma_f32_32x32x16_bf16 v[0:15], v[164:167], v[180:183], v[0:15]
	s_waitcnt vmcnt(0) lgkmcnt(0)
	s_barrier
	v_xor_b32_e32 v184, 0x10000, v184
	v_xor_b32_e32 v188, 0x10000, v188
	ds_read_b128 v[160:163], v184
	ds_read_b128 v[168:171], v188
	ds_read_b128 v[164:167], v184 offset:4096
	ds_read_b128 v[172:175], v188 offset:4096
	ds_read_b128 v[176:179], v188 offset:8192
	ds_read_b128 v[180:183], v188 offset:12288
	s_add_u32 s20, s16, 384
	s_addc_u32 s21, s17, 0
	s_add_u32 s24, s18, 384
	s_addc_u32 s25, s19, 0
	v_mfma_f32_32x32x16_bf16 v[112:127], v[128:131], v[136:139], v[112:127]
	v_xor_b32_e32 v185, 0x10000, v185
	v_xor_b32_e32 v189, 0x10000, v189
	s_add_u32 m0, s27, 65536
	s_nop 0
	global_load_lds_dwordx4 v192, s[20:21]
	v_mfma_f32_32x32x16_bf16 v[48:63], v[132:135], v[136:139], v[48:63]
	v_xor_b32_e32 v186, 0x10000, v186
	v_xor_b32_e32 v190, 0x10000, v190
	s_add_u32 m0, s27, 98304
	s_nop 0
	global_load_lds_dwordx4 v192, s[24:25]
	v_mfma_f32_32x32x16_bf16 v[96:111], v[128:131], v[140:143], v[96:111]
	v_xor_b32_e32 v187, 0x10000, v187
	v_xor_b32_e32 v191, 0x10000, v191
	s_add_u32 m0, s27, 73728
	s_nop 0
	global_load_lds_dwordx4 v194, s[20:21]
	v_mfma_f32_32x32x16_bf16 v[32:47], v[132:135], v[140:143], v[32:47]
	s_add_u32 m0, s27, 106496
	s_nop 0
	global_load_lds_dwordx4 v194, s[24:25]
	v_mfma_f32_32x32x16_bf16 v[80:95], v[128:131], v[144:147], v[80:95]
	s_add_u32 m0, s27, 81920
	s_nop 0
	global_load_lds_dwordx4 v196, s[20:21]
	v_mfma_f32_32x32x16_bf16 v[16:31], v[132:135], v[144:147], v[16:31]
	s_add_u32 m0, s27, 114688
	s_nop 0
	global_load_lds_dwordx4 v196, s[24:25]
	v_mfma_f32_32x32x16_bf16 v[64:79], v[128:131], v[148:151], v[64:79]
	s_add_u32 m0, s27, 90112
	s_nop 0
	global_load_lds_dwordx4 v198, s[20:21]
	v_mfma_f32_32x32x16_bf16 v[0:15], v[132:135], v[148:151], v[0:15]
	s_add_u32 m0, s27, 122880
	s_nop 0
	global_load_lds_dwordx4 v198, s[24:25]
	ds_read_b128 v[128:131], v185
	ds_read_b128 v[136:139], v189
	ds_read_b128 v[132:135], v185 offset:4096
	ds_read_b128 v[140:143], v189 offset:4096
	ds_read_b128 v[144:147], v189 offset:8192
	ds_read_b128 v[148:151], v189 offset:12288
	s_waitcnt lgkmcnt(6)
	v_mfma_f32_32x32x16_bf16 v[112:127], v[160:163], v[168:171], v[112:127]
	v_mfma_f32_32x32x16_bf16 v[48:63], v[164:167], v[168:171], v[48:63]
	v_mfma_f32_32x32x16_bf16 v[96:111], v[160:163], v[172:175], v[96:111]
	v_mfma_f32_32x32x16_bf16 v[32:47], v[164:167], v[172:175], v[32:47]
	v_mfma_f32_32x32x16_bf16 v[80:95], v[160:163], v[176:179], v[80:95]
	v_mfma_f32_32x32x16_bf16 v[16:31], v[164:167], v[176:179], v[16:31]
	v_mfma_f32_32x32x16_bf16 v[64:79], v[160:163], v[180:183], v[64:79]
	v_mfma_f32_32x32x16_bf16 v[0:15], v[164:167], v[180:183], v[0:15]
	ds_read_b128 v[160:163], v186
	ds_read_b128 v[168:171], v190
	ds_read_b128 v[164:167], v186 offset:4096
	ds_read_b128 v[172:175], v190 offset:4096
	ds_read_b128 v[176:179], v190 offset:8192
	ds_read_b128 v[180:183], v190 offset:12288
	s_waitcnt lgkmcnt(6)
	v_mfma_f32_32x32x16_bf16 v[112:127], v[128:131], v[136:139], v[112:127]
	v_mfma_f32_32x32x16_bf16 v[48:63], v[132:135], v[136:139], v[48:63]
	v_mfma_f32_32x32x16_bf16 v[96:111], v[128:131], v[140:143], v[96:111]
	v_mfma_f32_32x32x16_bf16 v[32:47], v[132:135], v[140:143], v[32:47]
	v_mfma_f32_32x32x16_bf16 v[80:95], v[128:131], v[144:147], v[80:95]
	v_mfma_f32_32x32x16_bf16 v[16:31], v[132:135], v[144:147], v[16:31]
	v_mfma_f32_32x32x16_bf16 v[64:79], v[128:131], v[148:151], v[64:79]
	v_mfma_f32_32x32x16_bf16 v[0:15], v[132:135], v[148:151], v[0:15]
	ds_read_b128 v[128:131], v187
	ds_read_b128 v[136:139], v191
	ds_read_b128 v[132:135], v187 offset:4096
	ds_read_b128 v[140:143], v191 offset:4096
	ds_read_b128 v[144:147], v191 offset:8192
	ds_read_b128 v[148:151], v191 offset:12288
	s_waitcnt lgkmcnt(6)
	v_mfma_f32_32x32x16_bf16 v[112:127], v[160:163], v[168:171], v[112:127]
	v_mfma_f32_32x32x16_bf16 v[48:63], v[164:167], v[168:171], v[48:63]
	v_mfma_f32_32x32x16_bf16 v[96:111], v[160:163], v[172:175], v[96:111]
	v_mfma_f32_32x32x16_bf16 v[32:47], v[164:167], v[172:175], v[32:47]
	v_mfma_f32_32x32x16_bf16 v[80:95], v[160:163], v[176:179], v[80:95]
	v_mfma_f32_32x32x16_bf16 v[16:31], v[164:167], v[176:179], v[16:31]
	v_mfma_f32_32x32x16_bf16 v[64:79], v[160:163], v[180:183], v[64:79]
	v_mfma_f32_32x32x16_bf16 v[0:15], v[164:167], v[180:183], v[0:15]
	s_waitcnt vmcnt(0) lgkmcnt(0)
	s_barrier
	v_xor_b32_e32 v184, 0x10000, v184
	v_xor_b32_e32 v188, 0x10000, v188
	ds_read_b128 v[160:163], v184
	ds_read_b128 v[168:171], v188
	ds_read_b128 v[164:167], v184 offset:4096
	ds_read_b128 v[172:175], v188 offset:4096
	ds_read_b128 v[176:179], v188 offset:8192
	ds_read_b128 v[180:183], v188 offset:12288
	s_add_u32 s20, s16, 512
	s_addc_u32 s21, s17, 0
	s_add_u32 s24, s18, 512
	s_addc_u32 s25, s19, 0
	v_mfma_f32_32x32x16_bf16 v[112:127], v[128:131], v[136:139], v[112:127]
	v_xor_b32_e32 v185, 0x10000, v185
	v_xor_b32_e32 v189, 0x10000, v189
	s_add_u32 m0, s27, 0
	s_nop 0
	global_load_lds_dwordx4 v192, s[20:21]
	v_mfma_f32_32x32x16_bf16 v[48:63], v[132:135], v[136:139], v[48:63]
	v_xor_b32_e32 v186, 0x10000, v186
	v_xor_b32_e32 v190, 0x10000, v190
	s_add_u32 m0, s27, 32768
	s_nop 0
	global_load_lds_dwordx4 v192, s[24:25]
	v_mfma_f32_32x32x16_bf16 v[96:111], v[128:131], v[140:143], v[96:111]
	v_xor_b32_e32 v187, 0x10000, v187
	v_xor_b32_e32 v191, 0x10000, v191
	s_add_u32 m0, s27, 8192
	s_nop 0
	global_load_lds_dwordx4 v194, s[20:21]
	v_mfma_f32_32x32x16_bf16 v[32:47], v[132:135], v[140:143], v[32:47]
	s_add_u32 m0, s27, 40960
	s_nop 0
	global_load_lds_dwordx4 v194, s[24:25]
	v_mfma_f32_32x32x16_bf16 v[80:95], v[128:131], v[144:147], v[80:95]
	s_add_u32 m0, s27, 16384
	s_nop 0
	global_load_lds_dwordx4 v196, s[20:21]
	v_mfma_f32_32x32x16_bf16 v[16:31], v[132:135], v[144:147], v[16:31]
	s_add_u32 m0, s27, 49152
	s_nop 0
	global_load_lds_dwordx4 v196, s[24:25]
	v_mfma_f32_32x32x16_bf16 v[64:79], v[128:131], v[148:151], v[64:79]
	s_add_u32 m0, s27, 24576
	s_nop 0
	global_load_lds_dwordx4 v198, s[20:21]
	v_mfma_f32_32x32x16_bf16 v[0:15], v[132:135], v[148:151], v[0:15]
	s_add_u32 m0, s27, 57344
	s_nop 0
	global_load_lds_dwordx4 v198, s[24:25]
	ds_read_b128 v[128:131], v185
	ds_read_b128 v[136:139], v189
	ds_read_b128 v[132:135], v185 offset:4096
	ds_read_b128 v[140:143], v189 offset:4096
	ds_read_b128 v[144:147], v189 offset:8192
	ds_read_b128 v[148:151], v189 offset:12288
	s_waitcnt lgkmcnt(6)
	v_mfma_f32_32x32x16_bf16 v[112:127], v[160:163], v[168:171], v[112:127]
	v_mfma_f32_32x32x16_bf16 v[48:63], v[164:167], v[168:171], v[48:63]
	v_mfma_f32_32x32x16_bf16 v[96:111], v[160:163], v[172:175], v[96:111]
	v_mfma_f32_32x32x16_bf16 v[32:47], v[164:167], v[172:175], v[32:47]
	v_mfma_f32_32x32x16_bf16 v[80:95], v[160:163], v[176:179], v[80:95]
	v_mfma_f32_32x32x16_bf16 v[16:31], v[164:167], v[176:179], v[16:31]
	v_mfma_f32_32x32x16_bf16 v[64:79], v[160:163], v[180:183], v[64:79]
	v_mfma_f32_32x32x16_bf16 v[0:15], v[164:167], v[180:183], v[0:15]
	ds_read_b128 v[160:163], v186
	ds_read_b128 v[168:171], v190
	ds_read_b128 v[164:167], v186 offset:4096
	ds_read_b128 v[172:175], v190 offset:4096
	ds_read_b128 v[176:179], v190 offset:8192
	ds_read_b128 v[180:183], v190 offset:12288
	s_waitcnt lgkmcnt(6)
	v_mfma_f32_32x32x16_bf16 v[112:127], v[128:131], v[136:139], v[112:127]
	v_mfma_f32_32x32x16_bf16 v[48:63], v[132:135], v[136:139], v[48:63]
	v_mfma_f32_32x32x16_bf16 v[96:111], v[128:131], v[140:143], v[96:111]
	v_mfma_f32_32x32x16_bf16 v[32:47], v[132:135], v[140:143], v[32:47]
	v_mfma_f32_32x32x16_bf16 v[80:95], v[128:131], v[144:147], v[80:95]
	v_mfma_f32_32x32x16_bf16 v[16:31], v[132:135], v[144:147], v[16:31]
	v_mfma_f32_32x32x16_bf16 v[64:79], v[128:131], v[148:151], v[64:79]
	v_mfma_f32_32x32x16_bf16 v[0:15], v[132:135], v[148:151], v[0:15]
	ds_read_b128 v[128:131], v187
	ds_read_b128 v[136:139], v191
	ds_read_b128 v[132:135], v187 offset:4096
	ds_read_b128 v[140:143], v191 offset:4096
	ds_read_b128 v[144:147], v191 offset:8192
	ds_read_b128 v[148:151], v191 offset:12288
	s_waitcnt lgkmcnt(6)
	v_mfma_f32_32x32x16_bf16 v[112:127], v[160:163], v[168:171], v[112:127]
	v_mfma_f32_32x32x16_bf16 v[48:63], v[164:167], v[168:171], v[48:63]
	v_mfma_f32_32x32x16_bf16 v[96:111], v[160:163], v[172:175], v[96:111]
	v_mfma_f32_32x32x16_bf16 v[32:47], v[164:167], v[172:175], v[32:47]
	v_mfma_f32_32x32x16_bf16 v[80:95], v[160:163], v[176:179], v[80:95]
	v_mfma_f32_32x32x16_bf16 v[16:31], v[164:167], v[176:179], v[16:31]
	v_mfma_f32_32x32x16_bf16 v[64:79], v[160:163], v[180:183], v[64:79]
	v_mfma_f32_32x32x16_bf16 v[0:15], v[164:167], v[180:183], v[0:15]
	s_waitcnt vmcnt(0) lgkmcnt(0)
	s_barrier
	v_xor_b32_e32 v184, 0x10000, v184
	v_xor_b32_e32 v188, 0x10000, v188
	ds_read_b128 v[160:163], v184
	ds_read_b128 v[168:171], v188
	ds_read_b128 v[164:167], v184 offset:4096
	ds_read_b128 v[172:175], v188 offset:4096
	ds_read_b128 v[176:179], v188 offset:8192
	ds_read_b128 v[180:183], v188 offset:12288
	s_add_u32 s20, s16, 640
	s_addc_u32 s21, s17, 0
	s_add_u32 s24, s18, 640
	s_addc_u32 s25, s19, 0
	v_mfma_f32_32x32x16_bf16 v[112:127], v[128:131], v[136:139], v[112:127]
	v_xor_b32_e32 v185, 0x10000, v185
	v_xor_b32_e32 v189, 0x10000, v189
	s_add_u32 m0, s27, 65536
	s_nop 0
	global_load_lds_dwordx4 v192, s[20:21]
	v_mfma_f32_32x32x16_bf16 v[48:63], v[132:135], v[136:139], v[48:63]
	v_xor_b32_e32 v186, 0x10000, v186
	v_xor_b32_e32 v190, 0x10000, v190
	s_add_u32 m0, s27, 98304
	s_nop 0
	global_load_lds_dwordx4 v192, s[24:25]
	v_mfma_f32_32x32x16_bf16 v[96:111], v[128:131], v[140:143], v[96:111]
	v_xor_b32_e32 v187, 0x10000, v187
	v_xor_b32_e32 v191, 0x10000, v191
	s_add_u32 m0, s27, 73728
	s_nop 0
	global_load_lds_dwordx4 v194, s[20:21]
	v_mfma_f32_32x32x16_bf16 v[32:47], v[132:135], v[140:143], v[32:47]
	s_add_u32 m0, s27, 106496
	s_nop 0
	global_load_lds_dwordx4 v194, s[24:25]
	v_mfma_f32_32x32x16_bf16 v[80:95], v[128:131], v[144:147], v[80:95]
	s_add_u32 m0, s27, 81920
	s_nop 0
	global_load_lds_dwordx4 v196, s[20:21]
	v_mfma_f32_32x32x16_bf16 v[16:31], v[132:135], v[144:147], v[16:31]
	s_add_u32 m0, s27, 114688
	s_nop 0
	global_load_lds_dwordx4 v196, s[24:25]
	v_mfma_f32_32x32x16_bf16 v[64:79], v[128:131], v[148:151], v[64:79]
	s_add_u32 m0, s27, 90112
	s_nop 0
	global_load_lds_dwordx4 v198, s[20:21]
	v_mfma_f32_32x32x16_bf16 v[0:15], v[132:135], v[148:151], v[0:15]
	s_add_u32 m0, s27, 122880
	s_nop 0
	global_load_lds_dwordx4 v198, s[24:25]
	ds_read_b128 v[128:131], v185
	ds_read_b128 v[136:139], v189
	ds_read_b128 v[132:135], v185 offset:4096
	ds_read_b128 v[140:143], v189 offset:4096
	ds_read_b128 v[144:147], v189 offset:8192
	ds_read_b128 v[148:151], v189 offset:12288
	s_waitcnt lgkmcnt(6)
	v_mfma_f32_32x32x16_bf16 v[112:127], v[160:163], v[168:171], v[112:127]
	v_mfma_f32_32x32x16_bf16 v[48:63], v[164:167], v[168:171], v[48:63]
	v_mfma_f32_32x32x16_bf16 v[96:111], v[160:163], v[172:175], v[96:111]
	v_mfma_f32_32x32x16_bf16 v[32:47], v[164:167], v[172:175], v[32:47]
	v_mfma_f32_32x32x16_bf16 v[80:95], v[160:163], v[176:179], v[80:95]
	v_mfma_f32_32x32x16_bf16 v[16:31], v[164:167], v[176:179], v[16:31]
	v_mfma_f32_32x32x16_bf16 v[64:79], v[160:163], v[180:183], v[64:79]
	v_mfma_f32_32x32x16_bf16 v[0:15], v[164:167], v[180:183], v[0:15]
	ds_read_b128 v[160:163], v186
	ds_read_b128 v[168:171], v190
	ds_read_b128 v[164:167], v186 offset:4096
	ds_read_b128 v[172:175], v190 offset:4096
	ds_read_b128 v[176:179], v190 offset:8192
	ds_read_b128 v[180:183], v190 offset:12288
	s_waitcnt lgkmcnt(6)
	v_mfma_f32_32x32x16_bf16 v[112:127], v[128:131], v[136:139], v[112:127]
	v_mfma_f32_32x32x16_bf16 v[48:63], v[132:135], v[136:139], v[48:63]
	v_mfma_f32_32x32x16_bf16 v[96:111], v[128:131], v[140:143], v[96:111]
	v_mfma_f32_32x32x16_bf16 v[32:47], v[132:135], v[140:143], v[32:47]
	v_mfma_f32_32x32x16_bf16 v[80:95], v[128:131], v[144:147], v[80:95]
	v_mfma_f32_32x32x16_bf16 v[16:31], v[132:135], v[144:147], v[16:31]
	v_mfma_f32_32x32x16_bf16 v[64:79], v[128:131], v[148:151], v[64:79]
	v_mfma_f32_32x32x16_bf16 v[0:15], v[132:135], v[148:151], v[0:15]
	ds_read_b128 v[128:131], v187
	ds_read_b128 v[136:139], v191
	ds_read_b128 v[132:135], v187 offset:4096
	ds_read_b128 v[140:143], v191 offset:4096
	ds_read_b128 v[144:147], v191 offset:8192
	ds_read_b128 v[148:151], v191 offset:12288
	s_waitcnt lgkmcnt(6)
	v_mfma_f32_32x32x16_bf16 v[112:127], v[160:163], v[168:171], v[112:127]
	v_mfma_f32_32x32x16_bf16 v[48:63], v[164:167], v[168:171], v[48:63]
	v_mfma_f32_32x32x16_bf16 v[96:111], v[160:163], v[172:175], v[96:111]
	v_mfma_f32_32x32x16_bf16 v[32:47], v[164:167], v[172:175], v[32:47]
	v_mfma_f32_32x32x16_bf16 v[80:95], v[160:163], v[176:179], v[80:95]
	v_mfma_f32_32x32x16_bf16 v[16:31], v[164:167], v[176:179], v[16:31]
	v_mfma_f32_32x32x16_bf16 v[64:79], v[160:163], v[180:183], v[64:79]
	v_mfma_f32_32x32x16_bf16 v[0:15], v[164:167], v[180:183], v[0:15]
	s_waitcnt vmcnt(0) lgkmcnt(0)
	s_barrier
	v_xor_b32_e32 v184, 0x10000, v184
	v_xor_b32_e32 v188, 0x10000, v188
	ds_read_b128 v[160:163], v184
	ds_read_b128 v[168:171], v188
	ds_read_b128 v[164:167], v184 offset:4096
	ds_read_b128 v[172:175], v188 offset:4096
	ds_read_b128 v[176:179], v188 offset:8192
	ds_read_b128 v[180:183], v188 offset:12288
	s_add_u32 s20, s16, 768
	s_addc_u32 s21, s17, 0
	s_add_u32 s24, s18, 768
	s_addc_u32 s25, s19, 0
	v_mfma_f32_32x32x16_bf16 v[112:127], v[128:131], v[136:139], v[112:127]
	v_xor_b32_e32 v185, 0x10000, v185
	v_xor_b32_e32 v189, 0x10000, v189
	s_add_u32 m0, s27, 0
	s_nop 0
	global_load_lds_dwordx4 v192, s[20:21]
	v_mfma_f32_32x32x16_bf16 v[48:63], v[132:135], v[136:139], v[48:63]
	v_xor_b32_e32 v186, 0x10000, v186
	v_xor_b32_e32 v190, 0x10000, v190
	s_add_u32 m0, s27, 32768
	s_nop 0
	global_load_lds_dwordx4 v192, s[24:25]
	v_mfma_f32_32x32x16_bf16 v[96:111], v[128:131], v[140:143], v[96:111]
	v_xor_b32_e32 v187, 0x10000, v187
	v_xor_b32_e32 v191, 0x10000, v191
	s_add_u32 m0, s27, 8192
	s_nop 0
	global_load_lds_dwordx4 v194, s[20:21]
	v_mfma_f32_32x32x16_bf16 v[32:47], v[132:135], v[140:143], v[32:47]
	s_add_u32 m0, s27, 40960
	s_nop 0
	global_load_lds_dwordx4 v194, s[24:25]
	v_mfma_f32_32x32x16_bf16 v[80:95], v[128:131], v[144:147], v[80:95]
	s_add_u32 m0, s27, 16384
	s_nop 0
	global_load_lds_dwordx4 v196, s[20:21]
	v_mfma_f32_32x32x16_bf16 v[16:31], v[132:135], v[144:147], v[16:31]
	s_add_u32 m0, s27, 49152
	s_nop 0
	global_load_lds_dwordx4 v196, s[24:25]
	v_mfma_f32_32x32x16_bf16 v[64:79], v[128:131], v[148:151], v[64:79]
	s_add_u32 m0, s27, 24576
	s_nop 0
	global_load_lds_dwordx4 v198, s[20:21]
	v_mfma_f32_32x32x16_bf16 v[0:15], v[132:135], v[148:151], v[0:15]
	s_add_u32 m0, s27, 57344
	s_nop 0
	global_load_lds_dwordx4 v198, s[24:25]
	ds_read_b128 v[128:131], v185
	ds_read_b128 v[136:139], v189
	ds_read_b128 v[132:135], v185 offset:4096
	ds_read_b128 v[140:143], v189 offset:4096
	ds_read_b128 v[144:147], v189 offset:8192
	ds_read_b128 v[148:151], v189 offset:12288
	s_waitcnt lgkmcnt(6)
	v_mfma_f32_32x32x16_bf16 v[112:127], v[160:163], v[168:171], v[112:127]
	v_mfma_f32_32x32x16_bf16 v[48:63], v[164:167], v[168:171], v[48:63]
	v_mfma_f32_32x32x16_bf16 v[96:111], v[160:163], v[172:175], v[96:111]
	v_mfma_f32_32x32x16_bf16 v[32:47], v[164:167], v[172:175], v[32:47]
	v_mfma_f32_32x32x16_bf16 v[80:95], v[160:163], v[176:179], v[80:95]
	v_mfma_f32_32x32x16_bf16 v[16:31], v[164:167], v[176:179], v[16:31]
	v_mfma_f32_32x32x16_bf16 v[64:79], v[160:163], v[180:183], v[64:79]
	v_mfma_f32_32x32x16_bf16 v[0:15], v[164:167], v[180:183], v[0:15]
	ds_read_b128 v[160:163], v186
	ds_read_b128 v[168:171], v190
	ds_read_b128 v[164:167], v186 offset:4096
	ds_read_b128 v[172:175], v190 offset:4096
	ds_read_b128 v[176:179], v190 offset:8192
	ds_read_b128 v[180:183], v190 offset:12288
	s_waitcnt lgkmcnt(6)
	v_mfma_f32_32x32x16_bf16 v[112:127], v[128:131], v[136:139], v[112:127]
	v_mfma_f32_32x32x16_bf16 v[48:63], v[132:135], v[136:139], v[48:63]
	v_mfma_f32_32x32x16_bf16 v[96:111], v[128:131], v[140:143], v[96:111]
	v_mfma_f32_32x32x16_bf16 v[32:47], v[132:135], v[140:143], v[32:47]
	v_mfma_f32_32x32x16_bf16 v[80:95], v[128:131], v[144:147], v[80:95]
	v_mfma_f32_32x32x16_bf16 v[16:31], v[132:135], v[144:147], v[16:31]
	v_mfma_f32_32x32x16_bf16 v[64:79], v[128:131], v[148:151], v[64:79]
	v_mfma_f32_32x32x16_bf16 v[0:15], v[132:135], v[148:151], v[0:15]
	ds_read_b128 v[128:131], v187
	ds_read_b128 v[136:139], v191
	ds_read_b128 v[132:135], v187 offset:4096
	ds_read_b128 v[140:143], v191 offset:4096
	ds_read_b128 v[144:147], v191 offset:8192
	ds_read_b128 v[148:151], v191 offset:12288
	s_waitcnt lgkmcnt(6)
	v_mfma_f32_32x32x16_bf16 v[112:127], v[160:163], v[168:171], v[112:127]
	v_mfma_f32_32x32x16_bf16 v[48:63], v[164:167], v[168:171], v[48:63]
	v_mfma_f32_32x32x16_bf16 v[96:111], v[160:163], v[172:175], v[96:111]
	v_mfma_f32_32x32x16_bf16 v[32:47], v[164:167], v[172:175], v[32:47]
	v_mfma_f32_32x32x16_bf16 v[80:95], v[160:163], v[176:179], v[80:95]
	v_mfma_f32_32x32x16_bf16 v[16:31], v[164:167], v[176:179], v[16:31]
	v_mfma_f32_32x32x16_bf16 v[64:79], v[160:163], v[180:183], v[64:79]
	v_mfma_f32_32x32x16_bf16 v[0:15], v[164:167], v[180:183], v[0:15]
	s_waitcnt vmcnt(0) lgkmcnt(0)
	s_barrier
	v_xor_b32_e32 v184, 0x10000, v184
	v_xor_b32_e32 v188, 0x10000, v188
	ds_read_b128 v[160:163], v184
	ds_read_b128 v[168:171], v188
	ds_read_b128 v[164:167], v184 offset:4096
	ds_read_b128 v[172:175], v188 offset:4096
	ds_read_b128 v[176:179], v188 offset:8192
	ds_read_b128 v[180:183], v188 offset:12288
	s_add_u32 s20, s16, 896
	s_addc_u32 s21, s17, 0
	s_add_u32 s24, s18, 896
	s_addc_u32 s25, s19, 0
	v_mfma_f32_32x32x16_bf16 v[112:127], v[128:131], v[136:139], v[112:127]
	v_xor_b32_e32 v185, 0x10000, v185
	v_xor_b32_e32 v189, 0x10000, v189
	s_add_u32 m0, s27, 65536
	s_nop 0
	global_load_lds_dwordx4 v192, s[20:21]
	v_mfma_f32_32x32x16_bf16 v[48:63], v[132:135], v[136:139], v[48:63]
	v_xor_b32_e32 v186, 0x10000, v186
	v_xor_b32_e32 v190, 0x10000, v190
	s_add_u32 m0, s27, 98304
	s_nop 0
	global_load_lds_dwordx4 v192, s[24:25]
	v_mfma_f32_32x32x16_bf16 v[96:111], v[128:131], v[140:143], v[96:111]
	v_xor_b32_e32 v187, 0x10000, v187
	v_xor_b32_e32 v191, 0x10000, v191
	s_add_u32 m0, s27, 73728
	s_nop 0
	global_load_lds_dwordx4 v194, s[20:21]
	v_mfma_f32_32x32x16_bf16 v[32:47], v[132:135], v[140:143], v[32:47]
	s_add_u32 m0, s27, 106496
	s_nop 0
	global_load_lds_dwordx4 v194, s[24:25]
	v_mfma_f32_32x32x16_bf16 v[80:95], v[128:131], v[144:147], v[80:95]
	s_add_u32 m0, s27, 81920
	s_nop 0
	global_load_lds_dwordx4 v196, s[20:21]
	v_mfma_f32_32x32x16_bf16 v[16:31], v[132:135], v[144:147], v[16:31]
	s_add_u32 m0, s27, 114688
	s_nop 0
	global_load_lds_dwordx4 v196, s[24:25]
	v_mfma_f32_32x32x16_bf16 v[64:79], v[128:131], v[148:151], v[64:79]
	s_add_u32 m0, s27, 90112
	s_nop 0
	global_load_lds_dwordx4 v198, s[20:21]
	v_mfma_f32_32x32x16_bf16 v[0:15], v[132:135], v[148:151], v[0:15]
	s_add_u32 m0, s27, 122880
	s_nop 0
	global_load_lds_dwordx4 v198, s[24:25]
	ds_read_b128 v[128:131], v185
	ds_read_b128 v[136:139], v189
	ds_read_b128 v[132:135], v185 offset:4096
	ds_read_b128 v[140:143], v189 offset:4096
	ds_read_b128 v[144:147], v189 offset:8192
	ds_read_b128 v[148:151], v189 offset:12288
	s_waitcnt lgkmcnt(6)
	v_mfma_f32_32x32x16_bf16 v[112:127], v[160:163], v[168:171], v[112:127]
	v_mfma_f32_32x32x16_bf16 v[48:63], v[164:167], v[168:171], v[48:63]
	v_mfma_f32_32x32x16_bf16 v[96:111], v[160:163], v[172:175], v[96:111]
	v_mfma_f32_32x32x16_bf16 v[32:47], v[164:167], v[172:175], v[32:47]
	v_mfma_f32_32x32x16_bf16 v[80:95], v[160:163], v[176:179], v[80:95]
	v_mfma_f32_32x32x16_bf16 v[16:31], v[164:167], v[176:179], v[16:31]
	v_mfma_f32_32x32x16_bf16 v[64:79], v[160:163], v[180:183], v[64:79]
	v_mfma_f32_32x32x16_bf16 v[0:15], v[164:167], v[180:183], v[0:15]
	ds_read_b128 v[160:163], v186
	ds_read_b128 v[168:171], v190
	ds_read_b128 v[164:167], v186 offset:4096
	ds_read_b128 v[172:175], v190 offset:4096
	ds_read_b128 v[176:179], v190 offset:8192
	ds_read_b128 v[180:183], v190 offset:12288
	s_waitcnt lgkmcnt(6)
	v_mfma_f32_32x32x16_bf16 v[112:127], v[128:131], v[136:139], v[112:127]
	v_mfma_f32_32x32x16_bf16 v[48:63], v[132:135], v[136:139], v[48:63]
	v_mfma_f32_32x32x16_bf16 v[96:111], v[128:131], v[140:143], v[96:111]
	v_mfma_f32_32x32x16_bf16 v[32:47], v[132:135], v[140:143], v[32:47]
	v_mfma_f32_32x32x16_bf16 v[80:95], v[128:131], v[144:147], v[80:95]
	v_mfma_f32_32x32x16_bf16 v[16:31], v[132:135], v[144:147], v[16:31]
	v_mfma_f32_32x32x16_bf16 v[64:79], v[128:131], v[148:151], v[64:79]
	v_mfma_f32_32x32x16_bf16 v[0:15], v[132:135], v[148:151], v[0:15]
	ds_read_b128 v[128:131], v187
	ds_read_b128 v[136:139], v191
	ds_read_b128 v[132:135], v187 offset:4096
	ds_read_b128 v[140:143], v191 offset:4096
	ds_read_b128 v[144:147], v191 offset:8192
	ds_read_b128 v[148:151], v191 offset:12288
	s_waitcnt lgkmcnt(6)
	v_mfma_f32_32x32x16_bf16 v[112:127], v[160:163], v[168:171], v[112:127]
	v_mfma_f32_32x32x16_bf16 v[48:63], v[164:167], v[168:171], v[48:63]
	v_mfma_f32_32x32x16_bf16 v[96:111], v[160:163], v[172:175], v[96:111]
	v_mfma_f32_32x32x16_bf16 v[32:47], v[164:167], v[172:175], v[32:47]
	v_mfma_f32_32x32x16_bf16 v[80:95], v[160:163], v[176:179], v[80:95]
	v_mfma_f32_32x32x16_bf16 v[16:31], v[164:167], v[176:179], v[16:31]
	v_mfma_f32_32x32x16_bf16 v[64:79], v[160:163], v[180:183], v[64:79]
	v_mfma_f32_32x32x16_bf16 v[0:15], v[164:167], v[180:183], v[0:15]
	s_waitcnt vmcnt(0) lgkmcnt(0)
	s_barrier
	v_xor_b32_e32 v184, 0x10000, v184
	v_xor_b32_e32 v188, 0x10000, v188
	ds_read_b128 v[160:163], v184
	ds_read_b128 v[168:171], v188
	ds_read_b128 v[164:167], v184 offset:4096
	ds_read_b128 v[172:175], v188 offset:4096
	ds_read_b128 v[176:179], v188 offset:8192
	ds_read_b128 v[180:183], v188 offset:12288
	s_add_u32 s20, s16, 1024
	s_addc_u32 s21, s17, 0
	s_add_u32 s24, s18, 1024
	s_addc_u32 s25, s19, 0
	v_mfma_f32_32x32x16_bf16 v[112:127], v[128:131], v[136:139], v[112:127]
	v_xor_b32_e32 v185, 0x10000, v185
	v_xor_b32_e32 v189, 0x10000, v189
	s_add_u32 m0, s27, 0
	s_nop 0
	global_load_lds_dwordx4 v192, s[20:21]
	v_mfma_f32_32x32x16_bf16 v[48:63], v[132:135], v[136:139], v[48:63]
	v_xor_b32_e32 v186, 0x10000, v186
	v_xor_b32_e32 v190, 0x10000, v190
	s_add_u32 m0, s27, 32768
	s_nop 0
	global_load_lds_dwordx4 v192, s[24:25]
	v_mfma_f32_32x32x16_bf16 v[96:111], v[128:131], v[140:143], v[96:111]
	v_xor_b32_e32 v187, 0x10000, v187
	v_xor_b32_e32 v191, 0x10000, v191
	s_add_u32 m0, s27, 8192
	s_nop 0
	global_load_lds_dwordx4 v194, s[20:21]
	v_mfma_f32_32x32x16_bf16 v[32:47], v[132:135], v[140:143], v[32:47]
	s_add_u32 m0, s27, 40960
	s_nop 0
	global_load_lds_dwordx4 v194, s[24:25]
	v_mfma_f32_32x32x16_bf16 v[80:95], v[128:131], v[144:147], v[80:95]
	s_add_u32 m0, s27, 16384
	s_nop 0
	global_load_lds_dwordx4 v196, s[20:21]
	v_mfma_f32_32x32x16_bf16 v[16:31], v[132:135], v[144:147], v[16:31]
	s_add_u32 m0, s27, 49152
	s_nop 0
	global_load_lds_dwordx4 v196, s[24:25]
	v_mfma_f32_32x32x16_bf16 v[64:79], v[128:131], v[148:151], v[64:79]
	s_add_u32 m0, s27, 24576
	s_nop 0
	global_load_lds_dwordx4 v198, s[20:21]
	v_mfma_f32_32x32x16_bf16 v[0:15], v[132:135], v[148:151], v[0:15]
	s_add_u32 m0, s27, 57344
	s_nop 0
	global_load_lds_dwordx4 v198, s[24:25]
	ds_read_b128 v[128:131], v185
	ds_read_b128 v[136:139], v189
	ds_read_b128 v[132:135], v185 offset:4096
	ds_read_b128 v[140:143], v189 offset:4096
	ds_read_b128 v[144:147], v189 offset:8192
	ds_read_b128 v[148:151], v189 offset:12288
	s_waitcnt lgkmcnt(6)
	v_mfma_f32_32x32x16_bf16 v[112:127], v[160:163], v[168:171], v[112:127]
	v_mfma_f32_32x32x16_bf16 v[48:63], v[164:167], v[168:171], v[48:63]
	v_mfma_f32_32x32x16_bf16 v[96:111], v[160:163], v[172:175], v[96:111]
	v_mfma_f32_32x32x16_bf16 v[32:47], v[164:167], v[172:175], v[32:47]
	v_mfma_f32_32x32x16_bf16 v[80:95], v[160:163], v[176:179], v[80:95]
	v_mfma_f32_32x32x16_bf16 v[16:31], v[164:167], v[176:179], v[16:31]
	v_mfma_f32_32x32x16_bf16 v[64:79], v[160:163], v[180:183], v[64:79]
	v_mfma_f32_32x32x16_bf16 v[0:15], v[164:167], v[180:183], v[0:15]
	ds_read_b128 v[160:163], v186
	ds_read_b128 v[168:171], v190
	ds_read_b128 v[164:167], v186 offset:4096
	ds_read_b128 v[172:175], v190 offset:4096
	ds_read_b128 v[176:179], v190 offset:8192
	ds_read_b128 v[180:183], v190 offset:12288
	s_waitcnt lgkmcnt(6)
	v_mfma_f32_32x32x16_bf16 v[112:127], v[128:131], v[136:139], v[112:127]
	v_mfma_f32_32x32x16_bf16 v[48:63], v[132:135], v[136:139], v[48:63]
	v_mfma_f32_32x32x16_bf16 v[96:111], v[128:131], v[140:143], v[96:111]
	v_mfma_f32_32x32x16_bf16 v[32:47], v[132:135], v[140:143], v[32:47]
	v_mfma_f32_32x32x16_bf16 v[80:95], v[128:131], v[144:147], v[80:95]
	v_mfma_f32_32x32x16_bf16 v[16:31], v[132:135], v[144:147], v[16:31]
	v_mfma_f32_32x32x16_bf16 v[64:79], v[128:131], v[148:151], v[64:79]
	v_mfma_f32_32x32x16_bf16 v[0:15], v[132:135], v[148:151], v[0:15]
	ds_read_b128 v[128:131], v187
	ds_read_b128 v[136:139], v191
	ds_read_b128 v[132:135], v187 offset:4096
	ds_read_b128 v[140:143], v191 offset:4096
	ds_read_b128 v[144:147], v191 offset:8192
	ds_read_b128 v[148:151], v191 offset:12288
	s_waitcnt lgkmcnt(6)
	v_mfma_f32_32x32x16_bf16 v[112:127], v[160:163], v[168:171], v[112:127]
	v_mfma_f32_32x32x16_bf16 v[48:63], v[164:167], v[168:171], v[48:63]
	v_mfma_f32_32x32x16_bf16 v[96:111], v[160:163], v[172:175], v[96:111]
	v_mfma_f32_32x32x16_bf16 v[32:47], v[164:167], v[172:175], v[32:47]
	v_mfma_f32_32x32x16_bf16 v[80:95], v[160:163], v[176:179], v[80:95]
	v_mfma_f32_32x32x16_bf16 v[16:31], v[164:167], v[176:179], v[16:31]
	v_mfma_f32_32x32x16_bf16 v[64:79], v[160:163], v[180:183], v[64:79]
	v_mfma_f32_32x32x16_bf16 v[0:15], v[164:167], v[180:183], v[0:15]
	s_waitcnt vmcnt(0) lgkmcnt(0)
	s_barrier
	v_xor_b32_e32 v184, 0x10000, v184
	v_xor_b32_e32 v188, 0x10000, v188
	ds_read_b128 v[160:163], v184
	ds_read_b128 v[168:171], v188
	ds_read_b128 v[164:167], v184 offset:4096
	ds_read_b128 v[172:175], v188 offset:4096
	ds_read_b128 v[176:179], v188 offset:8192
	ds_read_b128 v[180:183], v188 offset:12288
	s_add_u32 s20, s16, 1152
	s_addc_u32 s21, s17, 0
	s_add_u32 s24, s18, 1152
	s_addc_u32 s25, s19, 0
	v_mfma_f32_32x32x16_bf16 v[112:127], v[128:131], v[136:139], v[112:127]
	v_xor_b32_e32 v185, 0x10000, v185
	v_xor_b32_e32 v189, 0x10000, v189
	s_add_u32 m0, s27, 65536
	s_nop 0
	global_load_lds_dwordx4 v192, s[20:21]
	v_mfma_f32_32x32x16_bf16 v[48:63], v[132:135], v[136:139], v[48:63]
	v_xor_b32_e32 v186, 0x10000, v186
	v_xor_b32_e32 v190, 0x10000, v190
	s_add_u32 m0, s27, 98304
	s_nop 0
	global_load_lds_dwordx4 v192, s[24:25]
	v_mfma_f32_32x32x16_bf16 v[96:111], v[128:131], v[140:143], v[96:111]
	v_xor_b32_e32 v187, 0x10000, v187
	v_xor_b32_e32 v191, 0x10000, v191
	s_add_u32 m0, s27, 73728
	s_nop 0
	global_load_lds_dwordx4 v194, s[20:21]
	v_mfma_f32_32x32x16_bf16 v[32:47], v[132:135], v[140:143], v[32:47]
	s_add_u32 m0, s27, 106496
	s_nop 0
	global_load_lds_dwordx4 v194, s[24:25]
	v_mfma_f32_32x32x16_bf16 v[80:95], v[128:131], v[144:147], v[80:95]
	s_add_u32 m0, s27, 81920
	s_nop 0
	global_load_lds_dwordx4 v196, s[20:21]
	v_mfma_f32_32x32x16_bf16 v[16:31], v[132:135], v[144:147], v[16:31]
	s_add_u32 m0, s27, 114688
	s_nop 0
	global_load_lds_dwordx4 v196, s[24:25]
	v_mfma_f32_32x32x16_bf16 v[64:79], v[128:131], v[148:151], v[64:79]
	s_add_u32 m0, s27, 90112
	s_nop 0
	global_load_lds_dwordx4 v198, s[20:21]
	v_mfma_f32_32x32x16_bf16 v[0:15], v[132:135], v[148:151], v[0:15]
	s_add_u32 m0, s27, 122880
	s_nop 0
	global_load_lds_dwordx4 v198, s[24:25]
	ds_read_b128 v[128:131], v185
	ds_read_b128 v[136:139], v189
	ds_read_b128 v[132:135], v185 offset:4096
	ds_read_b128 v[140:143], v189 offset:4096
	ds_read_b128 v[144:147], v189 offset:8192
	ds_read_b128 v[148:151], v189 offset:12288
	s_waitcnt lgkmcnt(6)
	v_mfma_f32_32x32x16_bf16 v[112:127], v[160:163], v[168:171], v[112:127]
	v_mfma_f32_32x32x16_bf16 v[48:63], v[164:167], v[168:171], v[48:63]
	v_mfma_f32_32x32x16_bf16 v[96:111], v[160:163], v[172:175], v[96:111]
	v_mfma_f32_32x32x16_bf16 v[32:47], v[164:167], v[172:175], v[32:47]
	v_mfma_f32_32x32x16_bf16 v[80:95], v[160:163], v[176:179], v[80:95]
	v_mfma_f32_32x32x16_bf16 v[16:31], v[164:167], v[176:179], v[16:31]
	v_mfma_f32_32x32x16_bf16 v[64:79], v[160:163], v[180:183], v[64:79]
	v_mfma_f32_32x32x16_bf16 v[0:15], v[164:167], v[180:183], v[0:15]
	ds_read_b128 v[160:163], v186
	ds_read_b128 v[168:171], v190
	ds_read_b128 v[164:167], v186 offset:4096
	ds_read_b128 v[172:175], v190 offset:4096
	ds_read_b128 v[176:179], v190 offset:8192
	ds_read_b128 v[180:183], v190 offset:12288
	s_waitcnt lgkmcnt(6)
	v_mfma_f32_32x32x16_bf16 v[112:127], v[128:131], v[136:139], v[112:127]
	v_mfma_f32_32x32x16_bf16 v[48:63], v[132:135], v[136:139], v[48:63]
	v_mfma_f32_32x32x16_bf16 v[96:111], v[128:131], v[140:143], v[96:111]
	v_mfma_f32_32x32x16_bf16 v[32:47], v[132:135], v[140:143], v[32:47]
	v_mfma_f32_32x32x16_bf16 v[80:95], v[128:131], v[144:147], v[80:95]
	v_mfma_f32_32x32x16_bf16 v[16:31], v[132:135], v[144:147], v[16:31]
	v_mfma_f32_32x32x16_bf16 v[64:79], v[128:131], v[148:151], v[64:79]
	v_mfma_f32_32x32x16_bf16 v[0:15], v[132:135], v[148:151], v[0:15]
	ds_read_b128 v[128:131], v187
	ds_read_b128 v[136:139], v191
	ds_read_b128 v[132:135], v187 offset:4096
	ds_read_b128 v[140:143], v191 offset:4096
	ds_read_b128 v[144:147], v191 offset:8192
	ds_read_b128 v[148:151], v191 offset:12288
	s_waitcnt lgkmcnt(6)
	v_mfma_f32_32x32x16_bf16 v[112:127], v[160:163], v[168:171], v[112:127]
	v_mfma_f32_32x32x16_bf16 v[48:63], v[164:167], v[168:171], v[48:63]
	v_mfma_f32_32x32x16_bf16 v[96:111], v[160:163], v[172:175], v[96:111]
	v_mfma_f32_32x32x16_bf16 v[32:47], v[164:167], v[172:175], v[32:47]
	v_mfma_f32_32x32x16_bf16 v[80:95], v[160:163], v[176:179], v[80:95]
	v_mfma_f32_32x32x16_bf16 v[16:31], v[164:167], v[176:179], v[16:31]
	v_mfma_f32_32x32x16_bf16 v[64:79], v[160:163], v[180:183], v[64:79]
	v_mfma_f32_32x32x16_bf16 v[0:15], v[164:167], v[180:183], v[0:15]
	s_waitcnt vmcnt(0) lgkmcnt(0)
	s_barrier
	v_xor_b32_e32 v184, 0x10000, v184
	v_xor_b32_e32 v188, 0x10000, v188
	ds_read_b128 v[160:163], v184
	ds_read_b128 v[168:171], v188
	ds_read_b128 v[164:167], v184 offset:4096
	ds_read_b128 v[172:175], v188 offset:4096
	ds_read_b128 v[176:179], v188 offset:8192
	ds_read_b128 v[180:183], v188 offset:12288
	s_add_u32 s20, s16, 1280
	s_addc_u32 s21, s17, 0
	s_add_u32 s24, s18, 1280
	s_addc_u32 s25, s19, 0
	v_mfma_f32_32x32x16_bf16 v[112:127], v[128:131], v[136:139], v[112:127]
	v_xor_b32_e32 v185, 0x10000, v185
	v_xor_b32_e32 v189, 0x10000, v189
	s_add_u32 m0, s27, 0
	s_nop 0
	global_load_lds_dwordx4 v192, s[20:21]
	v_mfma_f32_32x32x16_bf16 v[48:63], v[132:135], v[136:139], v[48:63]
	v_xor_b32_e32 v186, 0x10000, v186
	v_xor_b32_e32 v190, 0x10000, v190
	s_add_u32 m0, s27, 32768
	s_nop 0
	global_load_lds_dwordx4 v192, s[24:25]
	v_mfma_f32_32x32x16_bf16 v[96:111], v[128:131], v[140:143], v[96:111]
	v_xor_b32_e32 v187, 0x10000, v187
	v_xor_b32_e32 v191, 0x10000, v191
	s_add_u32 m0, s27, 8192
	s_nop 0
	global_load_lds_dwordx4 v194, s[20:21]
	v_mfma_f32_32x32x16_bf16 v[32:47], v[132:135], v[140:143], v[32:47]
	s_add_u32 m0, s27, 40960
	s_nop 0
	global_load_lds_dwordx4 v194, s[24:25]
	v_mfma_f32_32x32x16_bf16 v[80:95], v[128:131], v[144:147], v[80:95]
	s_add_u32 m0, s27, 16384
	s_nop 0
	global_load_lds_dwordx4 v196, s[20:21]
	v_mfma_f32_32x32x16_bf16 v[16:31], v[132:135], v[144:147], v[16:31]
	s_add_u32 m0, s27, 49152
	s_nop 0
	global_load_lds_dwordx4 v196, s[24:25]
	v_mfma_f32_32x32x16_bf16 v[64:79], v[128:131], v[148:151], v[64:79]
	s_add_u32 m0, s27, 24576
	s_nop 0
	global_load_lds_dwordx4 v198, s[20:21]
	v_mfma_f32_32x32x16_bf16 v[0:15], v[132:135], v[148:151], v[0:15]
	s_add_u32 m0, s27, 57344
	s_nop 0
	global_load_lds_dwordx4 v198, s[24:25]
	ds_read_b128 v[128:131], v185
	ds_read_b128 v[136:139], v189
	ds_read_b128 v[132:135], v185 offset:4096
	ds_read_b128 v[140:143], v189 offset:4096
	ds_read_b128 v[144:147], v189 offset:8192
	ds_read_b128 v[148:151], v189 offset:12288
	s_waitcnt lgkmcnt(6)
	v_mfma_f32_32x32x16_bf16 v[112:127], v[160:163], v[168:171], v[112:127]
	v_mfma_f32_32x32x16_bf16 v[48:63], v[164:167], v[168:171], v[48:63]
	v_mfma_f32_32x32x16_bf16 v[96:111], v[160:163], v[172:175], v[96:111]
	v_mfma_f32_32x32x16_bf16 v[32:47], v[164:167], v[172:175], v[32:47]
	v_mfma_f32_32x32x16_bf16 v[80:95], v[160:163], v[176:179], v[80:95]
	v_mfma_f32_32x32x16_bf16 v[16:31], v[164:167], v[176:179], v[16:31]
	v_mfma_f32_32x32x16_bf16 v[64:79], v[160:163], v[180:183], v[64:79]
	v_mfma_f32_32x32x16_bf16 v[0:15], v[164:167], v[180:183], v[0:15]
	ds_read_b128 v[160:163], v186
	ds_read_b128 v[168:171], v190
	ds_read_b128 v[164:167], v186 offset:4096
	ds_read_b128 v[172:175], v190 offset:4096
	ds_read_b128 v[176:179], v190 offset:8192
	ds_read_b128 v[180:183], v190 offset:12288
	s_waitcnt lgkmcnt(6)
	v_mfma_f32_32x32x16_bf16 v[112:127], v[128:131], v[136:139], v[112:127]
	v_mfma_f32_32x32x16_bf16 v[48:63], v[132:135], v[136:139], v[48:63]
	v_mfma_f32_32x32x16_bf16 v[96:111], v[128:131], v[140:143], v[96:111]
	v_mfma_f32_32x32x16_bf16 v[32:47], v[132:135], v[140:143], v[32:47]
	v_mfma_f32_32x32x16_bf16 v[80:95], v[128:131], v[144:147], v[80:95]
	v_mfma_f32_32x32x16_bf16 v[16:31], v[132:135], v[144:147], v[16:31]
	v_mfma_f32_32x32x16_bf16 v[64:79], v[128:131], v[148:151], v[64:79]
	v_mfma_f32_32x32x16_bf16 v[0:15], v[132:135], v[148:151], v[0:15]
	ds_read_b128 v[128:131], v187
	ds_read_b128 v[136:139], v191
	ds_read_b128 v[132:135], v187 offset:4096
	ds_read_b128 v[140:143], v191 offset:4096
	ds_read_b128 v[144:147], v191 offset:8192
	ds_read_b128 v[148:151], v191 offset:12288
	s_waitcnt lgkmcnt(6)
	v_mfma_f32_32x32x16_bf16 v[112:127], v[160:163], v[168:171], v[112:127]
	v_mfma_f32_32x32x16_bf16 v[48:63], v[164:167], v[168:171], v[48:63]
	v_mfma_f32_32x32x16_bf16 v[96:111], v[160:163], v[172:175], v[96:111]
	v_mfma_f32_32x32x16_bf16 v[32:47], v[164:167], v[172:175], v[32:47]
	v_mfma_f32_32x32x16_bf16 v[80:95], v[160:163], v[176:179], v[80:95]
	v_mfma_f32_32x32x16_bf16 v[16:31], v[164:167], v[176:179], v[16:31]
	v_mfma_f32_32x32x16_bf16 v[64:79], v[160:163], v[180:183], v[64:79]
	v_mfma_f32_32x32x16_bf16 v[0:15], v[164:167], v[180:183], v[0:15]
	s_waitcnt vmcnt(0) lgkmcnt(0)
	s_barrier
	v_xor_b32_e32 v184, 0x10000, v184
	v_xor_b32_e32 v188, 0x10000, v188
	ds_read_b128 v[160:163], v184
	ds_read_b128 v[168:171], v188
	ds_read_b128 v[164:167], v184 offset:4096
	ds_read_b128 v[172:175], v188 offset:4096
	ds_read_b128 v[176:179], v188 offset:8192
	ds_read_b128 v[180:183], v188 offset:12288
	s_add_u32 s20, s16, 1408
	s_addc_u32 s21, s17, 0
	s_add_u32 s24, s18, 1408
	s_addc_u32 s25, s19, 0
	v_mfma_f32_32x32x16_bf16 v[112:127], v[128:131], v[136:139], v[112:127]
	v_xor_b32_e32 v185, 0x10000, v185
	v_xor_b32_e32 v189, 0x10000, v189
	s_add_u32 m0, s27, 65536
	s_nop 0
	global_load_lds_dwordx4 v192, s[20:21]
	v_mfma_f32_32x32x16_bf16 v[48:63], v[132:135], v[136:139], v[48:63]
	v_xor_b32_e32 v186, 0x10000, v186
	v_xor_b32_e32 v190, 0x10000, v190
	s_add_u32 m0, s27, 98304
	s_nop 0
	global_load_lds_dwordx4 v192, s[24:25]
	v_mfma_f32_32x32x16_bf16 v[96:111], v[128:131], v[140:143], v[96:111]
	v_xor_b32_e32 v187, 0x10000, v187
	v_xor_b32_e32 v191, 0x10000, v191
	s_add_u32 m0, s27, 73728
	s_nop 0
	global_load_lds_dwordx4 v194, s[20:21]
	v_mfma_f32_32x32x16_bf16 v[32:47], v[132:135], v[140:143], v[32:47]
	s_add_u32 m0, s27, 106496
	s_nop 0
	global_load_lds_dwordx4 v194, s[24:25]
	v_mfma_f32_32x32x16_bf16 v[80:95], v[128:131], v[144:147], v[80:95]
	s_add_u32 m0, s27, 81920
	s_nop 0
	global_load_lds_dwordx4 v196, s[20:21]
	v_mfma_f32_32x32x16_bf16 v[16:31], v[132:135], v[144:147], v[16:31]
	s_add_u32 m0, s27, 114688
	s_nop 0
	global_load_lds_dwordx4 v196, s[24:25]
	v_mfma_f32_32x32x16_bf16 v[64:79], v[128:131], v[148:151], v[64:79]
	s_add_u32 m0, s27, 90112
	s_nop 0
	global_load_lds_dwordx4 v198, s[20:21]
	v_mfma_f32_32x32x16_bf16 v[0:15], v[132:135], v[148:151], v[0:15]
	s_add_u32 m0, s27, 122880
	s_nop 0
	global_load_lds_dwordx4 v198, s[24:25]
	ds_read_b128 v[128:131], v185
	ds_read_b128 v[136:139], v189
	ds_read_b128 v[132:135], v185 offset:4096
	ds_read_b128 v[140:143], v189 offset:4096
	ds_read_b128 v[144:147], v189 offset:8192
	ds_read_b128 v[148:151], v189 offset:12288
	s_waitcnt lgkmcnt(6)
	v_mfma_f32_32x32x16_bf16 v[112:127], v[160:163], v[168:171], v[112:127]
	v_mfma_f32_32x32x16_bf16 v[48:63], v[164:167], v[168:171], v[48:63]
	v_mfma_f32_32x32x16_bf16 v[96:111], v[160:163], v[172:175], v[96:111]
	v_mfma_f32_32x32x16_bf16 v[32:47], v[164:167], v[172:175], v[32:47]
	v_mfma_f32_32x32x16_bf16 v[80:95], v[160:163], v[176:179], v[80:95]
	v_mfma_f32_32x32x16_bf16 v[16:31], v[164:167], v[176:179], v[16:31]
	v_mfma_f32_32x32x16_bf16 v[64:79], v[160:163], v[180:183], v[64:79]
	v_mfma_f32_32x32x16_bf16 v[0:15], v[164:167], v[180:183], v[0:15]
	ds_read_b128 v[160:163], v186
	ds_read_b128 v[168:171], v190
	ds_read_b128 v[164:167], v186 offset:4096
	ds_read_b128 v[172:175], v190 offset:4096
	ds_read_b128 v[176:179], v190 offset:8192
	ds_read_b128 v[180:183], v190 offset:12288
	s_waitcnt lgkmcnt(6)
	v_mfma_f32_32x32x16_bf16 v[112:127], v[128:131], v[136:139], v[112:127]
	v_mfma_f32_32x32x16_bf16 v[48:63], v[132:135], v[136:139], v[48:63]
	v_mfma_f32_32x32x16_bf16 v[96:111], v[128:131], v[140:143], v[96:111]
	v_mfma_f32_32x32x16_bf16 v[32:47], v[132:135], v[140:143], v[32:47]
	v_mfma_f32_32x32x16_bf16 v[80:95], v[128:131], v[144:147], v[80:95]
	v_mfma_f32_32x32x16_bf16 v[16:31], v[132:135], v[144:147], v[16:31]
	v_mfma_f32_32x32x16_bf16 v[64:79], v[128:131], v[148:151], v[64:79]
	v_mfma_f32_32x32x16_bf16 v[0:15], v[132:135], v[148:151], v[0:15]
	ds_read_b128 v[128:131], v187
	ds_read_b128 v[136:139], v191
	ds_read_b128 v[132:135], v187 offset:4096
	ds_read_b128 v[140:143], v191 offset:4096
	ds_read_b128 v[144:147], v191 offset:8192
	ds_read_b128 v[148:151], v191 offset:12288
	s_waitcnt lgkmcnt(6)
	v_mfma_f32_32x32x16_bf16 v[112:127], v[160:163], v[168:171], v[112:127]
	v_mfma_f32_32x32x16_bf16 v[48:63], v[164:167], v[168:171], v[48:63]
	v_mfma_f32_32x32x16_bf16 v[96:111], v[160:163], v[172:175], v[96:111]
	v_mfma_f32_32x32x16_bf16 v[32:47], v[164:167], v[172:175], v[32:47]
	v_mfma_f32_32x32x16_bf16 v[80:95], v[160:163], v[176:179], v[80:95]
	v_mfma_f32_32x32x16_bf16 v[16:31], v[164:167], v[176:179], v[16:31]
	v_mfma_f32_32x32x16_bf16 v[64:79], v[160:163], v[180:183], v[64:79]
	v_mfma_f32_32x32x16_bf16 v[0:15], v[164:167], v[180:183], v[0:15]
	s_waitcnt vmcnt(0) lgkmcnt(0)
	s_barrier
	v_xor_b32_e32 v184, 0x10000, v184
	v_xor_b32_e32 v188, 0x10000, v188
	ds_read_b128 v[160:163], v184
	ds_read_b128 v[168:171], v188
	ds_read_b128 v[164:167], v184 offset:4096
	ds_read_b128 v[172:175], v188 offset:4096
	ds_read_b128 v[176:179], v188 offset:8192
	ds_read_b128 v[180:183], v188 offset:12288
	s_add_u32 s20, s16, 1536
	s_addc_u32 s21, s17, 0
	s_add_u32 s24, s18, 1536
	s_addc_u32 s25, s19, 0
	v_mfma_f32_32x32x16_bf16 v[112:127], v[128:131], v[136:139], v[112:127]
	v_xor_b32_e32 v185, 0x10000, v185
	v_xor_b32_e32 v189, 0x10000, v189
	s_add_u32 m0, s27, 0
	s_nop 0
	global_load_lds_dwordx4 v192, s[20:21]
	v_mfma_f32_32x32x16_bf16 v[48:63], v[132:135], v[136:139], v[48:63]
	v_xor_b32_e32 v186, 0x10000, v186
	v_xor_b32_e32 v190, 0x10000, v190
	s_add_u32 m0, s27, 32768
	s_nop 0
	global_load_lds_dwordx4 v192, s[24:25]
	v_mfma_f32_32x32x16_bf16 v[96:111], v[128:131], v[140:143], v[96:111]
	v_xor_b32_e32 v187, 0x10000, v187
	v_xor_b32_e32 v191, 0x10000, v191
	s_add_u32 m0, s27, 8192
	s_nop 0
	global_load_lds_dwordx4 v194, s[20:21]
	v_mfma_f32_32x32x16_bf16 v[32:47], v[132:135], v[140:143], v[32:47]
	s_add_u32 m0, s27, 40960
	s_nop 0
	global_load_lds_dwordx4 v194, s[24:25]
	v_mfma_f32_32x32x16_bf16 v[80:95], v[128:131], v[144:147], v[80:95]
	s_add_u32 m0, s27, 16384
	s_nop 0
	global_load_lds_dwordx4 v196, s[20:21]
	v_mfma_f32_32x32x16_bf16 v[16:31], v[132:135], v[144:147], v[16:31]
	s_add_u32 m0, s27, 49152
	s_nop 0
	global_load_lds_dwordx4 v196, s[24:25]
	v_mfma_f32_32x32x16_bf16 v[64:79], v[128:131], v[148:151], v[64:79]
	s_add_u32 m0, s27, 24576
	s_nop 0
	global_load_lds_dwordx4 v198, s[20:21]
	v_mfma_f32_32x32x16_bf16 v[0:15], v[132:135], v[148:151], v[0:15]
	s_add_u32 m0, s27, 57344
	s_nop 0
	global_load_lds_dwordx4 v198, s[24:25]
	ds_read_b128 v[128:131], v185
	ds_read_b128 v[136:139], v189
	ds_read_b128 v[132:135], v185 offset:4096
	ds_read_b128 v[140:143], v189 offset:4096
	ds_read_b128 v[144:147], v189 offset:8192
	ds_read_b128 v[148:151], v189 offset:12288
	s_waitcnt lgkmcnt(6)
	v_mfma_f32_32x32x16_bf16 v[112:127], v[160:163], v[168:171], v[112:127]
	v_mfma_f32_32x32x16_bf16 v[48:63], v[164:167], v[168:171], v[48:63]
	v_mfma_f32_32x32x16_bf16 v[96:111], v[160:163], v[172:175], v[96:111]
	v_mfma_f32_32x32x16_bf16 v[32:47], v[164:167], v[172:175], v[32:47]
	v_mfma_f32_32x32x16_bf16 v[80:95], v[160:163], v[176:179], v[80:95]
	v_mfma_f32_32x32x16_bf16 v[16:31], v[164:167], v[176:179], v[16:31]
	v_mfma_f32_32x32x16_bf16 v[64:79], v[160:163], v[180:183], v[64:79]
	v_mfma_f32_32x32x16_bf16 v[0:15], v[164:167], v[180:183], v[0:15]
	ds_read_b128 v[160:163], v186
	ds_read_b128 v[168:171], v190
	ds_read_b128 v[164:167], v186 offset:4096
	ds_read_b128 v[172:175], v190 offset:4096
	ds_read_b128 v[176:179], v190 offset:8192
	ds_read_b128 v[180:183], v190 offset:12288
	s_waitcnt lgkmcnt(6)
	v_mfma_f32_32x32x16_bf16 v[112:127], v[128:131], v[136:139], v[112:127]
	v_mfma_f32_32x32x16_bf16 v[48:63], v[132:135], v[136:139], v[48:63]
	v_mfma_f32_32x32x16_bf16 v[96:111], v[128:131], v[140:143], v[96:111]
	v_mfma_f32_32x32x16_bf16 v[32:47], v[132:135], v[140:143], v[32:47]
	v_mfma_f32_32x32x16_bf16 v[80:95], v[128:131], v[144:147], v[80:95]
	v_mfma_f32_32x32x16_bf16 v[16:31], v[132:135], v[144:147], v[16:31]
	v_mfma_f32_32x32x16_bf16 v[64:79], v[128:131], v[148:151], v[64:79]
	v_mfma_f32_32x32x16_bf16 v[0:15], v[132:135], v[148:151], v[0:15]
	ds_read_b128 v[128:131], v187
	ds_read_b128 v[136:139], v191
	ds_read_b128 v[132:135], v187 offset:4096
	ds_read_b128 v[140:143], v191 offset:4096
	ds_read_b128 v[144:147], v191 offset:8192
	ds_read_b128 v[148:151], v191 offset:12288
	s_waitcnt lgkmcnt(6)
	v_mfma_f32_32x32x16_bf16 v[112:127], v[160:163], v[168:171], v[112:127]
	v_mfma_f32_32x32x16_bf16 v[48:63], v[164:167], v[168:171], v[48:63]
	v_mfma_f32_32x32x16_bf16 v[96:111], v[160:163], v[172:175], v[96:111]
	v_mfma_f32_32x32x16_bf16 v[32:47], v[164:167], v[172:175], v[32:47]
	v_mfma_f32_32x32x16_bf16 v[80:95], v[160:163], v[176:179], v[80:95]
	v_mfma_f32_32x32x16_bf16 v[16:31], v[164:167], v[176:179], v[16:31]
	v_mfma_f32_32x32x16_bf16 v[64:79], v[160:163], v[180:183], v[64:79]
	v_mfma_f32_32x32x16_bf16 v[0:15], v[164:167], v[180:183], v[0:15]
	s_waitcnt vmcnt(0) lgkmcnt(0)
	s_barrier
	v_xor_b32_e32 v184, 0x10000, v184
	v_xor_b32_e32 v188, 0x10000, v188
	ds_read_b128 v[160:163], v184
	ds_read_b128 v[168:171], v188
	ds_read_b128 v[164:167], v184 offset:4096
	ds_read_b128 v[172:175], v188 offset:4096
	ds_read_b128 v[176:179], v188 offset:8192
	ds_read_b128 v[180:183], v188 offset:12288
	s_add_u32 s20, s16, 1664
	s_addc_u32 s21, s17, 0
	s_add_u32 s24, s18, 1664
	s_addc_u32 s25, s19, 0
	v_mfma_f32_32x32x16_bf16 v[112:127], v[128:131], v[136:139], v[112:127]
	v_xor_b32_e32 v185, 0x10000, v185
	v_xor_b32_e32 v189, 0x10000, v189
	s_add_u32 m0, s27, 65536
	s_nop 0
	global_load_lds_dwordx4 v192, s[20:21]
	v_mfma_f32_32x32x16_bf16 v[48:63], v[132:135], v[136:139], v[48:63]
	v_xor_b32_e32 v186, 0x10000, v186
	v_xor_b32_e32 v190, 0x10000, v190
	s_add_u32 m0, s27, 98304
	s_nop 0
	global_load_lds_dwordx4 v192, s[24:25]
	v_mfma_f32_32x32x16_bf16 v[96:111], v[128:131], v[140:143], v[96:111]
	v_xor_b32_e32 v187, 0x10000, v187
	v_xor_b32_e32 v191, 0x10000, v191
	s_add_u32 m0, s27, 73728
	s_nop 0
	global_load_lds_dwordx4 v194, s[20:21]
	v_mfma_f32_32x32x16_bf16 v[32:47], v[132:135], v[140:143], v[32:47]
	s_add_u32 m0, s27, 106496
	s_nop 0
	global_load_lds_dwordx4 v194, s[24:25]
	v_mfma_f32_32x32x16_bf16 v[80:95], v[128:131], v[144:147], v[80:95]
	s_add_u32 m0, s27, 81920
	s_nop 0
	global_load_lds_dwordx4 v196, s[20:21]
	v_mfma_f32_32x32x16_bf16 v[16:31], v[132:135], v[144:147], v[16:31]
	s_add_u32 m0, s27, 114688
	s_nop 0
	global_load_lds_dwordx4 v196, s[24:25]
	v_mfma_f32_32x32x16_bf16 v[64:79], v[128:131], v[148:151], v[64:79]
	s_add_u32 m0, s27, 90112
	s_nop 0
	global_load_lds_dwordx4 v198, s[20:21]
	v_mfma_f32_32x32x16_bf16 v[0:15], v[132:135], v[148:151], v[0:15]
	s_add_u32 m0, s27, 122880
	s_nop 0
	global_load_lds_dwordx4 v198, s[24:25]
	ds_read_b128 v[128:131], v185
	ds_read_b128 v[136:139], v189
	ds_read_b128 v[132:135], v185 offset:4096
	ds_read_b128 v[140:143], v189 offset:4096
	ds_read_b128 v[144:147], v189 offset:8192
	ds_read_b128 v[148:151], v189 offset:12288
	s_waitcnt lgkmcnt(6)
	v_mfma_f32_32x32x16_bf16 v[112:127], v[160:163], v[168:171], v[112:127]
	v_mfma_f32_32x32x16_bf16 v[48:63], v[164:167], v[168:171], v[48:63]
	v_mfma_f32_32x32x16_bf16 v[96:111], v[160:163], v[172:175], v[96:111]
	v_mfma_f32_32x32x16_bf16 v[32:47], v[164:167], v[172:175], v[32:47]
	v_mfma_f32_32x32x16_bf16 v[80:95], v[160:163], v[176:179], v[80:95]
	v_mfma_f32_32x32x16_bf16 v[16:31], v[164:167], v[176:179], v[16:31]
	v_mfma_f32_32x32x16_bf16 v[64:79], v[160:163], v[180:183], v[64:79]
	v_mfma_f32_32x32x16_bf16 v[0:15], v[164:167], v[180:183], v[0:15]
	ds_read_b128 v[160:163], v186
	ds_read_b128 v[168:171], v190
	ds_read_b128 v[164:167], v186 offset:4096
	ds_read_b128 v[172:175], v190 offset:4096
	ds_read_b128 v[176:179], v190 offset:8192
	ds_read_b128 v[180:183], v190 offset:12288
	s_waitcnt lgkmcnt(6)
	v_mfma_f32_32x32x16_bf16 v[112:127], v[128:131], v[136:139], v[112:127]
	v_mfma_f32_32x32x16_bf16 v[48:63], v[132:135], v[136:139], v[48:63]
	v_mfma_f32_32x32x16_bf16 v[96:111], v[128:131], v[140:143], v[96:111]
	v_mfma_f32_32x32x16_bf16 v[32:47], v[132:135], v[140:143], v[32:47]
	v_mfma_f32_32x32x16_bf16 v[80:95], v[128:131], v[144:147], v[80:95]
	v_mfma_f32_32x32x16_bf16 v[16:31], v[132:135], v[144:147], v[16:31]
	v_mfma_f32_32x32x16_bf16 v[64:79], v[128:131], v[148:151], v[64:79]
	v_mfma_f32_32x32x16_bf16 v[0:15], v[132:135], v[148:151], v[0:15]
	ds_read_b128 v[128:131], v187
	ds_read_b128 v[136:139], v191
	ds_read_b128 v[132:135], v187 offset:4096
	ds_read_b128 v[140:143], v191 offset:4096
	ds_read_b128 v[144:147], v191 offset:8192
	ds_read_b128 v[148:151], v191 offset:12288
	s_waitcnt lgkmcnt(6)
	v_mfma_f32_32x32x16_bf16 v[112:127], v[160:163], v[168:171], v[112:127]
	v_mfma_f32_32x32x16_bf16 v[48:63], v[164:167], v[168:171], v[48:63]
	v_mfma_f32_32x32x16_bf16 v[96:111], v[160:163], v[172:175], v[96:111]
	v_mfma_f32_32x32x16_bf16 v[32:47], v[164:167], v[172:175], v[32:47]
	v_mfma_f32_32x32x16_bf16 v[80:95], v[160:163], v[176:179], v[80:95]
	v_mfma_f32_32x32x16_bf16 v[16:31], v[164:167], v[176:179], v[16:31]
	v_mfma_f32_32x32x16_bf16 v[64:79], v[160:163], v[180:183], v[64:79]
	v_mfma_f32_32x32x16_bf16 v[0:15], v[164:167], v[180:183], v[0:15]
	s_waitcnt vmcnt(0) lgkmcnt(0)
	s_barrier
	v_xor_b32_e32 v184, 0x10000, v184
	v_xor_b32_e32 v188, 0x10000, v188
	ds_read_b128 v[160:163], v184
	ds_read_b128 v[168:171], v188
	ds_read_b128 v[164:167], v184 offset:4096
	ds_read_b128 v[172:175], v188 offset:4096
	ds_read_b128 v[176:179], v188 offset:8192
	ds_read_b128 v[180:183], v188 offset:12288
	s_add_u32 s20, s16, 1792
	s_addc_u32 s21, s17, 0
	s_add_u32 s24, s18, 1792
	s_addc_u32 s25, s19, 0
	v_mfma_f32_32x32x16_bf16 v[112:127], v[128:131], v[136:139], v[112:127]
	v_xor_b32_e32 v185, 0x10000, v185
	v_xor_b32_e32 v189, 0x10000, v189
	s_add_u32 m0, s27, 0
	s_nop 0
	global_load_lds_dwordx4 v192, s[20:21]
	v_mfma_f32_32x32x16_bf16 v[48:63], v[132:135], v[136:139], v[48:63]
	v_xor_b32_e32 v186, 0x10000, v186
	v_xor_b32_e32 v190, 0x10000, v190
	s_add_u32 m0, s27, 32768
	s_nop 0
	global_load_lds_dwordx4 v192, s[24:25]
	v_mfma_f32_32x32x16_bf16 v[96:111], v[128:131], v[140:143], v[96:111]
	v_xor_b32_e32 v187, 0x10000, v187
	v_xor_b32_e32 v191, 0x10000, v191
	s_add_u32 m0, s27, 8192
	s_nop 0
	global_load_lds_dwordx4 v194, s[20:21]
	v_mfma_f32_32x32x16_bf16 v[32:47], v[132:135], v[140:143], v[32:47]
	s_add_u32 m0, s27, 40960
	s_nop 0
	global_load_lds_dwordx4 v194, s[24:25]
	v_mfma_f32_32x32x16_bf16 v[80:95], v[128:131], v[144:147], v[80:95]
	s_add_u32 m0, s27, 16384
	s_nop 0
	global_load_lds_dwordx4 v196, s[20:21]
	v_mfma_f32_32x32x16_bf16 v[16:31], v[132:135], v[144:147], v[16:31]
	s_add_u32 m0, s27, 49152
	s_nop 0
	global_load_lds_dwordx4 v196, s[24:25]
	v_mfma_f32_32x32x16_bf16 v[64:79], v[128:131], v[148:151], v[64:79]
	s_add_u32 m0, s27, 24576
	s_nop 0
	global_load_lds_dwordx4 v198, s[20:21]
	v_mfma_f32_32x32x16_bf16 v[0:15], v[132:135], v[148:151], v[0:15]
	s_add_u32 m0, s27, 57344
	s_nop 0
	global_load_lds_dwordx4 v198, s[24:25]
	ds_read_b128 v[128:131], v185
	ds_read_b128 v[136:139], v189
	ds_read_b128 v[132:135], v185 offset:4096
	ds_read_b128 v[140:143], v189 offset:4096
	ds_read_b128 v[144:147], v189 offset:8192
	ds_read_b128 v[148:151], v189 offset:12288
	s_waitcnt lgkmcnt(6)
	v_mfma_f32_32x32x16_bf16 v[112:127], v[160:163], v[168:171], v[112:127]
	v_mfma_f32_32x32x16_bf16 v[48:63], v[164:167], v[168:171], v[48:63]
	v_mfma_f32_32x32x16_bf16 v[96:111], v[160:163], v[172:175], v[96:111]
	v_mfma_f32_32x32x16_bf16 v[32:47], v[164:167], v[172:175], v[32:47]
	v_mfma_f32_32x32x16_bf16 v[80:95], v[160:163], v[176:179], v[80:95]
	v_mfma_f32_32x32x16_bf16 v[16:31], v[164:167], v[176:179], v[16:31]
	v_mfma_f32_32x32x16_bf16 v[64:79], v[160:163], v[180:183], v[64:79]
	v_mfma_f32_32x32x16_bf16 v[0:15], v[164:167], v[180:183], v[0:15]
	ds_read_b128 v[160:163], v186
	ds_read_b128 v[168:171], v190
	ds_read_b128 v[164:167], v186 offset:4096
	ds_read_b128 v[172:175], v190 offset:4096
	ds_read_b128 v[176:179], v190 offset:8192
	ds_read_b128 v[180:183], v190 offset:12288
	s_waitcnt lgkmcnt(6)
	v_mfma_f32_32x32x16_bf16 v[112:127], v[128:131], v[136:139], v[112:127]
	v_mfma_f32_32x32x16_bf16 v[48:63], v[132:135], v[136:139], v[48:63]
	v_mfma_f32_32x32x16_bf16 v[96:111], v[128:131], v[140:143], v[96:111]
	v_mfma_f32_32x32x16_bf16 v[32:47], v[132:135], v[140:143], v[32:47]
	v_mfma_f32_32x32x16_bf16 v[80:95], v[128:131], v[144:147], v[80:95]
	v_mfma_f32_32x32x16_bf16 v[16:31], v[132:135], v[144:147], v[16:31]
	v_mfma_f32_32x32x16_bf16 v[64:79], v[128:131], v[148:151], v[64:79]
	v_mfma_f32_32x32x16_bf16 v[0:15], v[132:135], v[148:151], v[0:15]
	ds_read_b128 v[128:131], v187
	ds_read_b128 v[136:139], v191
	ds_read_b128 v[132:135], v187 offset:4096
	ds_read_b128 v[140:143], v191 offset:4096
	ds_read_b128 v[144:147], v191 offset:8192
	ds_read_b128 v[148:151], v191 offset:12288
	s_waitcnt lgkmcnt(6)
	v_mfma_f32_32x32x16_bf16 v[112:127], v[160:163], v[168:171], v[112:127]
	v_mfma_f32_32x32x16_bf16 v[48:63], v[164:167], v[168:171], v[48:63]
	v_mfma_f32_32x32x16_bf16 v[96:111], v[160:163], v[172:175], v[96:111]
	v_mfma_f32_32x32x16_bf16 v[32:47], v[164:167], v[172:175], v[32:47]
	v_mfma_f32_32x32x16_bf16 v[80:95], v[160:163], v[176:179], v[80:95]
	v_mfma_f32_32x32x16_bf16 v[16:31], v[164:167], v[176:179], v[16:31]
	v_mfma_f32_32x32x16_bf16 v[64:79], v[160:163], v[180:183], v[64:79]
	v_mfma_f32_32x32x16_bf16 v[0:15], v[164:167], v[180:183], v[0:15]
	s_waitcnt vmcnt(0) lgkmcnt(0)
	s_barrier
	v_xor_b32_e32 v184, 0x10000, v184
	v_xor_b32_e32 v188, 0x10000, v188
	ds_read_b128 v[160:163], v184
	ds_read_b128 v[168:171], v188
	ds_read_b128 v[164:167], v184 offset:4096
	ds_read_b128 v[172:175], v188 offset:4096
	ds_read_b128 v[176:179], v188 offset:8192
	ds_read_b128 v[180:183], v188 offset:12288
	s_add_u32 s20, s16, 1920
	s_addc_u32 s21, s17, 0
	s_add_u32 s24, s18, 1920
	s_addc_u32 s25, s19, 0
	v_mfma_f32_32x32x16_bf16 v[112:127], v[128:131], v[136:139], v[112:127]
	v_xor_b32_e32 v185, 0x10000, v185
	v_xor_b32_e32 v189, 0x10000, v189
	s_add_u32 m0, s27, 65536
	s_nop 0
	global_load_lds_dwordx4 v192, s[20:21]
	v_mfma_f32_32x32x16_bf16 v[48:63], v[132:135], v[136:139], v[48:63]
	v_xor_b32_e32 v186, 0x10000, v186
	v_xor_b32_e32 v190, 0x10000, v190
	s_add_u32 m0, s27, 98304
	s_nop 0
	global_load_lds_dwordx4 v192, s[24:25]
	v_mfma_f32_32x32x16_bf16 v[96:111], v[128:131], v[140:143], v[96:111]
	v_xor_b32_e32 v187, 0x10000, v187
	v_xor_b32_e32 v191, 0x10000, v191
	s_add_u32 m0, s27, 73728
	s_nop 0
	global_load_lds_dwordx4 v194, s[20:21]
	v_mfma_f32_32x32x16_bf16 v[32:47], v[132:135], v[140:143], v[32:47]
	s_add_u32 m0, s27, 106496
	s_nop 0
	global_load_lds_dwordx4 v194, s[24:25]
	v_mfma_f32_32x32x16_bf16 v[80:95], v[128:131], v[144:147], v[80:95]
	s_add_u32 m0, s27, 81920
	s_nop 0
	global_load_lds_dwordx4 v196, s[20:21]
	v_mfma_f32_32x32x16_bf16 v[16:31], v[132:135], v[144:147], v[16:31]
	s_add_u32 m0, s27, 114688
	s_nop 0
	global_load_lds_dwordx4 v196, s[24:25]
	v_mfma_f32_32x32x16_bf16 v[64:79], v[128:131], v[148:151], v[64:79]
	s_add_u32 m0, s27, 90112
	s_nop 0
	global_load_lds_dwordx4 v198, s[20:21]
	v_mfma_f32_32x32x16_bf16 v[0:15], v[132:135], v[148:151], v[0:15]
	s_add_u32 m0, s27, 122880
	s_nop 0
	global_load_lds_dwordx4 v198, s[24:25]
	ds_read_b128 v[128:131], v185
	ds_read_b128 v[136:139], v189
	ds_read_b128 v[132:135], v185 offset:4096
	ds_read_b128 v[140:143], v189 offset:4096
	ds_read_b128 v[144:147], v189 offset:8192
	ds_read_b128 v[148:151], v189 offset:12288
	s_waitcnt lgkmcnt(6)
	v_mfma_f32_32x32x16_bf16 v[112:127], v[160:163], v[168:171], v[112:127]
	v_mfma_f32_32x32x16_bf16 v[48:63], v[164:167], v[168:171], v[48:63]
	v_mfma_f32_32x32x16_bf16 v[96:111], v[160:163], v[172:175], v[96:111]
	v_mfma_f32_32x32x16_bf16 v[32:47], v[164:167], v[172:175], v[32:47]
	v_mfma_f32_32x32x16_bf16 v[80:95], v[160:163], v[176:179], v[80:95]
	v_mfma_f32_32x32x16_bf16 v[16:31], v[164:167], v[176:179], v[16:31]
	v_mfma_f32_32x32x16_bf16 v[64:79], v[160:163], v[180:183], v[64:79]
	v_mfma_f32_32x32x16_bf16 v[0:15], v[164:167], v[180:183], v[0:15]
	ds_read_b128 v[160:163], v186
	ds_read_b128 v[168:171], v190
	ds_read_b128 v[164:167], v186 offset:4096
	ds_read_b128 v[172:175], v190 offset:4096
	ds_read_b128 v[176:179], v190 offset:8192
	ds_read_b128 v[180:183], v190 offset:12288
	s_waitcnt lgkmcnt(6)
	v_mfma_f32_32x32x16_bf16 v[112:127], v[128:131], v[136:139], v[112:127]
	v_mfma_f32_32x32x16_bf16 v[48:63], v[132:135], v[136:139], v[48:63]
	v_mfma_f32_32x32x16_bf16 v[96:111], v[128:131], v[140:143], v[96:111]
	v_mfma_f32_32x32x16_bf16 v[32:47], v[132:135], v[140:143], v[32:47]
	v_mfma_f32_32x32x16_bf16 v[80:95], v[128:131], v[144:147], v[80:95]
	v_mfma_f32_32x32x16_bf16 v[16:31], v[132:135], v[144:147], v[16:31]
	v_mfma_f32_32x32x16_bf16 v[64:79], v[128:131], v[148:151], v[64:79]
	v_mfma_f32_32x32x16_bf16 v[0:15], v[132:135], v[148:151], v[0:15]
	ds_read_b128 v[128:131], v187
	ds_read_b128 v[136:139], v191
	ds_read_b128 v[132:135], v187 offset:4096
	ds_read_b128 v[140:143], v191 offset:4096
	ds_read_b128 v[144:147], v191 offset:8192
	ds_read_b128 v[148:151], v191 offset:12288
	s_waitcnt lgkmcnt(6)
	v_mfma_f32_32x32x16_bf16 v[112:127], v[160:163], v[168:171], v[112:127]
	v_mfma_f32_32x32x16_bf16 v[48:63], v[164:167], v[168:171], v[48:63]
	v_mfma_f32_32x32x16_bf16 v[96:111], v[160:163], v[172:175], v[96:111]
	v_mfma_f32_32x32x16_bf16 v[32:47], v[164:167], v[172:175], v[32:47]
	v_mfma_f32_32x32x16_bf16 v[80:95], v[160:163], v[176:179], v[80:95]
	v_mfma_f32_32x32x16_bf16 v[16:31], v[164:167], v[176:179], v[16:31]
	v_mfma_f32_32x32x16_bf16 v[64:79], v[160:163], v[180:183], v[64:79]
	v_mfma_f32_32x32x16_bf16 v[0:15], v[164:167], v[180:183], v[0:15]
	s_waitcnt vmcnt(0) lgkmcnt(0)
	s_barrier
	v_xor_b32_e32 v184, 0x10000, v184
	v_xor_b32_e32 v188, 0x10000, v188
	ds_read_b128 v[160:163], v184
	ds_read_b128 v[168:171], v188
	ds_read_b128 v[164:167], v184 offset:4096
	ds_read_b128 v[172:175], v188 offset:4096
	ds_read_b128 v[176:179], v188 offset:8192
	ds_read_b128 v[180:183], v188 offset:12288
	s_add_u32 s37, s30, s42
	s_cmpk_ge_u32 s37, 0x780
	s_cbranch_scc1 .Lip11_full_nonext
	s_mul_hi_u32 s38, s37, 0x92492493
	s_lshr_b32 s38, s38, 3
	s_mul_i32 s39, s38, 14
	s_sub_u32 s39, s37, s39
	s_sub_u32 s98, s37, 0x700
	s_cmpk_lt_u32 s37, 0x700
	s_cselect_b32 s39, s39, 14
	s_cselect_b32 s38, s38, s98
	s_lshl_b32 s98, s38, 19
	s_add_u32 s16, s4, s98
	s_addc_u32 s17, s5, 0
	s_lshl_b32 s98, s39, 19
	s_add_u32 s18, s6, s98
	s_addc_u32 s19, s7, 0
	v_mfma_f32_32x32x16_bf16 v[112:127], v[128:131], v[136:139], v[112:127]
	v_xor_b32_e32 v185, 0x10000, v185
	v_xor_b32_e32 v189, 0x10000, v189
	s_add_u32 m0, s27, 0
	s_nop 0
	global_load_lds_dwordx4 v192, s[16:17]
	v_mfma_f32_32x32x16_bf16 v[48:63], v[132:135], v[136:139], v[48:63]
	v_xor_b32_e32 v186, 0x10000, v186
	v_xor_b32_e32 v190, 0x10000, v190
	s_add_u32 m0, s27, 32768
	s_nop 0
	global_load_lds_dwordx4 v192, s[18:19]
	v_mfma_f32_32x32x16_bf16 v[96:111], v[128:131], v[140:143], v[96:111]
	v_xor_b32_e32 v187, 0x10000, v187
	v_xor_b32_e32 v191, 0x10000, v191
	s_add_u32 m0, s27, 8192
	s_nop 0
	global_load_lds_dwordx4 v194, s[16:17]
	v_mfma_f32_32x32x16_bf16 v[32:47], v[132:135], v[140:143], v[32:47]
	s_add_u32 m0, s27, 40960
	s_nop 0
	global_load_lds_dwordx4 v194, s[18:19]
	v_mfma_f32_32x32x16_bf16 v[80:95], v[128:131], v[144:147], v[80:95]
	s_add_u32 m0, s27, 16384
	s_nop 0
	global_load_lds_dwordx4 v196, s[16:17]
	v_mfma_f32_32x32x16_bf16 v[16:31], v[132:135], v[144:147], v[16:31]
	s_add_u32 m0, s27, 49152
	s_nop 0
	global_load_lds_dwordx4 v196, s[18:19]
	v_mfma_f32_32x32x16_bf16 v[64:79], v[128:131], v[148:151], v[64:79]
	s_add_u32 m0, s27, 24576
	s_nop 0
	global_load_lds_dwordx4 v198, s[16:17]
	v_mfma_f32_32x32x16_bf16 v[0:15], v[132:135], v[148:151], v[0:15]
	s_add_u32 m0, s27, 57344
	s_nop 0
	global_load_lds_dwordx4 v198, s[18:19]
	s_branch .Lip11_full_join

.Lip11_light:
	s_cmp_eq_u32 s31, 0
	s_cbranch_scc0 .Lip11_lload
	ds_read_b128 v[160:163], v184
	ds_read_b128 v[168:171], v188
	ds_read_b128 v[164:167], v184 offset:4096
	ds_read_b128 v[172:175], v188 offset:4096
	ds_read_b128 v[128:131], v185
	ds_read_b128 v[136:139], v189
	ds_read_b128 v[132:135], v185 offset:4096
	ds_read_b128 v[140:143], v189 offset:4096
	s_waitcnt lgkmcnt(4)
	v_mfma_f32_32x32x16_bf16 v[112:127], v[160:163], v[168:171], 0
	v_mfma_f32_32x32x16_bf16 v[48:63], v[164:167], v[168:171], 0
	v_mfma_f32_32x32x16_bf16 v[96:111], v[160:163], v[172:175], 0
	v_mfma_f32_32x32x16_bf16 v[32:47], v[164:167], v[172:175], 0
	ds_read_b128 v[160:163], v186
	ds_read_b128 v[168:171], v190
	ds_read_b128 v[164:167], v186 offset:4096
	ds_read_b128 v[172:175], v190 offset:4096
	s_waitcnt lgkmcnt(4)
	v_mfma_f32_32x32x16_bf16 v[112:127], v[128:131], v[136:139], v[112:127]
	v_mfma_f32_32x32x16_bf16 v[48:63], v[132:135], v[136:139], v[48:63]
	v_mfma_f32_32x32x16_bf16 v[96:111], v[128:131], v[140:143], v[96:111]
	v_mfma_f32_32x32x16_bf16 v[32:47], v[132:135], v[140:143], v[32:47]
	ds_read_b128 v[128:131], v187
	ds_read_b128 v[136:139], v191
	ds_read_b128 v[132:135], v187 offset:4096
	ds_read_b128 v[140:143], v191 offset:4096
	s_waitcnt lgkmcnt(4)
	v_mfma_f32_32x32x16_bf16 v[112:127], v[160:163], v[168:171], v[112:127]
	v_mfma_f32_32x32x16_bf16 v[48:63], v[164:167], v[168:171], v[48:63]
	v_mfma_f32_32x32x16_bf16 v[96:111], v[160:163], v[172:175], v[96:111]
	v_mfma_f32_32x32x16_bf16 v[32:47], v[164:167], v[172:175], v[32:47]
	s_waitcnt vmcnt(0) lgkmcnt(0)
	s_barrier
	v_xor_b32_e32 v184, 0x10000, v184
	v_xor_b32_e32 v188, 0x10000, v188
	ds_read_b128 v[160:163], v184
	ds_read_b128 v[168:171], v188
	ds_read_b128 v[164:167], v184 offset:4096
	ds_read_b128 v[172:175], v188 offset:4096
	s_add_u32 s20, s16, 256
	s_addc_u32 s21, s17, 0
	s_add_u32 s24, s18, 256
	s_addc_u32 s25, s19, 0
	v_mfma_f32_32x32x16_bf16 v[112:127], v[128:131], v[136:139], v[112:127]
	v_xor_b32_e32 v185, 0x10000, v185
	v_xor_b32_e32 v189, 0x10000, v189
	s_add_u32 m0, s27, 0
	s_nop 0
	global_load_lds_dwordx4 v192, s[20:21]
	v_mfma_f32_32x32x16_bf16 v[48:63], v[132:135], v[136:139], v[48:63]
	v_xor_b32_e32 v186, 0x10000, v186
	v_xor_b32_e32 v190, 0x10000, v190
	s_add_u32 m0, s27, 32768
	s_nop 0
	global_load_lds_dwordx4 v192, s[24:25]
	v_mfma_f32_32x32x16_bf16 v[96:111], v[128:131], v[140:143], v[96:111]
	v_xor_b32_e32 v187, 0x10000, v187
	v_xor_b32_e32 v191, 0x10000, v191
	s_add_u32 m0, s27, 8192
	s_nop 0
	global_load_lds_dwordx4 v194, s[20:21]
	v_mfma_f32_32x32x16_bf16 v[32:47], v[132:135], v[140:143], v[32:47]
	s_add_u32 m0, s27, 40960
	s_nop 0
	global_load_lds_dwordx4 v194, s[24:25]
	s_add_u32 m0, s27, 16384
	s_nop 0
	global_load_lds_dwordx4 v196, s[20:21]
	s_add_u32 m0, s27, 49152
	s_nop 0
	global_load_lds_dwordx4 v196, s[24:25]
	s_add_u32 m0, s27, 24576
	s_nop 0
	global_load_lds_dwordx4 v198, s[20:21]
	s_add_u32 m0, s27, 57344
	s_nop 0
	global_load_lds_dwordx4 v198, s[24:25]
	ds_read_b128 v[128:131], v185
	ds_read_b128 v[136:139], v189
	ds_read_b128 v[132:135], v185 offset:4096
	ds_read_b128 v[140:143], v189 offset:4096
	s_waitcnt lgkmcnt(4)
	v_mfma_f32_32x32x16_bf16 v[112:127], v[160:163], v[168:171], v[112:127]
	v_mfma_f32_32x32x16_bf16 v[48:63], v[164:167], v[168:171], v[48:63]
	v_mfma_f32_32x32x16_bf16 v[96:111], v[160:163], v[172:175], v[96:111]
	v_mfma_f32_32x32x16_bf16 v[32:47], v[164:167], v[172:175], v[32:47]
	ds_read_b128 v[160:163], v186
	ds_read_b128 v[168:171], v190
	ds_read_b128 v[164:167], v186 offset:4096
	ds_read_b128 v[172:175], v190 offset:4096
	s_waitcnt lgkmcnt(4)
	v_mfma_f32_32x32x16_bf16 v[112:127], v[128:131], v[136:139], v[112:127]
	v_mfma_f32_32x32x16_bf16 v[48:63], v[132:135], v[136:139], v[48:63]
	v_mfma_f32_32x32x16_bf16 v[96:111], v[128:131], v[140:143], v[96:111]
	v_mfma_f32_32x32x16_bf16 v[32:47], v[132:135], v[140:143], v[32:47]
	ds_read_b128 v[128:131], v187
	ds_read_b128 v[136:139], v191
	ds_read_b128 v[132:135], v187 offset:4096
	ds_read_b128 v[140:143], v191 offset:4096
	s_waitcnt lgkmcnt(4)
	v_mfma_f32_32x32x16_bf16 v[112:127], v[160:163], v[168:171], v[112:127]
	v_mfma_f32_32x32x16_bf16 v[48:63], v[164:167], v[168:171], v[48:63]
	v_mfma_f32_32x32x16_bf16 v[96:111], v[160:163], v[172:175], v[96:111]
	v_mfma_f32_32x32x16_bf16 v[32:47], v[164:167], v[172:175], v[32:47]
	s_waitcnt vmcnt(0) lgkmcnt(0)
	s_barrier
	v_xor_b32_e32 v184, 0x10000, v184
	v_xor_b32_e32 v188, 0x10000, v188
	ds_read_b128 v[160:163], v184
	ds_read_b128 v[168:171], v188
	ds_read_b128 v[164:167], v184 offset:4096
	ds_read_b128 v[172:175], v188 offset:4096
	s_add_u32 s20, s16, 384
	s_addc_u32 s21, s17, 0
	s_add_u32 s24, s18, 384
	s_addc_u32 s25, s19, 0
	v_mfma_f32_32x32x16_bf16 v[112:127], v[128:131], v[136:139], v[112:127]
	v_xor_b32_e32 v185, 0x10000, v185
	v_xor_b32_e32 v189, 0x10000, v189
	s_add_u32 m0, s27, 65536
	s_nop 0
	global_load_lds_dwordx4 v192, s[20:21]
	v_mfma_f32_32x32x16_bf16 v[48:63], v[132:135], v[136:139], v[48:63]
	v_xor_b32_e32 v186, 0x10000, v186
	v_xor_b32_e32 v190, 0x10000, v190
	s_add_u32 m0, s27, 98304
	s_nop 0
	global_load_lds_dwordx4 v192, s[24:25]
	v_mfma_f32_32x32x16_bf16 v[96:111], v[128:131], v[140:143], v[96:111]
	v_xor_b32_e32 v187, 0x10000, v187
	v_xor_b32_e32 v191, 0x10000, v191
	s_add_u32 m0, s27, 73728
	s_nop 0
	global_load_lds_dwordx4 v194, s[20:21]
	v_mfma_f32_32x32x16_bf16 v[32:47], v[132:135], v[140:143], v[32:47]
	s_add_u32 m0, s27, 106496
	s_nop 0
	global_load_lds_dwordx4 v194, s[24:25]
	s_add_u32 m0, s27, 81920
	s_nop 0
	global_load_lds_dwordx4 v196, s[20:21]
	s_add_u32 m0, s27, 114688
	s_nop 0
	global_load_lds_dwordx4 v196, s[24:25]
	s_add_u32 m0, s27, 90112
	s_nop 0
	global_load_lds_dwordx4 v198, s[20:21]
	s_add_u32 m0, s27, 122880
	s_nop 0
	global_load_lds_dwordx4 v198, s[24:25]
	ds_read_b128 v[128:131], v185
	ds_read_b128 v[136:139], v189
	ds_read_b128 v[132:135], v185 offset:4096
	ds_read_b128 v[140:143], v189 offset:4096
	s_waitcnt lgkmcnt(4)
	v_mfma_f32_32x32x16_bf16 v[112:127], v[160:163], v[168:171], v[112:127]
	v_mfma_f32_32x32x16_bf16 v[48:63], v[164:167], v[168:171], v[48:63]
	v_mfma_f32_32x32x16_bf16 v[96:111], v[160:163], v[172:175], v[96:111]
	v_mfma_f32_32x32x16_bf16 v[32:47], v[164:167], v[172:175], v[32:47]
	ds_read_b128 v[160:163], v186
	ds_read_b128 v[168:171], v190
	ds_read_b128 v[164:167], v186 offset:4096
	ds_read_b128 v[172:175], v190 offset:4096
	s_waitcnt lgkmcnt(4)
	v_mfma_f32_32x32x16_bf16 v[112:127], v[128:131], v[136:139], v[112:127]
	v_mfma_f32_32x32x16_bf16 v[48:63], v[132:135], v[136:139], v[48:63]
	v_mfma_f32_32x32x16_bf16 v[96:111], v[128:131], v[140:143], v[96:111]
	v_mfma_f32_32x32x16_bf16 v[32:47], v[132:135], v[140:143], v[32:47]
	ds_read_b128 v[128:131], v187
	ds_read_b128 v[136:139], v191
	ds_read_b128 v[132:135], v187 offset:4096
	ds_read_b128 v[140:143], v191 offset:4096
	s_waitcnt lgkmcnt(4)
	v_mfma_f32_32x32x16_bf16 v[112:127], v[160:163], v[168:171], v[112:127]
	v_mfma_f32_32x32x16_bf16 v[48:63], v[164:167], v[168:171], v[48:63]
	v_mfma_f32_32x32x16_bf16 v[96:111], v[160:163], v[172:175], v[96:111]
	v_mfma_f32_32x32x16_bf16 v[32:47], v[164:167], v[172:175], v[32:47]
	s_waitcnt vmcnt(0) lgkmcnt(0)
	s_barrier
	v_xor_b32_e32 v184, 0x10000, v184
	v_xor_b32_e32 v188, 0x10000, v188
	ds_read_b128 v[160:163], v184
	ds_read_b128 v[168:171], v188
	ds_read_b128 v[164:167], v184 offset:4096
	ds_read_b128 v[172:175], v188 offset:4096
	s_add_u32 s20, s16, 512
	s_addc_u32 s21, s17, 0
	s_add_u32 s24, s18, 512
	s_addc_u32 s25, s19, 0
	v_mfma_f32_32x32x16_bf16 v[112:127], v[128:131], v[136:139], v[112:127]
	v_xor_b32_e32 v185, 0x10000, v185
	v_xor_b32_e32 v189, 0x10000, v189
	s_add_u32 m0, s27, 0
	s_nop 0
	global_load_lds_dwordx4 v192, s[20:21]
	v_mfma_f32_32x32x16_bf16 v[48:63], v[132:135], v[136:139], v[48:63]
	v_xor_b32_e32 v186, 0x10000, v186
	v_xor_b32_e32 v190, 0x10000, v190
	s_add_u32 m0, s27, 32768
	s_nop 0
	global_load_lds_dwordx4 v192, s[24:25]
	v_mfma_f32_32x32x16_bf16 v[96:111], v[128:131], v[140:143], v[96:111]
	v_xor_b32_e32 v187, 0x10000, v187
	v_xor_b32_e32 v191, 0x10000, v191
	s_add_u32 m0, s27, 8192
	s_nop 0
	global_load_lds_dwordx4 v194, s[20:21]
	v_mfma_f32_32x32x16_bf16 v[32:47], v[132:135], v[140:143], v[32:47]
	s_add_u32 m0, s27, 40960
	s_nop 0
	global_load_lds_dwordx4 v194, s[24:25]
	s_add_u32 m0, s27, 16384
	s_nop 0
	global_load_lds_dwordx4 v196, s[20:21]
	s_add_u32 m0, s27, 49152
	s_nop 0
	global_load_lds_dwordx4 v196, s[24:25]
	s_add_u32 m0, s27, 24576
	s_nop 0
	global_load_lds_dwordx4 v198, s[20:21]
	s_add_u32 m0, s27, 57344
	s_nop 0
	global_load_lds_dwordx4 v198, s[24:25]
	ds_read_b128 v[128:131], v185
	ds_read_b128 v[136:139], v189
	ds_read_b128 v[132:135], v185 offset:4096
	ds_read_b128 v[140:143], v189 offset:4096
	s_waitcnt lgkmcnt(4)
	v_mfma_f32_32x32x16_bf16 v[112:127], v[160:163], v[168:171], v[112:127]
	v_mfma_f32_32x32x16_bf16 v[48:63], v[164:167], v[168:171], v[48:63]
	v_mfma_f32_32x32x16_bf16 v[96:111], v[160:163], v[172:175], v[96:111]
	v_mfma_f32_32x32x16_bf16 v[32:47], v[164:167], v[172:175], v[32:47]
	ds_read_b128 v[160:163], v186
	ds_read_b128 v[168:171], v190
	ds_read_b128 v[164:167], v186 offset:4096
	ds_read_b128 v[172:175], v190 offset:4096
	s_waitcnt lgkmcnt(4)
	v_mfma_f32_32x32x16_bf16 v[112:127], v[128:131], v[136:139], v[112:127]
	v_mfma_f32_32x32x16_bf16 v[48:63], v[132:135], v[136:139], v[48:63]
	v_mfma_f32_32x32x16_bf16 v[96:111], v[128:131], v[140:143], v[96:111]
	v_mfma_f32_32x32x16_bf16 v[32:47], v[132:135], v[140:143], v[32:47]
	ds_read_b128 v[128:131], v187
	ds_read_b128 v[136:139], v191
	ds_read_b128 v[132:135], v187 offset:4096
	ds_read_b128 v[140:143], v191 offset:4096
	s_waitcnt lgkmcnt(4)
	v_mfma_f32_32x32x16_bf16 v[112:127], v[160:163], v[168:171], v[112:127]
	v_mfma_f32_32x32x16_bf16 v[48:63], v[164:167], v[168:171], v[48:63]
	v_mfma_f32_32x32x16_bf16 v[96:111], v[160:163], v[172:175], v[96:111]
	v_mfma_f32_32x32x16_bf16 v[32:47], v[164:167], v[172:175], v[32:47]
	s_waitcnt vmcnt(0) lgkmcnt(0)
	s_barrier
	v_xor_b32_e32 v184, 0x10000, v184
	v_xor_b32_e32 v188, 0x10000, v188
	ds_read_b128 v[160:163], v184
	ds_read_b128 v[168:171], v188
	ds_read_b128 v[164:167], v184 offset:4096
	ds_read_b128 v[172:175], v188 offset:4096
	s_add_u32 s20, s16, 640
	s_addc_u32 s21, s17, 0
	s_add_u32 s24, s18, 640
	s_addc_u32 s25, s19, 0
	v_mfma_f32_32x32x16_bf16 v[112:127], v[128:131], v[136:139], v[112:127]
	v_xor_b32_e32 v185, 0x10000, v185
	v_xor_b32_e32 v189, 0x10000, v189
	s_add_u32 m0, s27, 65536
	s_nop 0
	global_load_lds_dwordx4 v192, s[20:21]
	v_mfma_f32_32x32x16_bf16 v[48:63], v[132:135], v[136:139], v[48:63]
	v_xor_b32_e32 v186, 0x10000, v186
	v_xor_b32_e32 v190, 0x10000, v190
	s_add_u32 m0, s27, 98304
	s_nop 0
	global_load_lds_dwordx4 v192, s[24:25]
	v_mfma_f32_32x32x16_bf16 v[96:111], v[128:131], v[140:143], v[96:111]
	v_xor_b32_e32 v187, 0x10000, v187
	v_xor_b32_e32 v191, 0x10000, v191
	s_add_u32 m0, s27, 73728
	s_nop 0
	global_load_lds_dwordx4 v194, s[20:21]
	v_mfma_f32_32x32x16_bf16 v[32:47], v[132:135], v[140:143], v[32:47]
	s_add_u32 m0, s27, 106496
	s_nop 0
	global_load_lds_dwordx4 v194, s[24:25]
	s_add_u32 m0, s27, 81920
	s_nop 0
	global_load_lds_dwordx4 v196, s[20:21]
	s_add_u32 m0, s27, 114688
	s_nop 0
	global_load_lds_dwordx4 v196, s[24:25]
	s_add_u32 m0, s27, 90112
	s_nop 0
	global_load_lds_dwordx4 v198, s[20:21]
	s_add_u32 m0, s27, 122880
	s_nop 0
	global_load_lds_dwordx4 v198, s[24:25]
	ds_read_b128 v[128:131], v185
	ds_read_b128 v[136:139], v189
	ds_read_b128 v[132:135], v185 offset:4096
	ds_read_b128 v[140:143], v189 offset:4096
	s_waitcnt lgkmcnt(4)
	v_mfma_f32_32x32x16_bf16 v[112:127], v[160:163], v[168:171], v[112:127]
	v_mfma_f32_32x32x16_bf16 v[48:63], v[164:167], v[168:171], v[48:63]
	v_mfma_f32_32x32x16_bf16 v[96:111], v[160:163], v[172:175], v[96:111]
	v_mfma_f32_32x32x16_bf16 v[32:47], v[164:167], v[172:175], v[32:47]
	ds_read_b128 v[160:163], v186
	ds_read_b128 v[168:171], v190
	ds_read_b128 v[164:167], v186 offset:4096
	ds_read_b128 v[172:175], v190 offset:4096
	s_waitcnt lgkmcnt(4)
	v_mfma_f32_32x32x16_bf16 v[112:127], v[128:131], v[136:139], v[112:127]
	v_mfma_f32_32x32x16_bf16 v[48:63], v[132:135], v[136:139], v[48:63]
	v_mfma_f32_32x32x16_bf16 v[96:111], v[128:131], v[140:143], v[96:111]
	v_mfma_f32_32x32x16_bf16 v[32:47], v[132:135], v[140:143], v[32:47]
	ds_read_b128 v[128:131], v187
	ds_read_b128 v[136:139], v191
	ds_read_b128 v[132:135], v187 offset:4096
	ds_read_b128 v[140:143], v191 offset:4096
	s_waitcnt lgkmcnt(4)
	v_mfma_f32_32x32x16_bf16 v[112:127], v[160:163], v[168:171], v[112:127]
	v_mfma_f32_32x32x16_bf16 v[48:63], v[164:167], v[168:171], v[48:63]
	v_mfma_f32_32x32x16_bf16 v[96:111], v[160:163], v[172:175], v[96:111]
	v_mfma_f32_32x32x16_bf16 v[32:47], v[164:167], v[172:175], v[32:47]
	s_waitcnt vmcnt(0) lgkmcnt(0)
	s_barrier
	v_xor_b32_e32 v184, 0x10000, v184
	v_xor_b32_e32 v188, 0x10000, v188
	ds_read_b128 v[160:163], v184
	ds_read_b128 v[168:171], v188
	ds_read_b128 v[164:167], v184 offset:4096
	ds_read_b128 v[172:175], v188 offset:4096
	s_add_u32 s20, s16, 768
	s_addc_u32 s21, s17, 0
	s_add_u32 s24, s18, 768
	s_addc_u32 s25, s19, 0
	v_mfma_f32_32x32x16_bf16 v[112:127], v[128:131], v[136:139], v[112:127]
	v_xor_b32_e32 v185, 0x10000, v185
	v_xor_b32_e32 v189, 0x10000, v189
	s_add_u32 m0, s27, 0
	s_nop 0
	global_load_lds_dwordx4 v192, s[20:21]
	v_mfma_f32_32x32x16_bf16 v[48:63], v[132:135], v[136:139], v[48:63]
	v_xor_b32_e32 v186, 0x10000, v186
	v_xor_b32_e32 v190, 0x10000, v190
	s_add_u32 m0, s27, 32768
	s_nop 0
	global_load_lds_dwordx4 v192, s[24:25]
	v_mfma_f32_32x32x16_bf16 v[96:111], v[128:131], v[140:143], v[96:111]
	v_xor_b32_e32 v187, 0x10000, v187
	v_xor_b32_e32 v191, 0x10000, v191
	s_add_u32 m0, s27, 8192
	s_nop 0
	global_load_lds_dwordx4 v194, s[20:21]
	v_mfma_f32_32x32x16_bf16 v[32:47], v[132:135], v[140:143], v[32:47]
	s_add_u32 m0, s27, 40960
	s_nop 0
	global_load_lds_dwordx4 v194, s[24:25]
	s_add_u32 m0, s27, 16384
	s_nop 0
	global_load_lds_dwordx4 v196, s[20:21]
	s_add_u32 m0, s27, 49152
	s_nop 0
	global_load_lds_dwordx4 v196, s[24:25]
	s_add_u32 m0, s27, 24576
	s_nop 0
	global_load_lds_dwordx4 v198, s[20:21]
	s_add_u32 m0, s27, 57344
	s_nop 0
	global_load_lds_dwordx4 v198, s[24:25]
	ds_read_b128 v[128:131], v185
	ds_read_b128 v[136:139], v189
	ds_read_b128 v[132:135], v185 offset:4096
	ds_read_b128 v[140:143], v189 offset:4096
	s_waitcnt lgkmcnt(4)
	v_mfma_f32_32x32x16_bf16 v[112:127], v[160:163], v[168:171], v[112:127]
	v_mfma_f32_32x32x16_bf16 v[48:63], v[164:167], v[168:171], v[48:63]
	v_mfma_f32_32x32x16_bf16 v[96:111], v[160:163], v[172:175], v[96:111]
	v_mfma_f32_32x32x16_bf16 v[32:47], v[164:167], v[172:175], v[32:47]
	ds_read_b128 v[160:163], v186
	ds_read_b128 v[168:171], v190
	ds_read_b128 v[164:167], v186 offset:4096
	ds_read_b128 v[172:175], v190 offset:4096
	s_waitcnt lgkmcnt(4)
	v_mfma_f32_32x32x16_bf16 v[112:127], v[128:131], v[136:139], v[112:127]
	v_mfma_f32_32x32x16_bf16 v[48:63], v[132:135], v[136:139], v[48:63]
	v_mfma_f32_32x32x16_bf16 v[96:111], v[128:131], v[140:143], v[96:111]
	v_mfma_f32_32x32x16_bf16 v[32:47], v[132:135], v[140:143], v[32:47]
	ds_read_b128 v[128:131], v187
	ds_read_b128 v[136:139], v191
	ds_read_b128 v[132:135], v187 offset:4096
	ds_read_b128 v[140:143], v191 offset:4096
	s_waitcnt lgkmcnt(4)
	v_mfma_f32_32x32x16_bf16 v[112:127], v[160:163], v[168:171], v[112:127]
	v_mfma_f32_32x32x16_bf16 v[48:63], v[164:167], v[168:171], v[48:63]
	v_mfma_f32_32x32x16_bf16 v[96:111], v[160:163], v[172:175], v[96:111]
	v_mfma_f32_32x32x16_bf16 v[32:47], v[164:167], v[172:175], v[32:47]
	s_waitcnt vmcnt(0) lgkmcnt(0)
	s_barrier
	v_xor_b32_e32 v184, 0x10000, v184
	v_xor_b32_e32 v188, 0x10000, v188
	ds_read_b128 v[160:163], v184
	ds_read_b128 v[168:171], v188
	ds_read_b128 v[164:167], v184 offset:4096
	ds_read_b128 v[172:175], v188 offset:4096
	s_add_u32 s20, s16, 896
	s_addc_u32 s21, s17, 0
	s_add_u32 s24, s18, 896
	s_addc_u32 s25, s19, 0
	v_mfma_f32_32x32x16_bf16 v[112:127], v[128:131], v[136:139], v[112:127]
	v_xor_b32_e32 v185, 0x10000, v185
	v_xor_b32_e32 v189, 0x10000, v189
	s_add_u32 m0, s27, 65536
	s_nop 0
	global_load_lds_dwordx4 v192, s[20:21]
	v_mfma_f32_32x32x16_bf16 v[48:63], v[132:135], v[136:139], v[48:63]
	v_xor_b32_e32 v186, 0x10000, v186
	v_xor_b32_e32 v190, 0x10000, v190
	s_add_u32 m0, s27, 98304
	s_nop 0
	global_load_lds_dwordx4 v192, s[24:25]
	v_mfma_f32_32x32x16_bf16 v[96:111], v[128:131], v[140:143], v[96:111]
	v_xor_b32_e32 v187, 0x10000, v187
	v_xor_b32_e32 v191, 0x10000, v191
	s_add_u32 m0, s27, 73728
	s_nop 0
	global_load_lds_dwordx4 v194, s[20:21]
	v_mfma_f32_32x32x16_bf16 v[32:47], v[132:135], v[140:143], v[32:47]
	s_add_u32 m0, s27, 106496
	s_nop 0
	global_load_lds_dwordx4 v194, s[24:25]
	s_add_u32 m0, s27, 81920
	s_nop 0
	global_load_lds_dwordx4 v196, s[20:21]
	s_add_u32 m0, s27, 114688
	s_nop 0
	global_load_lds_dwordx4 v196, s[24:25]
	s_add_u32 m0, s27, 90112
	s_nop 0
	global_load_lds_dwordx4 v198, s[20:21]
	s_add_u32 m0, s27, 122880
	s_nop 0
	global_load_lds_dwordx4 v198, s[24:25]
	ds_read_b128 v[128:131], v185
	ds_read_b128 v[136:139], v189
	ds_read_b128 v[132:135], v185 offset:4096
	ds_read_b128 v[140:143], v189 offset:4096
	s_waitcnt lgkmcnt(4)
	v_mfma_f32_32x32x16_bf16 v[112:127], v[160:163], v[168:171], v[112:127]
	v_mfma_f32_32x32x16_bf16 v[48:63], v[164:167], v[168:171], v[48:63]
	v_mfma_f32_32x32x16_bf16 v[96:111], v[160:163], v[172:175], v[96:111]
	v_mfma_f32_32x32x16_bf16 v[32:47], v[164:167], v[172:175], v[32:47]
	ds_read_b128 v[160:163], v186
	ds_read_b128 v[168:171], v190
	ds_read_b128 v[164:167], v186 offset:4096
	ds_read_b128 v[172:175], v190 offset:4096
	s_waitcnt lgkmcnt(4)
	v_mfma_f32_32x32x16_bf16 v[112:127], v[128:131], v[136:139], v[112:127]
	v_mfma_f32_32x32x16_bf16 v[48:63], v[132:135], v[136:139], v[48:63]
	v_mfma_f32_32x32x16_bf16 v[96:111], v[128:131], v[140:143], v[96:111]
	v_mfma_f32_32x32x16_bf16 v[32:47], v[132:135], v[140:143], v[32:47]
	ds_read_b128 v[128:131], v187
	ds_read_b128 v[136:139], v191
	ds_read_b128 v[132:135], v187 offset:4096
	ds_read_b128 v[140:143], v191 offset:4096
	s_waitcnt lgkmcnt(4)
	v_mfma_f32_32x32x16_bf16 v[112:127], v[160:163], v[168:171], v[112:127]
	v_mfma_f32_32x32x16_bf16 v[48:63], v[164:167], v[168:171], v[48:63]
	v_mfma_f32_32x32x16_bf16 v[96:111], v[160:163], v[172:175], v[96:111]
	v_mfma_f32_32x32x16_bf16 v[32:47], v[164:167], v[172:175], v[32:47]
	s_waitcnt vmcnt(0) lgkmcnt(0)
	s_barrier
	v_xor_b32_e32 v184, 0x10000, v184
	v_xor_b32_e32 v188, 0x10000, v188
	ds_read_b128 v[160:163], v184
	ds_read_b128 v[168:171], v188
	ds_read_b128 v[164:167], v184 offset:4096
	ds_read_b128 v[172:175], v188 offset:4096
	s_add_u32 s20, s16, 1024
	s_addc_u32 s21, s17, 0
	s_add_u32 s24, s18, 1024
	s_addc_u32 s25, s19, 0
	v_mfma_f32_32x32x16_bf16 v[112:127], v[128:131], v[136:139], v[112:127]
	v_xor_b32_e32 v185, 0x10000, v185
	v_xor_b32_e32 v189, 0x10000, v189
	s_add_u32 m0, s27, 0
	s_nop 0
	global_load_lds_dwordx4 v192, s[20:21]
	v_mfma_f32_32x32x16_bf16 v[48:63], v[132:135], v[136:139], v[48:63]
	v_xor_b32_e32 v186, 0x10000, v186
	v_xor_b32_e32 v190, 0x10000, v190
	s_add_u32 m0, s27, 32768
	s_nop 0
	global_load_lds_dwordx4 v192, s[24:25]
	v_mfma_f32_32x32x16_bf16 v[96:111], v[128:131], v[140:143], v[96:111]
	v_xor_b32_e32 v187, 0x10000, v187
	v_xor_b32_e32 v191, 0x10000, v191
	s_add_u32 m0, s27, 8192
	s_nop 0
	global_load_lds_dwordx4 v194, s[20:21]
	v_mfma_f32_32x32x16_bf16 v[32:47], v[132:135], v[140:143], v[32:47]
	s_add_u32 m0, s27, 40960
	s_nop 0
	global_load_lds_dwordx4 v194, s[24:25]
	s_add_u32 m0, s27, 16384
	s_nop 0
	global_load_lds_dwordx4 v196, s[20:21]
	s_add_u32 m0, s27, 49152
	s_nop 0
	global_load_lds_dwordx4 v196, s[24:25]
	s_add_u32 m0, s27, 24576
	s_nop 0
	global_load_lds_dwordx4 v198, s[20:21]
	s_add_u32 m0, s27, 57344
	s_nop 0
	global_load_lds_dwordx4 v198, s[24:25]
	ds_read_b128 v[128:131], v185
	ds_read_b128 v[136:139], v189
	ds_read_b128 v[132:135], v185 offset:4096
	ds_read_b128 v[140:143], v189 offset:4096
	s_waitcnt lgkmcnt(4)
	v_mfma_f32_32x32x16_bf16 v[112:127], v[160:163], v[168:171], v[112:127]
	v_mfma_f32_32x32x16_bf16 v[48:63], v[164:167], v[168:171], v[48:63]
	v_mfma_f32_32x32x16_bf16 v[96:111], v[160:163], v[172:175], v[96:111]
	v_mfma_f32_32x32x16_bf16 v[32:47], v[164:167], v[172:175], v[32:47]
	ds_read_b128 v[160:163], v186
	ds_read_b128 v[168:171], v190
	ds_read_b128 v[164:167], v186 offset:4096
	ds_read_b128 v[172:175], v190 offset:4096
	s_waitcnt lgkmcnt(4)
	v_mfma_f32_32x32x16_bf16 v[112:127], v[128:131], v[136:139], v[112:127]
	v_mfma_f32_32x32x16_bf16 v[48:63], v[132:135], v[136:139], v[48:63]
	v_mfma_f32_32x32x16_bf16 v[96:111], v[128:131], v[140:143], v[96:111]
	v_mfma_f32_32x32x16_bf16 v[32:47], v[132:135], v[140:143], v[32:47]
	ds_read_b128 v[128:131], v187
	ds_read_b128 v[136:139], v191
	ds_read_b128 v[132:135], v187 offset:4096
	ds_read_b128 v[140:143], v191 offset:4096
	s_waitcnt lgkmcnt(4)
	v_mfma_f32_32x32x16_bf16 v[112:127], v[160:163], v[168:171], v[112:127]
	v_mfma_f32_32x32x16_bf16 v[48:63], v[164:167], v[168:171], v[48:63]
	v_mfma_f32_32x32x16_bf16 v[96:111], v[160:163], v[172:175], v[96:111]
	v_mfma_f32_32x32x16_bf16 v[32:47], v[164:167], v[172:175], v[32:47]
	s_waitcnt vmcnt(0) lgkmcnt(0)
	s_barrier
	v_xor_b32_e32 v184, 0x10000, v184
	v_xor_b32_e32 v188, 0x10000, v188
	ds_read_b128 v[160:163], v184
	ds_read_b128 v[168:171], v188
	ds_read_b128 v[164:167], v184 offset:4096
	ds_read_b128 v[172:175], v188 offset:4096
	s_add_u32 s20, s16, 1152
	s_addc_u32 s21, s17, 0
	s_add_u32 s24, s18, 1152
	s_addc_u32 s25, s19, 0
	v_mfma_f32_32x32x16_bf16 v[112:127], v[128:131], v[136:139], v[112:127]
	v_xor_b32_e32 v185, 0x10000, v185
	v_xor_b32_e32 v189, 0x10000, v189
	s_add_u32 m0, s27, 65536
	s_nop 0
	global_load_lds_dwordx4 v192, s[20:21]
	v_mfma_f32_32x32x16_bf16 v[48:63], v[132:135], v[136:139], v[48:63]
	v_xor_b32_e32 v186, 0x10000, v186
	v_xor_b32_e32 v190, 0x10000, v190
	s_add_u32 m0, s27, 98304
	s_nop 0
	global_load_lds_dwordx4 v192, s[24:25]
	v_mfma_f32_32x32x16_bf16 v[96:111], v[128:131], v[140:143], v[96:111]
	v_xor_b32_e32 v187, 0x10000, v187
	v_xor_b32_e32 v191, 0x10000, v191
	s_add_u32 m0, s27, 73728
	s_nop 0
	global_load_lds_dwordx4 v194, s[20:21]
	v_mfma_f32_32x32x16_bf16 v[32:47], v[132:135], v[140:143], v[32:47]
	s_add_u32 m0, s27, 106496
	s_nop 0
	global_load_lds_dwordx4 v194, s[24:25]
	s_add_u32 m0, s27, 81920
	s_nop 0
	global_load_lds_dwordx4 v196, s[20:21]
	s_add_u32 m0, s27, 114688
	s_nop 0
	global_load_lds_dwordx4 v196, s[24:25]
	s_add_u32 m0, s27, 90112
	s_nop 0
	global_load_lds_dwordx4 v198, s[20:21]
	s_add_u32 m0, s27, 122880
	s_nop 0
	global_load_lds_dwordx4 v198, s[24:25]
	ds_read_b128 v[128:131], v185
	ds_read_b128 v[136:139], v189
	ds_read_b128 v[132:135], v185 offset:4096
	ds_read_b128 v[140:143], v189 offset:4096
	s_waitcnt lgkmcnt(4)
	v_mfma_f32_32x32x16_bf16 v[112:127], v[160:163], v[168:171], v[112:127]
	v_mfma_f32_32x32x16_bf16 v[48:63], v[164:167], v[168:171], v[48:63]
	v_mfma_f32_32x32x16_bf16 v[96:111], v[160:163], v[172:175], v[96:111]
	v_mfma_f32_32x32x16_bf16 v[32:47], v[164:167], v[172:175], v[32:47]
	ds_read_b128 v[160:163], v186
	ds_read_b128 v[168:171], v190
	ds_read_b128 v[164:167], v186 offset:4096
	ds_read_b128 v[172:175], v190 offset:4096
	s_waitcnt lgkmcnt(4)
	v_mfma_f32_32x32x16_bf16 v[112:127], v[128:131], v[136:139], v[112:127]
	v_mfma_f32_32x32x16_bf16 v[48:63], v[132:135], v[136:139], v[48:63]
	v_mfma_f32_32x32x16_bf16 v[96:111], v[128:131], v[140:143], v[96:111]
	v_mfma_f32_32x32x16_bf16 v[32:47], v[132:135], v[140:143], v[32:47]
	ds_read_b128 v[128:131], v187
	ds_read_b128 v[136:139], v191
	ds_read_b128 v[132:135], v187 offset:4096
	ds_read_b128 v[140:143], v191 offset:4096
	s_waitcnt lgkmcnt(4)
	v_mfma_f32_32x32x16_bf16 v[112:127], v[160:163], v[168:171], v[112:127]
	v_mfma_f32_32x32x16_bf16 v[48:63], v[164:167], v[168:171], v[48:63]
	v_mfma_f32_32x32x16_bf16 v[96:111], v[160:163], v[172:175], v[96:111]
	v_mfma_f32_32x32x16_bf16 v[32:47], v[164:167], v[172:175], v[32:47]
	s_waitcnt vmcnt(0) lgkmcnt(0)
	s_barrier
	v_xor_b32_e32 v184, 0x10000, v184
	v_xor_b32_e32 v188, 0x10000, v188
	ds_read_b128 v[160:163], v184
	ds_read_b128 v[168:171], v188
	ds_read_b128 v[164:167], v184 offset:4096
	ds_read_b128 v[172:175], v188 offset:4096
	s_add_u32 s20, s16, 1280
	s_addc_u32 s21, s17, 0
	s_add_u32 s24, s18, 1280
	s_addc_u32 s25, s19, 0
	v_mfma_f32_32x32x16_bf16 v[112:127], v[128:131], v[136:139], v[112:127]
	v_xor_b32_e32 v185, 0x10000, v185
	v_xor_b32_e32 v189, 0x10000, v189
	s_add_u32 m0, s27, 0
	s_nop 0
	global_load_lds_dwordx4 v192, s[20:21]
	v_mfma_f32_32x32x16_bf16 v[48:63], v[132:135], v[136:139], v[48:63]
	v_xor_b32_e32 v186, 0x10000, v186
	v_xor_b32_e32 v190, 0x10000, v190
	s_add_u32 m0, s27, 32768
	s_nop 0
	global_load_lds_dwordx4 v192, s[24:25]
	v_mfma_f32_32x32x16_bf16 v[96:111], v[128:131], v[140:143], v[96:111]
	v_xor_b32_e32 v187, 0x10000, v187
	v_xor_b32_e32 v191, 0x10000, v191
	s_add_u32 m0, s27, 8192
	s_nop 0
	global_load_lds_dwordx4 v194, s[20:21]
	v_mfma_f32_32x32x16_bf16 v[32:47], v[132:135], v[140:143], v[32:47]
	s_add_u32 m0, s27, 40960
	s_nop 0
	global_load_lds_dwordx4 v194, s[24:25]
	s_add_u32 m0, s27, 16384
	s_nop 0
	global_load_lds_dwordx4 v196, s[20:21]
	s_add_u32 m0, s27, 49152
	s_nop 0
	global_load_lds_dwordx4 v196, s[24:25]
	s_add_u32 m0, s27, 24576
	s_nop 0
	global_load_lds_dwordx4 v198, s[20:21]
	s_add_u32 m0, s27, 57344
	s_nop 0
	global_load_lds_dwordx4 v198, s[24:25]
	ds_read_b128 v[128:131], v185
	ds_read_b128 v[136:139], v189
	ds_read_b128 v[132:135], v185 offset:4096
	ds_read_b128 v[140:143], v189 offset:4096
	s_waitcnt lgkmcnt(4)
	v_mfma_f32_32x32x16_bf16 v[112:127], v[160:163], v[168:171], v[112:127]
	v_mfma_f32_32x32x16_bf16 v[48:63], v[164:167], v[168:171], v[48:63]
	v_mfma_f32_32x32x16_bf16 v[96:111], v[160:163], v[172:175], v[96:111]
	v_mfma_f32_32x32x16_bf16 v[32:47], v[164:167], v[172:175], v[32:47]
	ds_read_b128 v[160:163], v186
	ds_read_b128 v[168:171], v190
	ds_read_b128 v[164:167], v186 offset:4096
	ds_read_b128 v[172:175], v190 offset:4096
	s_waitcnt lgkmcnt(4)
	v_mfma_f32_32x32x16_bf16 v[112:127], v[128:131], v[136:139], v[112:127]
	v_mfma_f32_32x32x16_bf16 v[48:63], v[132:135], v[136:139], v[48:63]
	v_mfma_f32_32x32x16_bf16 v[96:111], v[128:131], v[140:143], v[96:111]
	v_mfma_f32_32x32x16_bf16 v[32:47], v[132:135], v[140:143], v[32:47]
	ds_read_b128 v[128:131], v187
	ds_read_b128 v[136:139], v191
	ds_read_b128 v[132:135], v187 offset:4096
	ds_read_b128 v[140:143], v191 offset:4096
	s_waitcnt lgkmcnt(4)
	v_mfma_f32_32x32x16_bf16 v[112:127], v[160:163], v[168:171], v[112:127]
	v_mfma_f32_32x32x16_bf16 v[48:63], v[164:167], v[168:171], v[48:63]
	v_mfma_f32_32x32x16_bf16 v[96:111], v[160:163], v[172:175], v[96:111]
	v_mfma_f32_32x32x16_bf16 v[32:47], v[164:167], v[172:175], v[32:47]
	s_waitcnt vmcnt(0) lgkmcnt(0)
	s_barrier
	v_xor_b32_e32 v184, 0x10000, v184
	v_xor_b32_e32 v188, 0x10000, v188
	ds_read_b128 v[160:163], v184
	ds_read_b128 v[168:171], v188
	ds_read_b128 v[164:167], v184 offset:4096
	ds_read_b128 v[172:175], v188 offset:4096
	s_add_u32 s20, s16, 1408
	s_addc_u32 s21, s17, 0
	s_add_u32 s24, s18, 1408
	s_addc_u32 s25, s19, 0
	v_mfma_f32_32x32x16_bf16 v[112:127], v[128:131], v[136:139], v[112:127]
	v_xor_b32_e32 v185, 0x10000, v185
	v_xor_b32_e32 v189, 0x10000, v189
	s_add_u32 m0, s27, 65536
	s_nop 0
	global_load_lds_dwordx4 v192, s[20:21]
	v_mfma_f32_32x32x16_bf16 v[48:63], v[132:135], v[136:139], v[48:63]
	v_xor_b32_e32 v186, 0x10000, v186
	v_xor_b32_e32 v190, 0x10000, v190
	s_add_u32 m0, s27, 98304
	s_nop 0
	global_load_lds_dwordx4 v192, s[24:25]
	v_mfma_f32_32x32x16_bf16 v[96:111], v[128:131], v[140:143], v[96:111]
	v_xor_b32_e32 v187, 0x10000, v187
	v_xor_b32_e32 v191, 0x10000, v191
	s_add_u32 m0, s27, 73728
	s_nop 0
	global_load_lds_dwordx4 v194, s[20:21]
	v_mfma_f32_32x32x16_bf16 v[32:47], v[132:135], v[140:143], v[32:47]
	s_add_u32 m0, s27, 106496
	s_nop 0
	global_load_lds_dwordx4 v194, s[24:25]
	s_add_u32 m0, s27, 81920
	s_nop 0
	global_load_lds_dwordx4 v196, s[20:21]
	s_add_u32 m0, s27, 114688
	s_nop 0
	global_load_lds_dwordx4 v196, s[24:25]
	s_add_u32 m0, s27, 90112
	s_nop 0
	global_load_lds_dwordx4 v198, s[20:21]
	s_add_u32 m0, s27, 122880
	s_nop 0
	global_load_lds_dwordx4 v198, s[24:25]
	ds_read_b128 v[128:131], v185
	ds_read_b128 v[136:139], v189
	ds_read_b128 v[132:135], v185 offset:4096
	ds_read_b128 v[140:143], v189 offset:4096
	s_waitcnt lgkmcnt(4)
	v_mfma_f32_32x32x16_bf16 v[112:127], v[160:163], v[168:171], v[112:127]
	v_mfma_f32_32x32x16_bf16 v[48:63], v[164:167], v[168:171], v[48:63]
	v_mfma_f32_32x32x16_bf16 v[96:111], v[160:163], v[172:175], v[96:111]
	v_mfma_f32_32x32x16_bf16 v[32:47], v[164:167], v[172:175], v[32:47]
	ds_read_b128 v[160:163], v186
	ds_read_b128 v[168:171], v190
	ds_read_b128 v[164:167], v186 offset:4096
	ds_read_b128 v[172:175], v190 offset:4096
	s_waitcnt lgkmcnt(4)
	v_mfma_f32_32x32x16_bf16 v[112:127], v[128:131], v[136:139], v[112:127]
	v_mfma_f32_32x32x16_bf16 v[48:63], v[132:135], v[136:139], v[48:63]
	v_mfma_f32_32x32x16_bf16 v[96:111], v[128:131], v[140:143], v[96:111]
	v_mfma_f32_32x32x16_bf16 v[32:47], v[132:135], v[140:143], v[32:47]
	ds_read_b128 v[128:131], v187
	ds_read_b128 v[136:139], v191
	ds_read_b128 v[132:135], v187 offset:4096
	ds_read_b128 v[140:143], v191 offset:4096
	s_waitcnt lgkmcnt(4)
	v_mfma_f32_32x32x16_bf16 v[112:127], v[160:163], v[168:171], v[112:127]
	v_mfma_f32_32x32x16_bf16 v[48:63], v[164:167], v[168:171], v[48:63]
	v_mfma_f32_32x32x16_bf16 v[96:111], v[160:163], v[172:175], v[96:111]
	v_mfma_f32_32x32x16_bf16 v[32:47], v[164:167], v[172:175], v[32:47]
	s_waitcnt vmcnt(0) lgkmcnt(0)
	s_barrier
	v_xor_b32_e32 v184, 0x10000, v184
	v_xor_b32_e32 v188, 0x10000, v188
	ds_read_b128 v[160:163], v184
	ds_read_b128 v[168:171], v188
	ds_read_b128 v[164:167], v184 offset:4096
	ds_read_b128 v[172:175], v188 offset:4096
	s_add_u32 s20, s16, 1536
	s_addc_u32 s21, s17, 0
	s_add_u32 s24, s18, 1536
	s_addc_u32 s25, s19, 0
	v_mfma_f32_32x32x16_bf16 v[112:127], v[128:131], v[136:139], v[112:127]
	v_xor_b32_e32 v185, 0x10000, v185
	v_xor_b32_e32 v189, 0x10000, v189
	s_add_u32 m0, s27, 0
	s_nop 0
	global_load_lds_dwordx4 v192, s[20:21]
	v_mfma_f32_32x32x16_bf16 v[48:63], v[132:135], v[136:139], v[48:63]
	v_xor_b32_e32 v186, 0x10000, v186
	v_xor_b32_e32 v190, 0x10000, v190
	s_add_u32 m0, s27, 32768
	s_nop 0
	global_load_lds_dwordx4 v192, s[24:25]
	v_mfma_f32_32x32x16_bf16 v[96:111], v[128:131], v[140:143], v[96:111]
	v_xor_b32_e32 v187, 0x10000, v187
	v_xor_b32_e32 v191, 0x10000, v191
	s_add_u32 m0, s27, 8192
	s_nop 0
	global_load_lds_dwordx4 v194, s[20:21]
	v_mfma_f32_32x32x16_bf16 v[32:47], v[132:135], v[140:143], v[32:47]
	s_add_u32 m0, s27, 40960
	s_nop 0
	global_load_lds_dwordx4 v194, s[24:25]
	s_add_u32 m0, s27, 16384
	s_nop 0
	global_load_lds_dwordx4 v196, s[20:21]
	s_add_u32 m0, s27, 49152
	s_nop 0
	global_load_lds_dwordx4 v196, s[24:25]
	s_add_u32 m0, s27, 24576
	s_nop 0
	global_load_lds_dwordx4 v198, s[20:21]
	s_add_u32 m0, s27, 57344
	s_nop 0
	global_load_lds_dwordx4 v198, s[24:25]
	ds_read_b128 v[128:131], v185
	ds_read_b128 v[136:139], v189
	ds_read_b128 v[132:135], v185 offset:4096
	ds_read_b128 v[140:143], v189 offset:4096
	s_waitcnt lgkmcnt(4)
	v_mfma_f32_32x32x16_bf16 v[112:127], v[160:163], v[168:171], v[112:127]
	v_mfma_f32_32x32x16_bf16 v[48:63], v[164:167], v[168:171], v[48:63]
	v_mfma_f32_32x32x16_bf16 v[96:111], v[160:163], v[172:175], v[96:111]
	v_mfma_f32_32x32x16_bf16 v[32:47], v[164:167], v[172:175], v[32:47]
	ds_read_b128 v[160:163], v186
	ds_read_b128 v[168:171], v190
	ds_read_b128 v[164:167], v186 offset:4096
	ds_read_b128 v[172:175], v190 offset:4096
	s_waitcnt lgkmcnt(4)
	v_mfma_f32_32x32x16_bf16 v[112:127], v[128:131], v[136:139], v[112:127]
	v_mfma_f32_32x32x16_bf16 v[48:63], v[132:135], v[136:139], v[48:63]
	v_mfma_f32_32x32x16_bf16 v[96:111], v[128:131], v[140:143], v[96:111]
	v_mfma_f32_32x32x16_bf16 v[32:47], v[132:135], v[140:143], v[32:47]
	ds_read_b128 v[128:131], v187
	ds_read_b128 v[136:139], v191
	ds_read_b128 v[132:135], v187 offset:4096
	ds_read_b128 v[140:143], v191 offset:4096
	s_waitcnt lgkmcnt(4)
	v_mfma_f32_32x32x16_bf16 v[112:127], v[160:163], v[168:171], v[112:127]
	v_mfma_f32_32x32x16_bf16 v[48:63], v[164:167], v[168:171], v[48:63]
	v_mfma_f32_32x32x16_bf16 v[96:111], v[160:163], v[172:175], v[96:111]
	v_mfma_f32_32x32x16_bf16 v[32:47], v[164:167], v[172:175], v[32:47]
	s_waitcnt vmcnt(0) lgkmcnt(0)
	s_barrier
	v_xor_b32_e32 v184, 0x10000, v184
	v_xor_b32_e32 v188, 0x10000, v188
	ds_read_b128 v[160:163], v184
	ds_read_b128 v[168:171], v188
	ds_read_b128 v[164:167], v184 offset:4096
	ds_read_b128 v[172:175], v188 offset:4096
	s_add_u32 s20, s16, 1664
	s_addc_u32 s21, s17, 0
	s_add_u32 s24, s18, 1664
	s_addc_u32 s25, s19, 0
	v_mfma_f32_32x32x16_bf16 v[112:127], v[128:131], v[136:139], v[112:127]
	v_xor_b32_e32 v185, 0x10000, v185
	v_xor_b32_e32 v189, 0x10000, v189
	s_add_u32 m0, s27, 65536
	s_nop 0
	global_load_lds_dwordx4 v192, s[20:21]
	v_mfma_f32_32x32x16_bf16 v[48:63], v[132:135], v[136:139], v[48:63]
	v_xor_b32_e32 v186, 0x10000, v186
	v_xor_b32_e32 v190, 0x10000, v190
	s_add_u32 m0, s27, 98304
	s_nop 0
	global_load_lds_dwordx4 v192, s[24:25]
	v_mfma_f32_32x32x16_bf16 v[96:111], v[128:131], v[140:143], v[96:111]
	v_xor_b32_e32 v187, 0x10000, v187
	v_xor_b32_e32 v191, 0x10000, v191
	s_add_u32 m0, s27, 73728
	s_nop 0
	global_load_lds_dwordx4 v194, s[20:21]
	v_mfma_f32_32x32x16_bf16 v[32:47], v[132:135], v[140:143], v[32:47]
	s_add_u32 m0, s27, 106496
	s_nop 0
	global_load_lds_dwordx4 v194, s[24:25]
	s_add_u32 m0, s27, 81920
	s_nop 0
	global_load_lds_dwordx4 v196, s[20:21]
	s_add_u32 m0, s27, 114688
	s_nop 0
	global_load_lds_dwordx4 v196, s[24:25]
	s_add_u32 m0, s27, 90112
	s_nop 0
	global_load_lds_dwordx4 v198, s[20:21]
	s_add_u32 m0, s27, 122880
	s_nop 0
	global_load_lds_dwordx4 v198, s[24:25]
	ds_read_b128 v[128:131], v185
	ds_read_b128 v[136:139], v189
	ds_read_b128 v[132:135], v185 offset:4096
	ds_read_b128 v[140:143], v189 offset:4096
	s_waitcnt lgkmcnt(4)
	v_mfma_f32_32x32x16_bf16 v[112:127], v[160:163], v[168:171], v[112:127]
	v_mfma_f32_32x32x16_bf16 v[48:63], v[164:167], v[168:171], v[48:63]
	v_mfma_f32_32x32x16_bf16 v[96:111], v[160:163], v[172:175], v[96:111]
	v_mfma_f32_32x32x16_bf16 v[32:47], v[164:167], v[172:175], v[32:47]
	ds_read_b128 v[160:163], v186
	ds_read_b128 v[168:171], v190
	ds_read_b128 v[164:167], v186 offset:4096
	ds_read_b128 v[172:175], v190 offset:4096
	s_waitcnt lgkmcnt(4)
	v_mfma_f32_32x32x16_bf16 v[112:127], v[128:131], v[136:139], v[112:127]
	v_mfma_f32_32x32x16_bf16 v[48:63], v[132:135], v[136:139], v[48:63]
	v_mfma_f32_32x32x16_bf16 v[96:111], v[128:131], v[140:143], v[96:111]
	v_mfma_f32_32x32x16_bf16 v[32:47], v[132:135], v[140:143], v[32:47]
	ds_read_b128 v[128:131], v187
	ds_read_b128 v[136:139], v191
	ds_read_b128 v[132:135], v187 offset:4096
	ds_read_b128 v[140:143], v191 offset:4096
	s_waitcnt lgkmcnt(4)
	v_mfma_f32_32x32x16_bf16 v[112:127], v[160:163], v[168:171], v[112:127]
	v_mfma_f32_32x32x16_bf16 v[48:63], v[164:167], v[168:171], v[48:63]
	v_mfma_f32_32x32x16_bf16 v[96:111], v[160:163], v[172:175], v[96:111]
	v_mfma_f32_32x32x16_bf16 v[32:47], v[164:167], v[172:175], v[32:47]
	s_waitcnt vmcnt(0) lgkmcnt(0)
	s_barrier
	v_xor_b32_e32 v184, 0x10000, v184
	v_xor_b32_e32 v188, 0x10000, v188
	ds_read_b128 v[160:163], v184
	ds_read_b128 v[168:171], v188
	ds_read_b128 v[164:167], v184 offset:4096
	ds_read_b128 v[172:175], v188 offset:4096
	s_add_u32 s20, s16, 1792
	s_addc_u32 s21, s17, 0
	s_add_u32 s24, s18, 1792
	s_addc_u32 s25, s19, 0
	v_mfma_f32_32x32x16_bf16 v[112:127], v[128:131], v[136:139], v[112:127]
	v_xor_b32_e32 v185, 0x10000, v185
	v_xor_b32_e32 v189, 0x10000, v189
	s_add_u32 m0, s27, 0
	s_nop 0
	global_load_lds_dwordx4 v192, s[20:21]
	v_mfma_f32_32x32x16_bf16 v[48:63], v[132:135], v[136:139], v[48:63]
	v_xor_b32_e32 v186, 0x10000, v186
	v_xor_b32_e32 v190, 0x10000, v190
	s_add_u32 m0, s27, 32768
	s_nop 0
	global_load_lds_dwordx4 v192, s[24:25]
	v_mfma_f32_32x32x16_bf16 v[96:111], v[128:131], v[140:143], v[96:111]
	v_xor_b32_e32 v187, 0x10000, v187
	v_xor_b32_e32 v191, 0x10000, v191
	s_add_u32 m0, s27, 8192
	s_nop 0
	global_load_lds_dwordx4 v194, s[20:21]
	v_mfma_f32_32x32x16_bf16 v[32:47], v[132:135], v[140:143], v[32:47]
	s_add_u32 m0, s27, 40960
	s_nop 0
	global_load_lds_dwordx4 v194, s[24:25]
	s_add_u32 m0, s27, 16384
	s_nop 0
	global_load_lds_dwordx4 v196, s[20:21]
	s_add_u32 m0, s27, 49152
	s_nop 0
	global_load_lds_dwordx4 v196, s[24:25]
	s_add_u32 m0, s27, 24576
	s_nop 0
	global_load_lds_dwordx4 v198, s[20:21]
	s_add_u32 m0, s27, 57344
	s_nop 0
	global_load_lds_dwordx4 v198, s[24:25]
	ds_read_b128 v[128:131], v185
	ds_read_b128 v[136:139], v189
	ds_read_b128 v[132:135], v185 offset:4096
	ds_read_b128 v[140:143], v189 offset:4096
	s_waitcnt lgkmcnt(4)
	v_mfma_f32_32x32x16_bf16 v[112:127], v[160:163], v[168:171], v[112:127]
	v_mfma_f32_32x32x16_bf16 v[48:63], v[164:167], v[168:171], v[48:63]
	v_mfma_f32_32x32x16_bf16 v[96:111], v[160:163], v[172:175], v[96:111]
	v_mfma_f32_32x32x16_bf16 v[32:47], v[164:167], v[172:175], v[32:47]
	ds_read_b128 v[160:163], v186
	ds_read_b128 v[168:171], v190
	ds_read_b128 v[164:167], v186 offset:4096
	ds_read_b128 v[172:175], v190 offset:4096
	s_waitcnt lgkmcnt(4)
	v_mfma_f32_32x32x16_bf16 v[112:127], v[128:131], v[136:139], v[112:127]
	v_mfma_f32_32x32x16_bf16 v[48:63], v[132:135], v[136:139], v[48:63]
	v_mfma_f32_32x32x16_bf16 v[96:111], v[128:131], v[140:143], v[96:111]
	v_mfma_f32_32x32x16_bf16 v[32:47], v[132:135], v[140:143], v[32:47]
	ds_read_b128 v[128:131], v187
	ds_read_b128 v[136:139], v191
	ds_read_b128 v[132:135], v187 offset:4096
	ds_read_b128 v[140:143], v191 offset:4096
	s_waitcnt lgkmcnt(4)
	v_mfma_f32_32x32x16_bf16 v[112:127], v[160:163], v[168:171], v[112:127]
	v_mfma_f32_32x32x16_bf16 v[48:63], v[164:167], v[168:171], v[48:63]
	v_mfma_f32_32x32x16_bf16 v[96:111], v[160:163], v[172:175], v[96:111]
	v_mfma_f32_32x32x16_bf16 v[32:47], v[164:167], v[172:175], v[32:47]
	s_waitcnt vmcnt(0) lgkmcnt(0)
	s_barrier
	v_xor_b32_e32 v184, 0x10000, v184
	v_xor_b32_e32 v188, 0x10000, v188
	ds_read_b128 v[160:163], v184
	ds_read_b128 v[168:171], v188
	ds_read_b128 v[164:167], v184 offset:4096
	ds_read_b128 v[172:175], v188 offset:4096
	s_add_u32 s20, s16, 1920
	s_addc_u32 s21, s17, 0
	s_add_u32 s24, s18, 1920
	s_addc_u32 s25, s19, 0
	v_mfma_f32_32x32x16_bf16 v[112:127], v[128:131], v[136:139], v[112:127]
	v_xor_b32_e32 v185, 0x10000, v185
	v_xor_b32_e32 v189, 0x10000, v189
	s_add_u32 m0, s27, 65536
	s_nop 0
	global_load_lds_dwordx4 v192, s[20:21]
	v_mfma_f32_32x32x16_bf16 v[48:63], v[132:135], v[136:139], v[48:63]
	v_xor_b32_e32 v186, 0x10000, v186
	v_xor_b32_e32 v190, 0x10000, v190
	s_add_u32 m0, s27, 98304
	s_nop 0
	global_load_lds_dwordx4 v192, s[24:25]
	v_mfma_f32_32x32x16_bf16 v[96:111], v[128:131], v[140:143], v[96:111]
	v_xor_b32_e32 v187, 0x10000, v187
	v_xor_b32_e32 v191, 0x10000, v191
	s_add_u32 m0, s27, 73728
	s_nop 0
	global_load_lds_dwordx4 v194, s[20:21]
	v_mfma_f32_32x32x16_bf16 v[32:47], v[132:135], v[140:143], v[32:47]
	s_add_u32 m0, s27, 106496
	s_nop 0
	global_load_lds_dwordx4 v194, s[24:25]
	s_add_u32 m0, s27, 81920
	s_nop 0
	global_load_lds_dwordx4 v196, s[20:21]
	s_add_u32 m0, s27, 114688
	s_nop 0
	global_load_lds_dwordx4 v196, s[24:25]
	s_add_u32 m0, s27, 90112
	s_nop 0
	global_load_lds_dwordx4 v198, s[20:21]
	s_add_u32 m0, s27, 122880
	s_nop 0
	global_load_lds_dwordx4 v198, s[24:25]
	ds_read_b128 v[128:131], v185
	ds_read_b128 v[136:139], v189
	ds_read_b128 v[132:135], v185 offset:4096
	ds_read_b128 v[140:143], v189 offset:4096
	s_waitcnt lgkmcnt(4)
	v_mfma_f32_32x32x16_bf16 v[112:127], v[160:163], v[168:171], v[112:127]
	v_mfma_f32_32x32x16_bf16 v[48:63], v[164:167], v[168:171], v[48:63]
	v_mfma_f32_32x32x16_bf16 v[96:111], v[160:163], v[172:175], v[96:111]
	v_mfma_f32_32x32x16_bf16 v[32:47], v[164:167], v[172:175], v[32:47]
	ds_read_b128 v[160:163], v186
	ds_read_b128 v[168:171], v190
	ds_read_b128 v[164:167], v186 offset:4096
	ds_read_b128 v[172:175], v190 offset:4096
	s_waitcnt lgkmcnt(4)
	v_mfma_f32_32x32x16_bf16 v[112:127], v[128:131], v[136:139], v[112:127]
	v_mfma_f32_32x32x16_bf16 v[48:63], v[132:135], v[136:139], v[48:63]
	v_mfma_f32_32x32x16_bf16 v[96:111], v[128:131], v[140:143], v[96:111]
	v_mfma_f32_32x32x16_bf16 v[32:47], v[132:135], v[140:143], v[32:47]
	ds_read_b128 v[128:131], v187
	ds_read_b128 v[136:139], v191
	ds_read_b128 v[132:135], v187 offset:4096
	ds_read_b128 v[140:143], v191 offset:4096
	s_waitcnt lgkmcnt(4)
	v_mfma_f32_32x32x16_bf16 v[112:127], v[160:163], v[168:171], v[112:127]
	v_mfma_f32_32x32x16_bf16 v[48:63], v[164:167], v[168:171], v[48:63]
	v_mfma_f32_32x32x16_bf16 v[96:111], v[160:163], v[172:175], v[96:111]
	v_mfma_f32_32x32x16_bf16 v[32:47], v[164:167], v[172:175], v[32:47]
	s_waitcnt vmcnt(0) lgkmcnt(0)
	s_barrier
	v_xor_b32_e32 v184, 0x10000, v184
	v_xor_b32_e32 v188, 0x10000, v188
	ds_read_b128 v[160:163], v184
	ds_read_b128 v[168:171], v188
	ds_read_b128 v[164:167], v184 offset:4096
	ds_read_b128 v[172:175], v188 offset:4096
	s_add_u32 s37, s30, s42
	s_cmpk_ge_u32 s37, 0x780
	s_cbranch_scc1 .Lip11_lc_nonext
	s_mul_hi_u32 s38, s37, 0x92492493
	s_lshr_b32 s38, s38, 3
	s_mul_i32 s39, s38, 14
	s_sub_u32 s39, s37, s39
	s_sub_u32 s98, s37, 0x700
	s_cmpk_lt_u32 s37, 0x700
	s_cselect_b32 s39, s39, 14
	s_cselect_b32 s38, s38, s98
	s_lshl_b32 s98, s38, 19
	s_add_u32 s16, s4, s98
	s_addc_u32 s17, s5, 0
	s_lshl_b32 s98, s39, 19
	s_add_u32 s18, s6, s98
	s_addc_u32 s19, s7, 0
	v_mfma_f32_32x32x16_bf16 v[112:127], v[128:131], v[136:139], v[112:127]
	v_xor_b32_e32 v185, 0x10000, v185
	v_xor_b32_e32 v189, 0x10000, v189
	s_add_u32 m0, s27, 0
	s_nop 0
	global_load_lds_dwordx4 v192, s[16:17]
	v_mfma_f32_32x32x16_bf16 v[48:63], v[132:135], v[136:139], v[48:63]
	v_xor_b32_e32 v186, 0x10000, v186
	v_xor_b32_e32 v190, 0x10000, v190
	s_add_u32 m0, s27, 32768
	s_nop 0
	global_load_lds_dwordx4 v192, s[18:19]
	v_mfma_f32_32x32x16_bf16 v[96:111], v[128:131], v[140:143], v[96:111]
	v_xor_b32_e32 v187, 0x10000, v187
	v_xor_b32_e32 v191, 0x10000, v191
	s_add_u32 m0, s27, 8192
	s_nop 0
	global_load_lds_dwordx4 v194, s[16:17]
	v_mfma_f32_32x32x16_bf16 v[32:47], v[132:135], v[140:143], v[32:47]
	s_add_u32 m0, s27, 40960
	s_nop 0
	global_load_lds_dwordx4 v194, s[18:19]
	s_add_u32 m0, s27, 16384
	s_nop 0
	global_load_lds_dwordx4 v196, s[16:17]
	s_add_u32 m0, s27, 49152
	s_nop 0
	global_load_lds_dwordx4 v196, s[18:19]
	s_add_u32 m0, s27, 24576
	s_nop 0
	global_load_lds_dwordx4 v198, s[16:17]
	s_add_u32 m0, s27, 57344
	s_nop 0
	global_load_lds_dwordx4 v198, s[18:19]
	s_branch .Lip11_lc_join

.Lip11_lload:
	s_waitcnt vmcnt(0) lgkmcnt(0)
	s_barrier
	s_add_u32 s20, s16, 256
	s_addc_u32 s21, s17, 0
	s_add_u32 s24, s18, 256
	s_addc_u32 s25, s19, 0
	s_add_u32 m0, s27, 0
	s_nop 0
	global_load_lds_dwordx4 v192, s[20:21]
	s_add_u32 m0, s27, 32768
	s_nop 0
	global_load_lds_dwordx4 v192, s[24:25]
	s_add_u32 m0, s27, 8192
	s_nop 0
	global_load_lds_dwordx4 v194, s[20:21]
	s_add_u32 m0, s27, 40960
	s_nop 0
	global_load_lds_dwordx4 v194, s[24:25]
	s_add_u32 m0, s27, 16384
	s_nop 0
	global_load_lds_dwordx4 v196, s[20:21]
	s_add_u32 m0, s27, 49152
	s_nop 0
	global_load_lds_dwordx4 v196, s[24:25]
	s_add_u32 m0, s27, 24576
	s_nop 0
	global_load_lds_dwordx4 v198, s[20:21]
	s_add_u32 m0, s27, 57344
	s_nop 0
	global_load_lds_dwordx4 v198, s[24:25]
	s_waitcnt vmcnt(0) lgkmcnt(0)
	s_barrier
	s_add_u32 s20, s16, 384
	s_addc_u32 s21, s17, 0
	s_add_u32 s24, s18, 384
	s_addc_u32 s25, s19, 0
	s_add_u32 m0, s27, 65536
	s_nop 0
	global_load_lds_dwordx4 v192, s[20:21]
	s_add_u32 m0, s27, 98304
	s_nop 0
	global_load_lds_dwordx4 v192, s[24:25]
	s_add_u32 m0, s27, 73728
	s_nop 0
	global_load_lds_dwordx4 v194, s[20:21]
	s_add_u32 m0, s27, 106496
	s_nop 0
	global_load_lds_dwordx4 v194, s[24:25]
	s_add_u32 m0, s27, 81920
	s_nop 0
	global_load_lds_dwordx4 v196, s[20:21]
	s_add_u32 m0, s27, 114688
	s_nop 0
	global_load_lds_dwordx4 v196, s[24:25]
	s_add_u32 m0, s27, 90112
	s_nop 0
	global_load_lds_dwordx4 v198, s[20:21]
	s_add_u32 m0, s27, 122880
	s_nop 0
	global_load_lds_dwordx4 v198, s[24:25]
	s_waitcnt vmcnt(0) lgkmcnt(0)
	s_barrier
	s_add_u32 s20, s16, 512
	s_addc_u32 s21, s17, 0
	s_add_u32 s24, s18, 512
	s_addc_u32 s25, s19, 0
	s_add_u32 m0, s27, 0
	s_nop 0
	global_load_lds_dwordx4 v192, s[20:21]
	s_add_u32 m0, s27, 32768
	s_nop 0
	global_load_lds_dwordx4 v192, s[24:25]
	s_add_u32 m0, s27, 8192
	s_nop 0
	global_load_lds_dwordx4 v194, s[20:21]
	s_add_u32 m0, s27, 40960
	s_nop 0
	global_load_lds_dwordx4 v194, s[24:25]
	s_add_u32 m0, s27, 16384
	s_nop 0
	global_load_lds_dwordx4 v196, s[20:21]
	s_add_u32 m0, s27, 49152
	s_nop 0
	global_load_lds_dwordx4 v196, s[24:25]
	s_add_u32 m0, s27, 24576
	s_nop 0
	global_load_lds_dwordx4 v198, s[20:21]
	s_add_u32 m0, s27, 57344
	s_nop 0
	global_load_lds_dwordx4 v198, s[24:25]
	s_waitcnt vmcnt(0) lgkmcnt(0)
	s_barrier
	s_add_u32 s20, s16, 640
	s_addc_u32 s21, s17, 0
	s_add_u32 s24, s18, 640
	s_addc_u32 s25, s19, 0
	s_add_u32 m0, s27, 65536
	s_nop 0
	global_load_lds_dwordx4 v192, s[20:21]
	s_add_u32 m0, s27, 98304
	s_nop 0
	global_load_lds_dwordx4 v192, s[24:25]
	s_add_u32 m0, s27, 73728
	s_nop 0
	global_load_lds_dwordx4 v194, s[20:21]
	s_add_u32 m0, s27, 106496
	s_nop 0
	global_load_lds_dwordx4 v194, s[24:25]
	s_add_u32 m0, s27, 81920
	s_nop 0
	global_load_lds_dwordx4 v196, s[20:21]
	s_add_u32 m0, s27, 114688
	s_nop 0
	global_load_lds_dwordx4 v196, s[24:25]
	s_add_u32 m0, s27, 90112
	s_nop 0
	global_load_lds_dwordx4 v198, s[20:21]
	s_add_u32 m0, s27, 122880
	s_nop 0
	global_load_lds_dwordx4 v198, s[24:25]
	s_waitcnt vmcnt(0) lgkmcnt(0)
	s_barrier
	s_add_u32 s20, s16, 768
	s_addc_u32 s21, s17, 0
	s_add_u32 s24, s18, 768
	s_addc_u32 s25, s19, 0
	s_add_u32 m0, s27, 0
	s_nop 0
	global_load_lds_dwordx4 v192, s[20:21]
	s_add_u32 m0, s27, 32768
	s_nop 0
	global_load_lds_dwordx4 v192, s[24:25]
	s_add_u32 m0, s27, 8192
	s_nop 0
	global_load_lds_dwordx4 v194, s[20:21]
	s_add_u32 m0, s27, 40960
	s_nop 0
	global_load_lds_dwordx4 v194, s[24:25]
	s_add_u32 m0, s27, 16384
	s_nop 0
	global_load_lds_dwordx4 v196, s[20:21]
	s_add_u32 m0, s27, 49152
	s_nop 0
	global_load_lds_dwordx4 v196, s[24:25]
	s_add_u32 m0, s27, 24576
	s_nop 0
	global_load_lds_dwordx4 v198, s[20:21]
	s_add_u32 m0, s27, 57344
	s_nop 0
	global_load_lds_dwordx4 v198, s[24:25]
	s_waitcnt vmcnt(0) lgkmcnt(0)
	s_barrier
	s_add_u32 s20, s16, 896
	s_addc_u32 s21, s17, 0
	s_add_u32 s24, s18, 896
	s_addc_u32 s25, s19, 0
	s_add_u32 m0, s27, 65536
	s_nop 0
	global_load_lds_dwordx4 v192, s[20:21]
	s_add_u32 m0, s27, 98304
	s_nop 0
	global_load_lds_dwordx4 v192, s[24:25]
	s_add_u32 m0, s27, 73728
	s_nop 0
	global_load_lds_dwordx4 v194, s[20:21]
	s_add_u32 m0, s27, 106496
	s_nop 0
	global_load_lds_dwordx4 v194, s[24:25]
	s_add_u32 m0, s27, 81920
	s_nop 0
	global_load_lds_dwordx4 v196, s[20:21]
	s_add_u32 m0, s27, 114688
	s_nop 0
	global_load_lds_dwordx4 v196, s[24:25]
	s_add_u32 m0, s27, 90112
	s_nop 0
	global_load_lds_dwordx4 v198, s[20:21]
	s_add_u32 m0, s27, 122880
	s_nop 0
	global_load_lds_dwordx4 v198, s[24:25]
	s_waitcnt vmcnt(0) lgkmcnt(0)
	s_barrier
	s_add_u32 s20, s16, 1024
	s_addc_u32 s21, s17, 0
	s_add_u32 s24, s18, 1024
	s_addc_u32 s25, s19, 0
	s_add_u32 m0, s27, 0
	s_nop 0
	global_load_lds_dwordx4 v192, s[20:21]
	s_add_u32 m0, s27, 32768
	s_nop 0
	global_load_lds_dwordx4 v192, s[24:25]
	s_add_u32 m0, s27, 8192
	s_nop 0
	global_load_lds_dwordx4 v194, s[20:21]
	s_add_u32 m0, s27, 40960
	s_nop 0
	global_load_lds_dwordx4 v194, s[24:25]
	s_add_u32 m0, s27, 16384
	s_nop 0
	global_load_lds_dwordx4 v196, s[20:21]
	s_add_u32 m0, s27, 49152
	s_nop 0
	global_load_lds_dwordx4 v196, s[24:25]
	s_add_u32 m0, s27, 24576
	s_nop 0
	global_load_lds_dwordx4 v198, s[20:21]
	s_add_u32 m0, s27, 57344
	s_nop 0
	global_load_lds_dwordx4 v198, s[24:25]
	s_waitcnt vmcnt(0) lgkmcnt(0)
	s_barrier
	s_add_u32 s20, s16, 1152
	s_addc_u32 s21, s17, 0
	s_add_u32 s24, s18, 1152
	s_addc_u32 s25, s19, 0
	s_add_u32 m0, s27, 65536
	s_nop 0
	global_load_lds_dwordx4 v192, s[20:21]
	s_add_u32 m0, s27, 98304
	s_nop 0
	global_load_lds_dwordx4 v192, s[24:25]
	s_add_u32 m0, s27, 73728
	s_nop 0
	global_load_lds_dwordx4 v194, s[20:21]
	s_add_u32 m0, s27, 106496
	s_nop 0
	global_load_lds_dwordx4 v194, s[24:25]
	s_add_u32 m0, s27, 81920
	s_nop 0
	global_load_lds_dwordx4 v196, s[20:21]
	s_add_u32 m0, s27, 114688
	s_nop 0
	global_load_lds_dwordx4 v196, s[24:25]
	s_add_u32 m0, s27, 90112
	s_nop 0
	global_load_lds_dwordx4 v198, s[20:21]
	s_add_u32 m0, s27, 122880
	s_nop 0
	global_load_lds_dwordx4 v198, s[24:25]
	s_waitcnt vmcnt(0) lgkmcnt(0)
	s_barrier
	s_add_u32 s20, s16, 1280
	s_addc_u32 s21, s17, 0
	s_add_u32 s24, s18, 1280
	s_addc_u32 s25, s19, 0
	s_add_u32 m0, s27, 0
	s_nop 0
	global_load_lds_dwordx4 v192, s[20:21]
	s_add_u32 m0, s27, 32768
	s_nop 0
	global_load_lds_dwordx4 v192, s[24:25]
	s_add_u32 m0, s27, 8192
	s_nop 0
	global_load_lds_dwordx4 v194, s[20:21]
	s_add_u32 m0, s27, 40960
	s_nop 0
	global_load_lds_dwordx4 v194, s[24:25]
	s_add_u32 m0, s27, 16384
	s_nop 0
	global_load_lds_dwordx4 v196, s[20:21]
	s_add_u32 m0, s27, 49152
	s_nop 0
	global_load_lds_dwordx4 v196, s[24:25]
	s_add_u32 m0, s27, 24576
	s_nop 0
	global_load_lds_dwordx4 v198, s[20:21]
	s_add_u32 m0, s27, 57344
	s_nop 0
	global_load_lds_dwordx4 v198, s[24:25]
	s_waitcnt vmcnt(0) lgkmcnt(0)
	s_barrier
	s_add_u32 s20, s16, 1408
	s_addc_u32 s21, s17, 0
	s_add_u32 s24, s18, 1408
	s_addc_u32 s25, s19, 0
	s_add_u32 m0, s27, 65536
	s_nop 0
	global_load_lds_dwordx4 v192, s[20:21]
	s_add_u32 m0, s27, 98304
	s_nop 0
	global_load_lds_dwordx4 v192, s[24:25]
	s_add_u32 m0, s27, 73728
	s_nop 0
	global_load_lds_dwordx4 v194, s[20:21]
	s_add_u32 m0, s27, 106496
	s_nop 0
	global_load_lds_dwordx4 v194, s[24:25]
	s_add_u32 m0, s27, 81920
	s_nop 0
	global_load_lds_dwordx4 v196, s[20:21]
	s_add_u32 m0, s27, 114688
	s_nop 0
	global_load_lds_dwordx4 v196, s[24:25]
	s_add_u32 m0, s27, 90112
	s_nop 0
	global_load_lds_dwordx4 v198, s[20:21]
	s_add_u32 m0, s27, 122880
	s_nop 0
	global_load_lds_dwordx4 v198, s[24:25]
	s_waitcnt vmcnt(0) lgkmcnt(0)
	s_barrier
	s_add_u32 s20, s16, 1536
	s_addc_u32 s21, s17, 0
	s_add_u32 s24, s18, 1536
	s_addc_u32 s25, s19, 0
	s_add_u32 m0, s27, 0
	s_nop 0
	global_load_lds_dwordx4 v192, s[20:21]
	s_add_u32 m0, s27, 32768
	s_nop 0
	global_load_lds_dwordx4 v192, s[24:25]
	s_add_u32 m0, s27, 8192
	s_nop 0
	global_load_lds_dwordx4 v194, s[20:21]
	s_add_u32 m0, s27, 40960
	s_nop 0
	global_load_lds_dwordx4 v194, s[24:25]
	s_add_u32 m0, s27, 16384
	s_nop 0
	global_load_lds_dwordx4 v196, s[20:21]
	s_add_u32 m0, s27, 49152
	s_nop 0
	global_load_lds_dwordx4 v196, s[24:25]
	s_add_u32 m0, s27, 24576
	s_nop 0
	global_load_lds_dwordx4 v198, s[20:21]
	s_add_u32 m0, s27, 57344
	s_nop 0
	global_load_lds_dwordx4 v198, s[24:25]
	s_waitcnt vmcnt(0) lgkmcnt(0)
	s_barrier
	s_add_u32 s20, s16, 1664
	s_addc_u32 s21, s17, 0
	s_add_u32 s24, s18, 1664
	s_addc_u32 s25, s19, 0
	s_add_u32 m0, s27, 65536
	s_nop 0
	global_load_lds_dwordx4 v192, s[20:21]
	s_add_u32 m0, s27, 98304
	s_nop 0
	global_load_lds_dwordx4 v192, s[24:25]
	s_add_u32 m0, s27, 73728
	s_nop 0
	global_load_lds_dwordx4 v194, s[20:21]
	s_add_u32 m0, s27, 106496
	s_nop 0
	global_load_lds_dwordx4 v194, s[24:25]
	s_add_u32 m0, s27, 81920
	s_nop 0
	global_load_lds_dwordx4 v196, s[20:21]
	s_add_u32 m0, s27, 114688
	s_nop 0
	global_load_lds_dwordx4 v196, s[24:25]
	s_add_u32 m0, s27, 90112
	s_nop 0
	global_load_lds_dwordx4 v198, s[20:21]
	s_add_u32 m0, s27, 122880
	s_nop 0
	global_load_lds_dwordx4 v198, s[24:25]
	s_waitcnt vmcnt(0) lgkmcnt(0)
	s_barrier
	s_add_u32 s20, s16, 1792
	s_addc_u32 s21, s17, 0
	s_add_u32 s24, s18, 1792
	s_addc_u32 s25, s19, 0
	s_add_u32 m0, s27, 0
	s_nop 0
	global_load_lds_dwordx4 v192, s[20:21]
	s_add_u32 m0, s27, 32768
	s_nop 0
	global_load_lds_dwordx4 v192, s[24:25]
	s_add_u32 m0, s27, 8192
	s_nop 0
	global_load_lds_dwordx4 v194, s[20:21]
	s_add_u32 m0, s27, 40960
	s_nop 0
	global_load_lds_dwordx4 v194, s[24:25]
	s_add_u32 m0, s27, 16384
	s_nop 0
	global_load_lds_dwordx4 v196, s[20:21]
	s_add_u32 m0, s27, 49152
	s_nop 0
	global_load_lds_dwordx4 v196, s[24:25]
	s_add_u32 m0, s27, 24576
	s_nop 0
	global_load_lds_dwordx4 v198, s[20:21]
	s_add_u32 m0, s27, 57344
	s_nop 0
	global_load_lds_dwordx4 v198, s[24:25]
	s_waitcnt vmcnt(0) lgkmcnt(0)
	s_barrier
	s_add_u32 s20, s16, 1920
	s_addc_u32 s21, s17, 0
	s_add_u32 s24, s18, 1920
	s_addc_u32 s25, s19, 0
	s_add_u32 m0, s27, 65536
	s_nop 0
	global_load_lds_dwordx4 v192, s[20:21]
	s_add_u32 m0, s27, 98304
	s_nop 0
	global_load_lds_dwordx4 v192, s[24:25]
	s_add_u32 m0, s27, 73728
	s_nop 0
	global_load_lds_dwordx4 v194, s[20:21]
	s_add_u32 m0, s27, 106496
	s_nop 0
	global_load_lds_dwordx4 v194, s[24:25]
	s_add_u32 m0, s27, 81920
	s_nop 0
	global_load_lds_dwordx4 v196, s[20:21]
	s_add_u32 m0, s27, 114688
	s_nop 0
	global_load_lds_dwordx4 v196, s[24:25]
	s_add_u32 m0, s27, 90112
	s_nop 0
	global_load_lds_dwordx4 v198, s[20:21]
	s_add_u32 m0, s27, 122880
	s_nop 0
	global_load_lds_dwordx4 v198, s[24:25]
	s_waitcnt vmcnt(0) lgkmcnt(0)
	s_barrier
	s_add_u32 s37, s30, s42
	s_cmpk_ge_u32 s37, 0x780
	s_cbranch_scc1 .Lip11_ll_nonext
	s_mul_hi_u32 s38, s37, 0x92492493
	s_lshr_b32 s38, s38, 3
	s_mul_i32 s39, s38, 14
	s_sub_u32 s39, s37, s39
	s_sub_u32 s98, s37, 0x700
	s_cmpk_lt_u32 s37, 0x700
	s_cselect_b32 s39, s39, 14
	s_cselect_b32 s38, s38, s98
	s_lshl_b32 s98, s38, 19
	s_add_u32 s16, s4, s98
	s_addc_u32 s17, s5, 0
	s_lshl_b32 s98, s39, 19
	s_add_u32 s18, s6, s98
	s_addc_u32 s19, s7, 0
	s_add_u32 m0, s27, 0
	s_nop 0
	global_load_lds_dwordx4 v192, s[16:17]
	s_add_u32 m0, s27, 32768
	s_nop 0
	global_load_lds_dwordx4 v192, s[18:19]
	s_add_u32 m0, s27, 8192
	s_nop 0
	global_load_lds_dwordx4 v194, s[16:17]
	s_add_u32 m0, s27, 40960
	s_nop 0
	global_load_lds_dwordx4 v194, s[18:19]
	s_add_u32 m0, s27, 16384
	s_nop 0
	global_load_lds_dwordx4 v196, s[16:17]
	s_add_u32 m0, s27, 49152
	s_nop 0
	global_load_lds_dwordx4 v196, s[18:19]
	s_add_u32 m0, s27, 24576
	s_nop 0
	global_load_lds_dwordx4 v198, s[16:17]
	s_add_u32 m0, s27, 57344
	s_nop 0
	global_load_lds_dwordx4 v198, s[18:19]
	s_branch .Lip11_ll_join

.Lmq19_vb:
	v_mbcnt_hi_u32_b32 v206, -1, v210
	s_lshr_b32 s29, s70, 6
	s_lshl_b32 s88, s70, 4
	s_and_b32 s90, s70, 0x40
	v_and_b32_e32 v245, 48, v206
	v_or_b32_e32 v245, s90, v245
	v_and_b32_e32 v207, 31, v206
	v_lshrrev_b32_e32 v208, 5, v206
	v_bfe_u32 v209, v206, 1, 3
	v_lshlrev_b32_e32 v211, 7, v207
	s_lshr_b32 s91, s70, 7
	s_lshl_b32 s31, s91, 6
	s_lshl_b32 s91, s91, 13
	s_lshl_b32 s34, s90, 1
	s_lshl_b32 s90, s90, 8
	s_add_u32 s90, s90, 0x8000
	v_xor_b32_e32 v212, v208, v209
	v_lshl_add_u32 v212, v212, 4, v211
	v_add_u32_e32 v184, s91, v212
	v_add_u32_e32 v188, s90, v212
	v_or_b32_e32 v212, 2, v208
	v_xor_b32_e32 v212, v212, v209
	v_lshl_add_u32 v212, v212, 4, v211
	v_add_u32_e32 v185, s91, v212
	v_add_u32_e32 v189, s90, v212
	v_or_b32_e32 v212, 4, v208
	v_xor_b32_e32 v212, v212, v209
	v_lshl_add_u32 v212, v212, 4, v211
	v_add_u32_e32 v186, s91, v212
	v_add_u32_e32 v190, s90, v212
	v_or_b32_e32 v212, 6, v208
	v_xor_b32_e32 v212, v212, v209
	v_lshl_add_u32 v212, v212, 4, v211
	v_add_u32_e32 v187, s91, v212
	v_add_u32_e32 v191, s90, v212
	v_lshlrev_b32_e32 v200, 3, v207
	v_lshlrev_b32_e32 v203, 2, v208
	s_mul_i32 s91, s29, 0x1200
	s_add_u32 s91, s91, 0x12000
	v_mul_u32_u24_e32 v212, 0x240, v208
	v_lshl_add_u32 v212, v207, 1, v212
	v_add_u32_e32 v201, s91, v212
	v_lshrrev_b32_e32 v204, 3, v206
	v_and_b32_e32 v212, 7, v206
	v_lshlrev_b32_e32 v205, 4, v212
	v_mul_u32_u24_e32 v212, 0x90, v204
	v_add3_u32 v202, v212, v205, s91
	s_load_dwordx2 s[4:5], s[0:1], 0x168
	s_load_dwordx2 s[6:7], s[0:1], 0xd8
	s_load_dwordx2 s[8:9], s[0:1], 0x210
	s_load_dwordx2 s[10:11], s[0:1], 0x148
	s_load_dwordx2 s[12:13], s[0:1], 0x178
	s_lshl_b32 s96, s29, 3
	v_add_u32_e32 v206, s96, v204
	v_xor_b32_e32 v207, v245, v205
	v_lshl_add_u32 v192, v206, 9, v207
	v_mov_b32_e32 v193, 0
	v_add_u32_e32 v208, 64, v206
	v_lshl_add_u32 v194, v208, 9, v207
	v_mov_b32_e32 v195, 0
	v_add_u32_e32 v208, 128, v206
	v_lshl_add_u32 v196, v208, 9, v207
	v_mov_b32_e32 v197, 0
	v_add_u32_e32 v208, 192, v206
	v_lshl_add_u32 v198, v208, 9, v207
	v_mov_b32_e32 v199, 0
	s_mov_b32 s30, s28
	s_cmp_ge_u32 s30, 768
	s_cbranch_scc1 .Lmq19q_done
	s_waitcnt lgkmcnt(0)
	s_mul_hi_u32 s35, s30, 0xaaaaaaab
	s_lshr_b32 s35, s35, 2
	s_mul_i32 s36, s35, 6
	s_sub_u32 s36, s30, s36
	s_lshl_b32 s98, s35, 17
	s_add_u32 s16, s4, s98
	s_addc_u32 s17, s5, 0
	s_lshl_b32 s98, s36, 17
	s_add_u32 s18, s6, s98
	s_addc_u32 s19, s7, 0
	s_add_u32 m0, s88, 0
	s_nop 0
	global_load_lds_dwordx4 v192, s[16:17]
	s_add_u32 m0, s88, 32768
	s_nop 0
	global_load_lds_dwordx4 v192, s[18:19]
	s_add_u32 m0, s88, 8192
	s_nop 0
	global_load_lds_dwordx4 v194, s[16:17]
	s_add_u32 m0, s88, 40960
	s_nop 0
	global_load_lds_dwordx4 v194, s[18:19]
	s_add_u32 m0, s88, 16384
	s_nop 0
	global_load_lds_dwordx4 v196, s[16:17]
	s_add_u32 m0, s88, 49152
	s_nop 0
	global_load_lds_dwordx4 v196, s[18:19]
	s_add_u32 m0, s88, 24576
	s_nop 0
	global_load_lds_dwordx4 v198, s[16:17]
	s_add_u32 m0, s88, 57344
	s_nop 0
	global_load_lds_dwordx4 v198, s[18:19]

.Lmq19q_done:
	s_load_dwordx2 s[4:5], s[0:1], 0x170
	s_load_dwordx2 s[6:7], s[0:1], 0xe8
	s_load_dwordx2 s[8:9], s[0:1], 0x218
	s_load_dwordx2 s[10:11], s[0:1], 0x148
	s_load_dwordx2 s[12:13], s[0:1], 0x180
	s_load_dwordx2 s[14:15], s[0:1], 0x188
	s_lshl_b32 s96, s29, 3
	v_add_u32_e32 v206, s96, v204
	v_xor_b32_e32 v207, v245, v205
	v_lshl_add_u32 v192, v206, 8, v207
	v_mov_b32_e32 v193, 0
	v_add_u32_e32 v208, 64, v206
	v_lshl_add_u32 v194, v208, 8, v207
	v_mov_b32_e32 v195, 0
	v_add_u32_e32 v208, 128, v206
	v_lshl_add_u32 v196, v208, 8, v207
	v_mov_b32_e32 v197, 0
	v_add_u32_e32 v208, 192, v206
	v_lshl_add_u32 v198, v208, 8, v207
	v_mov_b32_e32 v199, 0
	s_mov_b32 s30, s28
	s_cmp_ge_u32 s30, 1024
	s_cbranch_scc1 .Lmq19k_done
	s_waitcnt lgkmcnt(0)
	s_lshr_b32 s35, s30, 3
	s_mul_i32 s36, s35, 8
	s_sub_u32 s36, s30, s36
	s_lshl_b32 s98, s35, 16
	s_add_u32 s16, s4, s98
	s_addc_u32 s17, s5, 0
	s_lshl_b32 s98, s36, 16
	s_add_u32 s18, s6, s98
	s_addc_u32 s19, s7, 0
	s_add_u32 m0, s88, 0
	s_nop 0
	global_load_lds_dwordx4 v192, s[16:17]
	s_add_u32 m0, s88, 32768
	s_nop 0
	global_load_lds_dwordx4 v192, s[18:19]
	s_add_u32 m0, s88, 8192
	s_nop 0
	global_load_lds_dwordx4 v194, s[16:17]
	s_add_u32 m0, s88, 40960
	s_nop 0
	global_load_lds_dwordx4 v194, s[18:19]
	s_add_u32 m0, s88, 16384
	s_nop 0
	global_load_lds_dwordx4 v196, s[16:17]
	s_add_u32 m0, s88, 49152
	s_nop 0
	global_load_lds_dwordx4 v196, s[18:19]
	s_add_u32 m0, s88, 24576
	s_nop 0
	global_load_lds_dwordx4 v198, s[16:17]
	s_add_u32 m0, s88, 57344
	s_nop 0
	global_load_lds_dwordx4 v198, s[18:19]
